# P7: expert-table fp8 conversion moved to tile top with one-tile-ahead register prefetch; attention main loops: LDS fragment reads software-pipelined under the MFMAs
# speedup vs baseline: 1.0236x; 1.0164x over previous
; #define LAS __attribute__((address_space(3)))
; __device__ __forceinline__ int crow(int r, int hi) { return (r & 3) + 8 * (r >> 2) + 4 * hi; }
; __device__ __forceinline__ void attn_unit(LAS unsigned char* lds, int b, int h, int qb, const bf16_t* Q, const bf16_t* KF, const bf16_t* VT,
;                                           const float* gout, bf16_t* MIXED, int wave, int lane) {
;     ...
;         if (key0 <= q0w + 31) {
;             const LAS unsigned char* kb_ = lds + (kt & 1) * ABUF;
;             const LAS unsigned char* vb_ = kb_ + KT_BYTES;
;             f32x16 sacc[2];
;             __builtin_amdgcn_s_setprio(1);
; #pragma unroll
;             for (int kb = 0; kb < 2; ++kb) {
; #pragma unroll
;                 for (int i = 0; i < 16; ++i) sacc[kb][i] = 0.f;
; #pragma unroll
;                 for (int ks = 0; ks < 12; ++ks) { const bf16x8 kf = *(const LAS bf16x8*)(kb_ + (kb * 32 + l31) * KT_STRIDE + ks * 32 + hi * 16);
;                     sacc[kb] = __builtin_amdgcn_mfma_f32_32x32x16_bf16(kf, qf[ks], sacc[kb], 0, 0, 0); }
;                 __builtin_amdgcn_sched_barrier(0);
;             }
;             __builtin_amdgcn_s_setprio(0);
;             if (key0 + 63 > q0w) {
; #pragma unroll
;                 for (int kb = 0; kb < 2; ++kb)
; #pragma unroll
;                     for (int i = 0; i < 16; ++i) { const int key = key0 + kb * 32 + crow(i, hi); if (key > qpos) sacc[kb][i] = -INFINITY; }
;             }
.LBB0_453:
	s_bitcmp1_b32 s85, 0
	s_cselect_b32 s56, 0xac00, 0
	s_setprio 1
	v_add_u32_e32 v107, s56, v106
	v_add_u32_e32 v114, v107, v113
	ds_read_b128 v[224:227], v114
	ds_read_b128 v[228:231], v114 offset:32
	ds_read_b128 v[80:83], v114 offset:64
	s_waitcnt lgkmcnt(2)
	v_mfma_f32_32x32x16_bf16 v[64:79], v[224:227], v[128:131], 0
	ds_read_b128 v[224:227], v114 offset:96
	s_waitcnt lgkmcnt(2)
	v_mfma_f32_32x32x16_bf16 v[64:79], v[228:231], v[200:203], v[64:79]
	ds_read_b128 v[228:231], v114 offset:128
	s_waitcnt lgkmcnt(2)
	v_mfma_f32_32x32x16_bf16 v[64:79], v[80:83], v[196:199], v[64:79]
	ds_read_b128 v[80:83], v114 offset:160
	s_waitcnt lgkmcnt(2)
	v_mfma_f32_32x32x16_bf16 v[64:79], v[224:227], v[192:195], v[64:79]
	ds_read_b128 v[224:227], v114 offset:192
	s_waitcnt lgkmcnt(2)
	v_mfma_f32_32x32x16_bf16 v[64:79], v[228:231], v[188:191], v[64:79]
	ds_read_b128 v[228:231], v114 offset:224
	s_waitcnt lgkmcnt(2)
	v_mfma_f32_32x32x16_bf16 v[64:79], v[80:83], v[184:187], v[64:79]
	ds_read_b128 v[80:83], v114 offset:256
	s_waitcnt lgkmcnt(2)
	v_mfma_f32_32x32x16_bf16 v[64:79], v[224:227], v[180:183], v[64:79]
	ds_read_b128 v[224:227], v114 offset:288
	s_waitcnt lgkmcnt(2)
	v_mfma_f32_32x32x16_bf16 v[64:79], v[228:231], v[176:179], v[64:79]
	ds_read_b128 v[228:231], v114 offset:320
	s_waitcnt lgkmcnt(2)
	v_mfma_f32_32x32x16_bf16 v[64:79], v[80:83], v[172:175], v[64:79]
	ds_read_b128 v[80:83], v114 offset:352
	s_waitcnt lgkmcnt(2)
	v_mfma_f32_32x32x16_bf16 v[64:79], v[224:227], v[168:171], v[64:79]
	ds_read_b128 v[224:227], v114 offset:12800
	s_waitcnt lgkmcnt(2)
	v_mfma_f32_32x32x16_bf16 v[64:79], v[228:231], v[164:167], v[64:79]
	ds_read_b128 v[228:231], v114 offset:12832
	s_waitcnt lgkmcnt(2)
	v_mfma_f32_32x32x16_bf16 v[64:79], v[80:83], v[160:163], v[64:79]
	ds_read_b128 v[108:111], v114 offset:12864
	s_waitcnt lgkmcnt(2)
	v_mfma_f32_32x32x16_bf16 v[80:95], v[224:227], v[128:131], 0
	ds_read_b128 v[224:227], v114 offset:12896
	s_waitcnt lgkmcnt(2)
	v_mfma_f32_32x32x16_bf16 v[80:95], v[228:231], v[200:203], v[80:95]
	ds_read_b128 v[228:231], v114 offset:12928
	s_waitcnt lgkmcnt(2)
	v_mfma_f32_32x32x16_bf16 v[80:95], v[108:111], v[196:199], v[80:95]
	ds_read_b128 v[108:111], v114 offset:12960
	s_waitcnt lgkmcnt(2)
	v_mfma_f32_32x32x16_bf16 v[80:95], v[224:227], v[192:195], v[80:95]
	ds_read_b128 v[224:227], v114 offset:12992
	s_waitcnt lgkmcnt(2)
	v_mfma_f32_32x32x16_bf16 v[80:95], v[228:231], v[188:191], v[80:95]
	ds_read_b128 v[228:231], v114 offset:13024
	s_waitcnt lgkmcnt(2)
	v_mfma_f32_32x32x16_bf16 v[80:95], v[108:111], v[184:187], v[80:95]
	ds_read_b128 v[108:111], v114 offset:13056
	s_waitcnt lgkmcnt(2)
	v_mfma_f32_32x32x16_bf16 v[80:95], v[224:227], v[180:183], v[80:95]
	ds_read_b128 v[224:227], v114 offset:13088
	s_waitcnt lgkmcnt(2)
	v_mfma_f32_32x32x16_bf16 v[80:95], v[228:231], v[176:179], v[80:95]
	ds_read_b128 v[228:231], v114 offset:13120
	s_waitcnt lgkmcnt(2)
	v_mfma_f32_32x32x16_bf16 v[80:95], v[108:111], v[172:175], v[80:95]
	ds_read_b128 v[108:111], v114 offset:13152
	s_waitcnt lgkmcnt(2)
	v_mfma_f32_32x32x16_bf16 v[80:95], v[224:227], v[168:171], v[80:95]
	s_waitcnt lgkmcnt(1)
	v_mfma_f32_32x32x16_bf16 v[80:95], v[228:231], v[164:167], v[80:95]
	s_waitcnt lgkmcnt(0)
	v_mfma_f32_32x32x16_bf16 v[80:95], v[108:111], v[160:163], v[80:95]
	s_setprio 0
	s_add_i32 s56, s80, 63
	s_cmp_le_i32 s56, s61
	s_cbranch_scc1 .LBB0_455
	v_add_u32_e32 v108, s80, v210
	v_cmp_gt_i32_e32 vcc, v108, v212
	s_nop 1
	v_cndmask_b32_e32 v109, v64, v218, vcc
	v_cmp_lt_i32_e32 vcc, v108, v212
	s_nop 1
	v_cndmask_b32_e32 v64, v109, v64, vcc
	v_add_u32_e32 v109, 2, v108
	v_cndmask_b32_e32 v65, v218, v65, vcc
	v_cmp_le_i32_e32 vcc, v109, v212
	v_add_u32_e32 v109, 3, v108
	s_nop 0
	v_cndmask_b32_e32 v66, v218, v66, vcc
	v_cmp_le_i32_e32 vcc, v109, v212
	v_add_u32_e32 v109, 8, v108
	s_nop 0
	v_cndmask_b32_e32 v67, v218, v67, vcc
	v_cmp_le_i32_e32 vcc, v109, v212
	v_add_u32_e32 v109, 9, v108
	s_nop 0
	v_cndmask_b32_e32 v68, v218, v68, vcc
	v_cmp_le_i32_e32 vcc, v109, v212
	v_add_u32_e32 v109, 10, v108
	s_nop 0
	v_cndmask_b32_e32 v69, v218, v69, vcc
	v_cmp_le_i32_e32 vcc, v109, v212
	v_add_u32_e32 v109, 11, v108
	s_nop 0
	v_cndmask_b32_e32 v70, v218, v70, vcc
	v_cmp_le_i32_e32 vcc, v109, v212
	v_add_u32_e32 v109, 16, v108
	s_nop 0
	v_cndmask_b32_e32 v71, v218, v71, vcc
	v_cmp_le_i32_e32 vcc, v109, v212
	v_add_u32_e32 v109, 17, v108
	s_nop 0
	v_cndmask_b32_e32 v72, v218, v72, vcc
	v_cmp_le_i32_e32 vcc, v109, v212
	v_add_u32_e32 v109, 18, v108
	s_nop 0
	v_cndmask_b32_e32 v73, v218, v73, vcc
	v_cmp_le_i32_e32 vcc, v109, v212
	v_add_u32_e32 v109, 19, v108
	s_nop 0
	v_cndmask_b32_e32 v74, v218, v74, vcc
	v_cmp_le_i32_e32 vcc, v109, v212
	v_add_u32_e32 v109, 24, v108
	s_nop 0
	v_cndmask_b32_e32 v75, v218, v75, vcc
	v_cmp_le_i32_e32 vcc, v109, v212
	v_add_u32_e32 v109, 25, v108
	s_nop 0
	v_cndmask_b32_e32 v76, v218, v76, vcc
	v_cmp_le_i32_e32 vcc, v109, v212
	v_add_u32_e32 v109, 26, v108
	s_nop 0
	v_cndmask_b32_e32 v77, v218, v77, vcc
	v_cmp_le_i32_e32 vcc, v109, v212
	v_add_u32_e32 v109, 27, v108
	s_nop 0
	v_cndmask_b32_e32 v78, v218, v78, vcc
	v_cmp_le_i32_e32 vcc, v109, v212
	v_add_u32_e32 v109, 32, v108
	s_nop 0
	v_cndmask_b32_e32 v79, v218, v79, vcc
	v_cmp_le_i32_e32 vcc, v109, v212
	s_nop 1
	v_cndmask_b32_e32 v80, v218, v80, vcc
	v_cmp_lt_i32_e32 vcc, v109, v212
	v_add_u32_e32 v109, 34, v108
	s_nop 0
	v_cndmask_b32_e32 v81, v218, v81, vcc
	v_cmp_le_i32_e32 vcc, v109, v212
	v_add_u32_e32 v109, 35, v108
	s_nop 0
	v_cndmask_b32_e32 v82, v218, v82, vcc
	v_cmp_le_i32_e32 vcc, v109, v212
	v_add_u32_e32 v109, 40, v108
	s_nop 0
	v_cndmask_b32_e32 v83, v218, v83, vcc
	v_cmp_le_i32_e32 vcc, v109, v212
	v_add_u32_e32 v109, 41, v108
	s_nop 0
	v_cndmask_b32_e32 v84, v218, v84, vcc
	v_cmp_le_i32_e32 vcc, v109, v212
	v_add_u32_e32 v109, 42, v108
	s_nop 0
	v_cndmask_b32_e32 v85, v218, v85, vcc
	v_cmp_le_i32_e32 vcc, v109, v212
	v_add_u32_e32 v109, 43, v108
	s_nop 0
	v_cndmask_b32_e32 v86, v218, v86, vcc
	v_cmp_le_i32_e32 vcc, v109, v212
	v_add_u32_e32 v109, 48, v108
	s_nop 0
	v_cndmask_b32_e32 v87, v218, v87, vcc
	v_cmp_le_i32_e32 vcc, v109, v212
	v_add_u32_e32 v109, 49, v108
	s_nop 0
	v_cndmask_b32_e32 v88, v218, v88, vcc
	v_cmp_le_i32_e32 vcc, v109, v212
	v_add_u32_e32 v109, 50, v108
	s_nop 0
	v_cndmask_b32_e32 v89, v218, v89, vcc
	v_cmp_le_i32_e32 vcc, v109, v212
	v_add_u32_e32 v109, 51, v108
	s_nop 0
	v_cndmask_b32_e32 v90, v218, v90, vcc
	v_cmp_le_i32_e32 vcc, v109, v212
	v_add_u32_e32 v109, 56, v108
	s_nop 0
	v_cndmask_b32_e32 v91, v218, v91, vcc
	v_cmp_le_i32_e32 vcc, v109, v212
	v_add_u32_e32 v109, 57, v108
	s_nop 0
	v_cndmask_b32_e32 v92, v218, v92, vcc
	v_cmp_le_i32_e32 vcc, v109, v212
	v_add_u32_e32 v109, 58, v108
	v_add_u32_e32 v108, 59, v108
	v_cndmask_b32_e32 v93, v218, v93, vcc
	v_cmp_le_i32_e32 vcc, v109, v212
	s_nop 1
	v_cndmask_b32_e32 v94, v218, v94, vcc
	v_cmp_le_i32_e32 vcc, v108, v212
	s_nop 1
	v_cndmask_b32_e32 v95, v218, v95, vcc

; #define LAS __attribute__((address_space(3)))
; __device__ __forceinline__ unsigned pk2(float lo, float hi) { f32x2 v = {lo, hi}; bf16x2_t b = __builtin_convertvector(v, bf16x2_t); return __builtin_bit_cast(unsigned, b); }
; __device__ __forceinline__ void attn_unit(LAS unsigned char* lds, int b, int h, int qb, const bf16_t* Q, const bf16_t* KF, const bf16_t* VT,
;                                           const float* gout, bf16_t* MIXED, int wave, int lane) {
;     ...
;             float rs = 0.f;
; #pragma unroll
;             for (int kb = 0; kb < 2; ++kb)
; #pragma unroll
;                 for (int i = 0; i < 16; ++i) { const float pv = __builtin_amdgcn_exp2f(sacc[kb][i] - m_run); sacc[kb][i] = pv; rs += pv; }
;             l_run += rs;
;             __builtin_amdgcn_s_setprio(1);
; #pragma unroll
;             for (int kb = 0; kb < 2; ++kb)
; #pragma unroll
;                 for (int s = 0; s < 2; ++s) {
;                     u32x4 pw; pw.x = pk2(sacc[kb][8 * s + 0], sacc[kb][8 * s + 1]); pw.y = pk2(sacc[kb][8 * s + 2], sacc[kb][8 * s + 3]);
;                     pw.z = pk2(sacc[kb][8 * s + 4], sacc[kb][8 * s + 5]); pw.w = pk2(sacc[kb][8 * s + 6], sacc[kb][8 * s + 7]);
;                     const bf16x8 pf = __builtin_bit_cast(bf16x8, pw);
; #pragma unroll
;                     for (int db = 0; db < 4; ++db) {
;                         const bf16x8 vf = *(const LAS bf16x8*)(vb_ + (db * 32 + l31) * VT_STRIDE + (2 * (kb * 2 + s) + hi) * 16);
;                         oacc[db] = __builtin_amdgcn_mfma_f32_32x32x16_bf16(vf, pf, oacc[db], 0, 0, 0);
;                     }
;                     __builtin_amdgcn_sched_barrier(0);
;                 }
;             __builtin_amdgcn_s_setprio(0);
.LBB0_457:
	v_sub_f32_e32 v64, v64, v220
	v_exp_f32_e32 v64, v64
	v_sub_f32_e32 v65, v65, v220
	v_sub_f32_e32 v66, v66, v220
	v_exp_f32_e32 v65, v65
	v_exp_f32_e32 v66, v66
	v_sub_f32_e32 v67, v67, v220
	v_exp_f32_e32 v67, v67
	v_sub_f32_e32 v68, v68, v220
	v_add_f32_e32 v108, 0, v64
	v_exp_f32_e32 v68, v68
	v_sub_f32_e32 v69, v69, v220
	v_add_f32_e32 v108, v65, v108
	v_exp_f32_e32 v69, v69
	v_sub_f32_e32 v70, v70, v220
	v_add_f32_e32 v108, v66, v108
	v_exp_f32_e32 v70, v70
	v_sub_f32_e32 v71, v71, v220
	v_add_f32_e32 v108, v67, v108
	v_exp_f32_e32 v71, v71
	v_sub_f32_e32 v72, v72, v220
	v_add_f32_e32 v108, v68, v108
	v_exp_f32_e32 v72, v72
	v_sub_f32_e32 v73, v73, v220
	v_add_f32_e32 v108, v69, v108
	v_exp_f32_e32 v73, v73
	v_sub_f32_e32 v74, v74, v220
	v_add_f32_e32 v108, v70, v108
	v_exp_f32_e32 v74, v74
	v_sub_f32_e32 v75, v75, v220
	v_add_f32_e32 v108, v71, v108
	v_exp_f32_e32 v75, v75
	v_sub_f32_e32 v76, v76, v220
	v_add_f32_e32 v108, v72, v108
	v_exp_f32_e32 v76, v76
	v_sub_f32_e32 v77, v77, v220
	v_add_f32_e32 v108, v73, v108
	v_exp_f32_e32 v77, v77
	v_sub_f32_e32 v78, v78, v220
	v_add_f32_e32 v108, v74, v108
	v_exp_f32_e32 v78, v78
	v_sub_f32_e32 v79, v79, v220
	v_add_f32_e32 v108, v75, v108
	v_exp_f32_e32 v79, v79
	v_add_f32_e32 v108, v76, v108
	v_add_f32_e32 v108, v77, v108
	v_sub_f32_e32 v80, v80, v220
	v_sub_f32_e32 v81, v81, v220
	v_sub_f32_e32 v82, v82, v220
	v_sub_f32_e32 v83, v83, v220
	v_sub_f32_e32 v84, v84, v220
	v_sub_f32_e32 v85, v85, v220
	v_sub_f32_e32 v86, v86, v220
	v_sub_f32_e32 v87, v87, v220
	v_sub_f32_e32 v88, v88, v220
	v_sub_f32_e32 v89, v89, v220
	v_sub_f32_e32 v90, v90, v220
	v_sub_f32_e32 v91, v91, v220
	v_sub_f32_e32 v92, v92, v220
	v_sub_f32_e32 v93, v93, v220
	v_sub_f32_e32 v94, v94, v220
	v_sub_f32_e32 v95, v95, v220
	v_add_f32_e32 v108, v78, v108
	v_exp_f32_e32 v80, v80
	v_exp_f32_e32 v81, v81
	v_exp_f32_e32 v82, v82
	v_exp_f32_e32 v83, v83
	v_exp_f32_e32 v84, v84
	v_exp_f32_e32 v85, v85
	v_exp_f32_e32 v86, v86
	v_exp_f32_e32 v87, v87
	v_exp_f32_e32 v88, v88
	v_exp_f32_e32 v89, v89
	v_exp_f32_e32 v90, v90
	v_exp_f32_e32 v91, v91
	v_exp_f32_e32 v92, v92
	v_exp_f32_e32 v93, v93
	v_exp_f32_e32 v94, v94
	v_exp_f32_e32 v95, v95
	v_add_f32_e32 v108, v79, v108
	s_setprio 1
	v_add_u32_e32 v107, v107, v213
	ds_read_b128 v[224:227], v107 offset:25600
	ds_read_b128 v[228:231], v107 offset:30208
	v_cvt_pk_bf16_f32 v64, v64, v65
	v_cvt_pk_bf16_f32 v65, v66, v67
	v_cvt_pk_bf16_f32 v66, v68, v69
	v_cvt_pk_bf16_f32 v67, v70, v71
	ds_read_b128 v[68:71], v107 offset:34816
	s_waitcnt lgkmcnt(2)
	v_mfma_f32_32x32x16_bf16 v[48:63], v[224:227], v[64:67], v[48:63]
	ds_read_b128 v[224:227], v107 offset:39424
	s_waitcnt lgkmcnt(2)
	v_mfma_f32_32x32x16_bf16 v[32:47], v[228:231], v[64:67], v[32:47]
	ds_read_b128 v[228:231], v107 offset:25632
	s_waitcnt lgkmcnt(2)
	v_mfma_f32_32x32x16_bf16 v[16:31], v[68:71], v[64:67], v[16:31]
	ds_read_b128 v[68:71], v107 offset:30240
	s_waitcnt lgkmcnt(2)
	v_mfma_f32_32x32x16_bf16 v[0:15], v[224:227], v[64:67], v[0:15]
	ds_read_b128 v[224:227], v107 offset:34848
	v_cvt_pk_bf16_f32 v64, v72, v73
	v_cvt_pk_bf16_f32 v65, v74, v75
	v_cvt_pk_bf16_f32 v66, v76, v77
	v_cvt_pk_bf16_f32 v67, v78, v79
	s_nop 0
	s_waitcnt lgkmcnt(2)
	v_mfma_f32_32x32x16_bf16 v[48:63], v[228:231], v[64:67], v[48:63]
	ds_read_b128 v[228:231], v107 offset:39456
	s_waitcnt lgkmcnt(2)
	v_mfma_f32_32x32x16_bf16 v[32:47], v[68:71], v[64:67], v[32:47]
	ds_read_b128 v[68:71], v107 offset:25664
	s_waitcnt lgkmcnt(2)
	v_mfma_f32_32x32x16_bf16 v[16:31], v[224:227], v[64:67], v[16:31]
	ds_read_b128 v[224:227], v107 offset:30272
	s_waitcnt lgkmcnt(2)
	v_mfma_f32_32x32x16_bf16 v[0:15], v[228:231], v[64:67], v[0:15]
	ds_read_b128 v[228:231], v107 offset:34880
	v_cvt_pk_bf16_f32 v64, v80, v81
	v_cvt_pk_bf16_f32 v65, v82, v83
	v_cvt_pk_bf16_f32 v66, v84, v85
	v_cvt_pk_bf16_f32 v67, v86, v87
	s_nop 0
	s_waitcnt lgkmcnt(2)
	v_mfma_f32_32x32x16_bf16 v[48:63], v[68:71], v[64:67], v[48:63]
	ds_read_b128 v[68:71], v107 offset:39488
	s_waitcnt lgkmcnt(2)
	v_mfma_f32_32x32x16_bf16 v[32:47], v[224:227], v[64:67], v[32:47]
	ds_read_b128 v[224:227], v107 offset:25696
	s_waitcnt lgkmcnt(2)
	v_mfma_f32_32x32x16_bf16 v[16:31], v[228:231], v[64:67], v[16:31]
	ds_read_b128 v[228:231], v107 offset:30304
	s_waitcnt lgkmcnt(2)
	v_mfma_f32_32x32x16_bf16 v[0:15], v[68:71], v[64:67], v[0:15]
	ds_read_b128 v[68:71], v107 offset:34912
	v_cvt_pk_bf16_f32 v64, v88, v89
	v_cvt_pk_bf16_f32 v65, v90, v91
	v_cvt_pk_bf16_f32 v66, v92, v93
	v_cvt_pk_bf16_f32 v67, v94, v95
	s_nop 0
	s_waitcnt lgkmcnt(2)
	v_mfma_f32_32x32x16_bf16 v[48:63], v[224:227], v[64:67], v[48:63]
	ds_read_b128 v[224:227], v107 offset:39520
	s_waitcnt lgkmcnt(2)
	v_mfma_f32_32x32x16_bf16 v[32:47], v[228:231], v[64:67], v[32:47]
	s_waitcnt lgkmcnt(1)
	v_mfma_f32_32x32x16_bf16 v[16:31], v[68:71], v[64:67], v[16:31]
	s_waitcnt lgkmcnt(0)
	v_mfma_f32_32x32x16_bf16 v[0:15], v[224:227], v[64:67], v[0:15]
	v_add_f32_e32 v64, v80, v108
	v_add_f32_e32 v64, v81, v64
	v_add_f32_e32 v64, v82, v64
	v_add_f32_e32 v64, v83, v64
	v_add_f32_e32 v64, v84, v64
	v_add_f32_e32 v64, v85, v64
	v_add_f32_e32 v64, v86, v64
	v_add_f32_e32 v64, v87, v64
	v_add_f32_e32 v64, v88, v64
	v_add_f32_e32 v64, v89, v64
	v_add_f32_e32 v64, v90, v64
	v_add_f32_e32 v64, v91, v64
	v_add_f32_e32 v64, v92, v64
	v_add_f32_e32 v64, v93, v64
	v_add_f32_e32 v64, v94, v64
	v_add_f32_e32 v64, v95, v64
	v_add_f32_e32 v211, v211, v64
	s_setprio 0

; #define LAS __attribute__((address_space(3)))
; __device__ __forceinline__ int crow(int r, int hi) { return (r & 3) + 8 * (r >> 2) + 4 * hi; }
; __device__ __forceinline__ void attn_unit(LAS unsigned char* lds, int b, int h, int qb, const bf16_t* Q, const bf16_t* KF, const bf16_t* VT,
;                                           const float* gout, bf16_t* MIXED, int wave, int lane) {
;     ...
;         if (key0 <= q0w + 31) {
;             const LAS unsigned char* kb_ = lds + (kt & 1) * ABUF;
;             const LAS unsigned char* vb_ = kb_ + KT_BYTES;
;             f32x16 sacc[2];
;             __builtin_amdgcn_s_setprio(1);
; #pragma unroll
;             for (int kb = 0; kb < 2; ++kb) {
; #pragma unroll
;                 for (int i = 0; i < 16; ++i) sacc[kb][i] = 0.f;
; #pragma unroll
;                 for (int ks = 0; ks < 12; ++ks) { const bf16x8 kf = *(const LAS bf16x8*)(kb_ + (kb * 32 + l31) * KT_STRIDE + ks * 32 + hi * 16);
;                     sacc[kb] = __builtin_amdgcn_mfma_f32_32x32x16_bf16(kf, qf[ks], sacc[kb], 0, 0, 0); }
;                 __builtin_amdgcn_sched_barrier(0);
;             }
;             __builtin_amdgcn_s_setprio(0);
;             if (key0 + 63 > q0w) {
; #pragma unroll
;                 for (int kb = 0; kb < 2; ++kb)
; #pragma unroll
;                     for (int i = 0; i < 16; ++i) { const int key = key0 + kb * 32 + crow(i, hi); if (key > qpos) sacc[kb][i] = -INFINITY; }
;             }
.LBB0_506:
	s_bitcmp1_b32 s25, 0
	s_cselect_b32 s25, 0xac00, 0
	s_setprio 1
	v_add_u32_e32 v109, s25, v108
	v_add_u32_e32 v114, v109, v107
	ds_read_b128 v[224:227], v114
	ds_read_b128 v[228:231], v114 offset:32
	ds_read_b128 v[80:83], v114 offset:64
	s_waitcnt lgkmcnt(2)
	v_mfma_f32_32x32x16_bf16 v[64:79], v[224:227], v[128:131], 0
	ds_read_b128 v[224:227], v114 offset:96
	s_waitcnt lgkmcnt(2)
	v_mfma_f32_32x32x16_bf16 v[64:79], v[228:231], v[200:203], v[64:79]
	ds_read_b128 v[228:231], v114 offset:128
	s_waitcnt lgkmcnt(2)
	v_mfma_f32_32x32x16_bf16 v[64:79], v[80:83], v[196:199], v[64:79]
	ds_read_b128 v[80:83], v114 offset:160
	s_waitcnt lgkmcnt(2)
	v_mfma_f32_32x32x16_bf16 v[64:79], v[224:227], v[192:195], v[64:79]
	ds_read_b128 v[224:227], v114 offset:192
	s_waitcnt lgkmcnt(2)
	v_mfma_f32_32x32x16_bf16 v[64:79], v[228:231], v[188:191], v[64:79]
	ds_read_b128 v[228:231], v114 offset:224
	s_waitcnt lgkmcnt(2)
	v_mfma_f32_32x32x16_bf16 v[64:79], v[80:83], v[184:187], v[64:79]
	ds_read_b128 v[80:83], v114 offset:256
	s_waitcnt lgkmcnt(2)
	v_mfma_f32_32x32x16_bf16 v[64:79], v[224:227], v[180:183], v[64:79]
	ds_read_b128 v[224:227], v114 offset:288
	s_waitcnt lgkmcnt(2)
	v_mfma_f32_32x32x16_bf16 v[64:79], v[228:231], v[176:179], v[64:79]
	ds_read_b128 v[228:231], v114 offset:320
	s_waitcnt lgkmcnt(2)
	v_mfma_f32_32x32x16_bf16 v[64:79], v[80:83], v[172:175], v[64:79]
	ds_read_b128 v[80:83], v114 offset:352
	s_waitcnt lgkmcnt(2)
	v_mfma_f32_32x32x16_bf16 v[64:79], v[224:227], v[168:171], v[64:79]
	ds_read_b128 v[224:227], v114 offset:12800
	s_waitcnt lgkmcnt(2)
	v_mfma_f32_32x32x16_bf16 v[64:79], v[228:231], v[164:167], v[64:79]
	ds_read_b128 v[228:231], v114 offset:12832
	s_waitcnt lgkmcnt(2)
	v_mfma_f32_32x32x16_bf16 v[64:79], v[80:83], v[160:163], v[64:79]
	ds_read_b128 v[110:113], v114 offset:12864
	s_waitcnt lgkmcnt(2)
	v_mfma_f32_32x32x16_bf16 v[80:95], v[224:227], v[128:131], 0
	ds_read_b128 v[224:227], v114 offset:12896
	s_waitcnt lgkmcnt(2)
	v_mfma_f32_32x32x16_bf16 v[80:95], v[228:231], v[200:203], v[80:95]
	ds_read_b128 v[228:231], v114 offset:12928
	s_waitcnt lgkmcnt(2)
	v_mfma_f32_32x32x16_bf16 v[80:95], v[110:113], v[196:199], v[80:95]
	ds_read_b128 v[110:113], v114 offset:12960
	s_waitcnt lgkmcnt(2)
	v_mfma_f32_32x32x16_bf16 v[80:95], v[224:227], v[192:195], v[80:95]
	ds_read_b128 v[224:227], v114 offset:12992
	s_waitcnt lgkmcnt(2)
	v_mfma_f32_32x32x16_bf16 v[80:95], v[228:231], v[188:191], v[80:95]
	ds_read_b128 v[228:231], v114 offset:13024
	s_waitcnt lgkmcnt(2)
	v_mfma_f32_32x32x16_bf16 v[80:95], v[110:113], v[184:187], v[80:95]
	ds_read_b128 v[110:113], v114 offset:13056
	s_waitcnt lgkmcnt(2)
	v_mfma_f32_32x32x16_bf16 v[80:95], v[224:227], v[180:183], v[80:95]
	ds_read_b128 v[224:227], v114 offset:13088
	s_waitcnt lgkmcnt(2)
	v_mfma_f32_32x32x16_bf16 v[80:95], v[228:231], v[176:179], v[80:95]
	ds_read_b128 v[228:231], v114 offset:13120
	s_waitcnt lgkmcnt(2)
	v_mfma_f32_32x32x16_bf16 v[80:95], v[110:113], v[172:175], v[80:95]
	ds_read_b128 v[110:113], v114 offset:13152
	s_waitcnt lgkmcnt(2)
	v_mfma_f32_32x32x16_bf16 v[80:95], v[224:227], v[168:171], v[80:95]
	s_waitcnt lgkmcnt(1)
	v_mfma_f32_32x32x16_bf16 v[80:95], v[228:231], v[164:167], v[80:95]
	s_waitcnt lgkmcnt(0)
	v_mfma_f32_32x32x16_bf16 v[80:95], v[110:113], v[160:163], v[80:95]
	s_setprio 0
	s_add_i32 s25, s22, 63
	s_cmp_le_i32 s25, s63
	s_cbranch_scc1 .LBB0_508
	v_add_u32_e32 v110, s22, v210
	v_cmp_gt_i32_e32 vcc, v110, v212
	s_nop 1
	v_cndmask_b32_e32 v111, v64, v218, vcc
	v_cmp_lt_i32_e32 vcc, v110, v212
	s_nop 1
	v_cndmask_b32_e32 v64, v111, v64, vcc
	v_add_u32_e32 v111, 2, v110
	v_cndmask_b32_e32 v65, v218, v65, vcc
	v_cmp_le_i32_e32 vcc, v111, v212
	v_add_u32_e32 v111, 3, v110
	s_nop 0
	v_cndmask_b32_e32 v66, v218, v66, vcc
	v_cmp_le_i32_e32 vcc, v111, v212
	v_add_u32_e32 v111, 8, v110
	s_nop 0
	v_cndmask_b32_e32 v67, v218, v67, vcc
	v_cmp_le_i32_e32 vcc, v111, v212
	v_add_u32_e32 v111, 9, v110
	s_nop 0
	v_cndmask_b32_e32 v68, v218, v68, vcc
	v_cmp_le_i32_e32 vcc, v111, v212
	v_add_u32_e32 v111, 10, v110
	s_nop 0
	v_cndmask_b32_e32 v69, v218, v69, vcc
	v_cmp_le_i32_e32 vcc, v111, v212
	v_add_u32_e32 v111, 11, v110
	s_nop 0
	v_cndmask_b32_e32 v70, v218, v70, vcc
	v_cmp_le_i32_e32 vcc, v111, v212
	v_add_u32_e32 v111, 16, v110
	s_nop 0
	v_cndmask_b32_e32 v71, v218, v71, vcc
	v_cmp_le_i32_e32 vcc, v111, v212
	v_add_u32_e32 v111, 17, v110
	s_nop 0
	v_cndmask_b32_e32 v72, v218, v72, vcc
	v_cmp_le_i32_e32 vcc, v111, v212
	v_add_u32_e32 v111, 18, v110
	s_nop 0
	v_cndmask_b32_e32 v73, v218, v73, vcc
	v_cmp_le_i32_e32 vcc, v111, v212
	v_add_u32_e32 v111, 19, v110
	s_nop 0
	v_cndmask_b32_e32 v74, v218, v74, vcc
	v_cmp_le_i32_e32 vcc, v111, v212
	v_add_u32_e32 v111, 24, v110
	s_nop 0
	v_cndmask_b32_e32 v75, v218, v75, vcc
	v_cmp_le_i32_e32 vcc, v111, v212
	v_add_u32_e32 v111, 25, v110
	s_nop 0
	v_cndmask_b32_e32 v76, v218, v76, vcc
	v_cmp_le_i32_e32 vcc, v111, v212
	v_add_u32_e32 v111, 26, v110
	s_nop 0
	v_cndmask_b32_e32 v77, v218, v77, vcc
	v_cmp_le_i32_e32 vcc, v111, v212
	v_add_u32_e32 v111, 27, v110
	s_nop 0
	v_cndmask_b32_e32 v78, v218, v78, vcc
	v_cmp_le_i32_e32 vcc, v111, v212
	v_add_u32_e32 v111, 32, v110
	s_nop 0
	v_cndmask_b32_e32 v79, v218, v79, vcc
	v_cmp_le_i32_e32 vcc, v111, v212
	s_nop 1
	v_cndmask_b32_e32 v80, v218, v80, vcc
	v_cmp_lt_i32_e32 vcc, v111, v212
	v_add_u32_e32 v111, 34, v110
	s_nop 0
	v_cndmask_b32_e32 v81, v218, v81, vcc
	v_cmp_le_i32_e32 vcc, v111, v212
	v_add_u32_e32 v111, 35, v110
	s_nop 0
	v_cndmask_b32_e32 v82, v218, v82, vcc
	v_cmp_le_i32_e32 vcc, v111, v212
	v_add_u32_e32 v111, 40, v110
	s_nop 0
	v_cndmask_b32_e32 v83, v218, v83, vcc
	v_cmp_le_i32_e32 vcc, v111, v212
	v_add_u32_e32 v111, 41, v110
	s_nop 0
	v_cndmask_b32_e32 v84, v218, v84, vcc
	v_cmp_le_i32_e32 vcc, v111, v212
	v_add_u32_e32 v111, 42, v110
	s_nop 0
	v_cndmask_b32_e32 v85, v218, v85, vcc
	v_cmp_le_i32_e32 vcc, v111, v212
	v_add_u32_e32 v111, 43, v110
	s_nop 0
	v_cndmask_b32_e32 v86, v218, v86, vcc
	v_cmp_le_i32_e32 vcc, v111, v212
	v_add_u32_e32 v111, 48, v110
	s_nop 0
	v_cndmask_b32_e32 v87, v218, v87, vcc
	v_cmp_le_i32_e32 vcc, v111, v212
	v_add_u32_e32 v111, 49, v110
	s_nop 0
	v_cndmask_b32_e32 v88, v218, v88, vcc
	v_cmp_le_i32_e32 vcc, v111, v212
	v_add_u32_e32 v111, 50, v110
	s_nop 0
	v_cndmask_b32_e32 v89, v218, v89, vcc
	v_cmp_le_i32_e32 vcc, v111, v212
	v_add_u32_e32 v111, 51, v110
	s_nop 0
	v_cndmask_b32_e32 v90, v218, v90, vcc
	v_cmp_le_i32_e32 vcc, v111, v212
	v_add_u32_e32 v111, 56, v110
	s_nop 0
	v_cndmask_b32_e32 v91, v218, v91, vcc
	v_cmp_le_i32_e32 vcc, v111, v212
	v_add_u32_e32 v111, 57, v110
	s_nop 0
	v_cndmask_b32_e32 v92, v218, v92, vcc
	v_cmp_le_i32_e32 vcc, v111, v212
	v_add_u32_e32 v111, 58, v110
	v_add_u32_e32 v110, 59, v110
	v_cndmask_b32_e32 v93, v218, v93, vcc
	v_cmp_le_i32_e32 vcc, v111, v212
	s_nop 1
	v_cndmask_b32_e32 v94, v218, v94, vcc
	v_cmp_le_i32_e32 vcc, v110, v212
	s_nop 1
	v_cndmask_b32_e32 v95, v218, v95, vcc

; #define LAS __attribute__((address_space(3)))
; __device__ __forceinline__ unsigned pk2(float lo, float hi) { f32x2 v = {lo, hi}; bf16x2_t b = __builtin_convertvector(v, bf16x2_t); return __builtin_bit_cast(unsigned, b); }
; __device__ __forceinline__ void attn_unit(LAS unsigned char* lds, int b, int h, int qb, const bf16_t* Q, const bf16_t* KF, const bf16_t* VT,
;                                           const float* gout, bf16_t* MIXED, int wave, int lane) {
;     ...
;             float rs = 0.f;
; #pragma unroll
;             for (int kb = 0; kb < 2; ++kb)
; #pragma unroll
;                 for (int i = 0; i < 16; ++i) { const float pv = __builtin_amdgcn_exp2f(sacc[kb][i] - m_run); sacc[kb][i] = pv; rs += pv; }
;             l_run += rs;
;             __builtin_amdgcn_s_setprio(1);
; #pragma unroll
;             for (int kb = 0; kb < 2; ++kb)
; #pragma unroll
;                 for (int s = 0; s < 2; ++s) {
;                     u32x4 pw; pw.x = pk2(sacc[kb][8 * s + 0], sacc[kb][8 * s + 1]); pw.y = pk2(sacc[kb][8 * s + 2], sacc[kb][8 * s + 3]);
;                     pw.z = pk2(sacc[kb][8 * s + 4], sacc[kb][8 * s + 5]); pw.w = pk2(sacc[kb][8 * s + 6], sacc[kb][8 * s + 7]);
;                     const bf16x8 pf = __builtin_bit_cast(bf16x8, pw);
; #pragma unroll
;                     for (int db = 0; db < 4; ++db) {
;                         const bf16x8 vf = *(const LAS bf16x8*)(vb_ + (db * 32 + l31) * VT_STRIDE + (2 * (kb * 2 + s) + hi) * 16);
;                         oacc[db] = __builtin_amdgcn_mfma_f32_32x32x16_bf16(vf, pf, oacc[db], 0, 0, 0);
;                     }
;                     __builtin_amdgcn_sched_barrier(0);
;                 }
;             __builtin_amdgcn_s_setprio(0);
.LBB0_510:
	v_sub_f32_e32 v64, v64, v220
	v_exp_f32_e32 v64, v64
	v_sub_f32_e32 v65, v65, v220
	v_sub_f32_e32 v66, v66, v220
	v_exp_f32_e32 v65, v65
	v_exp_f32_e32 v66, v66
	v_sub_f32_e32 v67, v67, v220
	v_exp_f32_e32 v67, v67
	v_sub_f32_e32 v68, v68, v220
	v_add_f32_e32 v110, 0, v64
	v_exp_f32_e32 v68, v68
	v_sub_f32_e32 v69, v69, v220
	v_add_f32_e32 v110, v65, v110
	v_exp_f32_e32 v69, v69
	v_sub_f32_e32 v70, v70, v220
	v_add_f32_e32 v110, v66, v110
	v_exp_f32_e32 v70, v70
	v_sub_f32_e32 v71, v71, v220
	v_add_f32_e32 v110, v67, v110
	v_exp_f32_e32 v71, v71
	v_sub_f32_e32 v72, v72, v220
	v_add_f32_e32 v110, v68, v110
	v_exp_f32_e32 v72, v72
	v_sub_f32_e32 v73, v73, v220
	v_add_f32_e32 v110, v69, v110
	v_exp_f32_e32 v73, v73
	v_sub_f32_e32 v74, v74, v220
	v_add_f32_e32 v110, v70, v110
	v_exp_f32_e32 v74, v74
	v_sub_f32_e32 v75, v75, v220
	v_add_f32_e32 v110, v71, v110
	v_exp_f32_e32 v75, v75
	v_sub_f32_e32 v76, v76, v220
	v_add_f32_e32 v110, v72, v110
	v_exp_f32_e32 v76, v76
	v_sub_f32_e32 v77, v77, v220
	v_add_f32_e32 v110, v73, v110
	v_exp_f32_e32 v77, v77
	v_sub_f32_e32 v78, v78, v220
	v_add_f32_e32 v110, v74, v110
	v_exp_f32_e32 v78, v78
	v_sub_f32_e32 v79, v79, v220
	v_add_f32_e32 v110, v75, v110
	v_exp_f32_e32 v79, v79
	v_add_f32_e32 v110, v76, v110
	v_add_f32_e32 v110, v77, v110
	v_sub_f32_e32 v80, v80, v220
	v_sub_f32_e32 v81, v81, v220
	v_sub_f32_e32 v82, v82, v220
	v_sub_f32_e32 v83, v83, v220
	v_sub_f32_e32 v84, v84, v220
	v_sub_f32_e32 v85, v85, v220
	v_sub_f32_e32 v86, v86, v220
	v_sub_f32_e32 v87, v87, v220
	v_sub_f32_e32 v88, v88, v220
	v_sub_f32_e32 v89, v89, v220
	v_sub_f32_e32 v90, v90, v220
	v_sub_f32_e32 v91, v91, v220
	v_sub_f32_e32 v92, v92, v220
	v_sub_f32_e32 v93, v93, v220
	v_sub_f32_e32 v94, v94, v220
	v_sub_f32_e32 v95, v95, v220
	v_add_f32_e32 v110, v78, v110
	v_exp_f32_e32 v80, v80
	v_exp_f32_e32 v81, v81
	v_exp_f32_e32 v82, v82
	v_exp_f32_e32 v83, v83
	v_exp_f32_e32 v84, v84
	v_exp_f32_e32 v85, v85
	v_exp_f32_e32 v86, v86
	v_exp_f32_e32 v87, v87
	v_exp_f32_e32 v88, v88
	v_exp_f32_e32 v89, v89
	v_exp_f32_e32 v90, v90
	v_exp_f32_e32 v91, v91
	v_exp_f32_e32 v92, v92
	v_exp_f32_e32 v93, v93
	v_exp_f32_e32 v94, v94
	v_exp_f32_e32 v95, v95
	v_add_f32_e32 v110, v79, v110
	s_setprio 1
	v_add_u32_e32 v109, v109, v213
	ds_read_b128 v[224:227], v109 offset:25600
	ds_read_b128 v[228:231], v109 offset:30208
	v_cvt_pk_bf16_f32 v64, v64, v65
	v_cvt_pk_bf16_f32 v65, v66, v67
	v_cvt_pk_bf16_f32 v66, v68, v69
	v_cvt_pk_bf16_f32 v67, v70, v71
	ds_read_b128 v[68:71], v109 offset:34816
	s_waitcnt lgkmcnt(2)
	v_mfma_f32_32x32x16_bf16 v[48:63], v[224:227], v[64:67], v[48:63]
	ds_read_b128 v[224:227], v109 offset:39424
	s_waitcnt lgkmcnt(2)
	v_mfma_f32_32x32x16_bf16 v[32:47], v[228:231], v[64:67], v[32:47]
	ds_read_b128 v[228:231], v109 offset:25632
	s_waitcnt lgkmcnt(2)
	v_mfma_f32_32x32x16_bf16 v[16:31], v[68:71], v[64:67], v[16:31]
	ds_read_b128 v[68:71], v109 offset:30240
	s_waitcnt lgkmcnt(2)
	v_mfma_f32_32x32x16_bf16 v[0:15], v[224:227], v[64:67], v[0:15]
	ds_read_b128 v[224:227], v109 offset:34848
	v_cvt_pk_bf16_f32 v64, v72, v73
	v_cvt_pk_bf16_f32 v65, v74, v75
	v_cvt_pk_bf16_f32 v66, v76, v77
	v_cvt_pk_bf16_f32 v67, v78, v79
	s_nop 0
	s_waitcnt lgkmcnt(2)
	v_mfma_f32_32x32x16_bf16 v[48:63], v[228:231], v[64:67], v[48:63]
	ds_read_b128 v[228:231], v109 offset:39456
	s_waitcnt lgkmcnt(2)
	v_mfma_f32_32x32x16_bf16 v[32:47], v[68:71], v[64:67], v[32:47]
	ds_read_b128 v[68:71], v109 offset:25664
	s_waitcnt lgkmcnt(2)
	v_mfma_f32_32x32x16_bf16 v[16:31], v[224:227], v[64:67], v[16:31]
	ds_read_b128 v[224:227], v109 offset:30272
	s_waitcnt lgkmcnt(2)
	v_mfma_f32_32x32x16_bf16 v[0:15], v[228:231], v[64:67], v[0:15]
	ds_read_b128 v[228:231], v109 offset:34880
	v_cvt_pk_bf16_f32 v64, v80, v81
	v_cvt_pk_bf16_f32 v65, v82, v83
	v_cvt_pk_bf16_f32 v66, v84, v85
	v_cvt_pk_bf16_f32 v67, v86, v87
	s_nop 0
	s_waitcnt lgkmcnt(2)
	v_mfma_f32_32x32x16_bf16 v[48:63], v[68:71], v[64:67], v[48:63]
	ds_read_b128 v[68:71], v109 offset:39488
	s_waitcnt lgkmcnt(2)
	v_mfma_f32_32x32x16_bf16 v[32:47], v[224:227], v[64:67], v[32:47]
	ds_read_b128 v[224:227], v109 offset:25696
	s_waitcnt lgkmcnt(2)
	v_mfma_f32_32x32x16_bf16 v[16:31], v[228:231], v[64:67], v[16:31]
	ds_read_b128 v[228:231], v109 offset:30304
	s_waitcnt lgkmcnt(2)
	v_mfma_f32_32x32x16_bf16 v[0:15], v[68:71], v[64:67], v[0:15]
	ds_read_b128 v[68:71], v109 offset:34912
	v_cvt_pk_bf16_f32 v64, v88, v89
	v_cvt_pk_bf16_f32 v65, v90, v91
	v_cvt_pk_bf16_f32 v66, v92, v93
	v_cvt_pk_bf16_f32 v67, v94, v95
	s_nop 0
	s_waitcnt lgkmcnt(2)
	v_mfma_f32_32x32x16_bf16 v[48:63], v[224:227], v[64:67], v[48:63]
	ds_read_b128 v[224:227], v109 offset:39520
	s_waitcnt lgkmcnt(2)
	v_mfma_f32_32x32x16_bf16 v[32:47], v[228:231], v[64:67], v[32:47]
	s_waitcnt lgkmcnt(1)
	v_mfma_f32_32x32x16_bf16 v[16:31], v[68:71], v[64:67], v[16:31]
	s_waitcnt lgkmcnt(0)
	v_mfma_f32_32x32x16_bf16 v[0:15], v[224:227], v[64:67], v[0:15]
	v_add_f32_e32 v64, v80, v110
	v_add_f32_e32 v64, v81, v64
	v_add_f32_e32 v64, v82, v64
	v_add_f32_e32 v64, v83, v64
	v_add_f32_e32 v64, v84, v64
	v_add_f32_e32 v64, v85, v64
	v_add_f32_e32 v64, v86, v64
	v_add_f32_e32 v64, v87, v64
	v_add_f32_e32 v64, v88, v64
	v_add_f32_e32 v64, v89, v64
	v_add_f32_e32 v64, v90, v64
	v_add_f32_e32 v64, v91, v64
	v_add_f32_e32 v64, v92, v64
	v_add_f32_e32 v64, v93, v64
	v_add_f32_e32 v64, v94, v64
	v_add_f32_e32 v64, v95, v64
	v_add_f32_e32 v211, v211, v64
	s_setprio 0

; #define LAS __attribute__((address_space(3)))
; __device__ __forceinline__ void row_to_fp8(const float* src, unsigned char* tab, int e, float* sc, int lane) {
;     f32x4 v[2][4]; float mx = 0.f;
; #pragma unroll
;     for (int c = 0; c < 2; ++c)
; #pragma unroll
;         for (int k = 0; k < 4; ++k) { v[c][k] = __builtin_nontemporal_load((const f32x4*)(src + c * 1024 + lane * 16 + k * 4));
; __global__ void __launch_bounds__(NTHR, 2) fwd_megakernel(Args a) {
;     ...
;         LAS float* SC = (LAS float*)lds;
;         LAS unsigned char* TOPI = lds + 256 * 129 * 4;
;         LAS unsigned* KX = (LAS unsigned*)(lds + 256 * 129 * 4 + 4096);
;         const int l31 = lane & 31, hi = lane >> 5;
;         const bf16_t* QP = R3;
;         for (int tile = bx; tile < (T / 128) * 8; tile += G) {
;             const int h = tile & 7, t0 = (tile >> 3) * 128;
;             {
;                 const int p = wave >> 2, r0 = (wave & 3) * 32;
;                 f32x16 acc[4];
; #pragma unroll
;                 for (int nb = 0; nb < 4; ++nb)
; #pragma unroll
;                     for (int i = 0; i < 16; ++i) acc[nb][i] = 0.f;
;                 const bf16_t* qa = QP + (size_t)(t0 + r0 + l31) * 2048 + h * 256 + p * 128 + hi * 8;
;                 const bf16_t* kb = KEYS + (size_t)((h * 2 + p) * 128 + l31) * 128 + hi * 8;
.LBB0_792:
	s_or_b64 exec, exec, s[0:1]
	s_add_u32 s26, s50, 0x4000000
	s_addc_u32 s27, s51, 0
	s_add_u32 s28, s50, 0x6000000
	s_addc_u32 s29, s51, 0
	s_add_u32 s30, s50, 0x3a000000
	s_addc_u32 s31, s51, 0
	s_add_u32 s4, s50, 0x3b000000
	s_addc_u32 s5, s51, 0
	v_readlane_b32 s0, v235, 47
	s_add_u32 s52, s50, 0x8400000
	v_mov_b32_e32 v76, v214
	v_readlane_b32 s1, v235, 48
	s_addc_u32 s53, s51, 0
	s_waitcnt lgkmcnt(0)
	s_barrier
	s_andn2_b64 vcc, exec, s[0:1]
	v_readfirstlane_b32 s0, v76
	s_cbranch_vccnz .LBB0_824
	v_bfe_u32 v4, v76, 5, 1
	s_ashr_i32 s14, s0, 6
	s_lshl_b32 s1, s14, 5
	s_ashr_i32 s0, s0, 1
	v_mov_b32_e32 v65, 0
	v_lshlrev_b32_e32 v64, 4, v4
	s_and_b32 s6, s1, 0x60
	s_and_b32 s34, s0, 0xffffff80
	v_lshl_add_u64 v[2:3], s[50:51], 0, v[64:65]
	s_mov_b64 s[0:1], 0x2d00000
	v_lshl_add_u64 v[66:67], v[2:3], 0, s[0:1]
	v_lshl_or_b32 v2, v4, 2, s6
	v_and_b32_e32 v5, 31, v76
	v_or_b32_e32 v8, s34, v2
	v_ashrrev_i32_e32 v2, 8, v76
	s_movk_i32 s1, 0x204
	v_or_b32_e32 v77, s6, v5
	v_lshlrev_b32_e32 v0, 3, v4
	v_mul_u32_u24_sdwa v3, v76, s1 dst_sel:DWORD dst_unused:UNUSED_PAD src0_sel:BYTE_0 src1_sel:DWORD
	v_lshlrev_b32_e32 v10, 6, v2
	v_and_b32_e32 v4, 0xffffff00, v76
	v_cmp_eq_u32_e64 s[6:7], 1, v2
	v_mov_b32_e32 v2, 6
	v_lshlrev_b32_e32 v12, 4, v76
	v_or_b32_e32 v78, s34, v5
	v_lshlrev_b32_e32 v9, 2, v5
	s_movk_i32 s0, 0xff
	v_add3_u32 v79, 0, v3, v4
	v_lshlrev_b32_sdwa v11, v2, v76 dst_sel:DWORD dst_unused:UNUSED_PAD src0_sel:DWORD src1_sel:BYTE_0
	v_lshlrev_b32_e32 v2, 18, v76
	v_and_b32_e32 v4, 0x70, v12
	v_mov_b32_e32 v5, v65
	v_and_b32_e32 v1, 63, v76
	v_cmp_lt_u32_e64 s[8:9], s0, v76
	v_and_b32_e32 v2, 0xe00000, v2
	v_lshl_add_u64 v[6:7], s[28:29], 0, v[4:5]
	v_mov_b32_e32 v3, v65
	v_lshl_add_u64 v[4:5], s[26:27], 0, v[4:5]
	s_add_i32 s0, 0, 0x20400
	s_ashr_i32 s35, s34, 31
	s_add_i32 s59, s14, -4
	v_lshlrev_b32_e32 v64, 6, v1
	v_lshl_add_u64 v[70:71], v[6:7], 0, v[2:3]
	v_lshl_add_u64 v[74:75], v[4:5], 0, v[2:3]
	v_add_u32_e32 v80, s0, v12
	s_movk_i32 s0, 0x7f
	v_mul_lo_u32 v2, v76, s1
	v_readlane_b32 s16, v235, 41
	v_lshl_add_u64 v[68:69], s[38:39], 0, v[64:65]
	v_cmp_eq_u32_e64 s[10:11], 0, v1
	v_lshl_add_u64 v[72:73], s[36:37], 0, v[64:65]
	v_lshlrev_b32_e32 v1, 6, v76
	v_cmp_lt_i32_e64 s[12:13], s0, v76
	s_cmp_gt_i32 s14, 1
	v_add_u32_e32 v82, 0, v2
	v_mul_lo_u32 v2, v8, s1
	s_mul_i32 s0, s16, 10
	v_lshlrev_b32_e32 v64, 1, v0
	v_add_u32_e32 v0, 0, v11
	s_cselect_b64 s[36:37], -1, 0
	s_add_i32 s60, s14, 2
	v_add3_u32 v84, 0, v9, v2
	s_add_i32 s0, s14, s0
	v_readlane_b32 s14, v235, 1
	v_add_u32_e32 v86, 0x21400, v0
	v_add_u32_e32 v0, 0, v1
	s_movk_i32 s33, 0xff80
	s_mov_b32 s45, 0
	s_movk_i32 s58, 0xff00
	v_add_u32_e32 v81, 0x800, v80
	v_add_u32_e32 v83, 0x10200, v82
	v_sub_u32_e32 v85, 0, v10
	s_add_i32 s61, s0, 0xffffaffc
	s_mul_i32 s64, s14, 10
	s_add_i32 s65, s0, 0xffffb002
	s_movk_i32 s66, 0x2000
	s_movk_i32 s67, 0x4000
	s_movk_i32 s68, 0x6000
	s_mov_b64 s[38:39], 0x1000
	s_movk_i32 s69, 0x1000
	s_mov_b32 s70, 0x43600000
	v_add_u32_e32 v87, 0x21400, v0
	s_mov_b32 s71, 0x7f7f7f7f
	v_mov_b32_e32 v88, 0x358637bd
	s_mov_b32 s72, 0x800000
	v_add_u32_e32 v89, 0x400, v84
	v_add_u32_e32 v90, 0x1000, v84
	v_add_u32_e32 v91, 0x1400, v84
	v_add_u32_e32 v92, 0x2000, v84
	v_add_u32_e32 v93, 0x2400, v84
	v_add_u32_e32 v94, 0x3000, v84
	v_add_u32_e32 v95, 0x3400, v84
	v_mbcnt_hi_u32_b32 v96, -1, v215
	s_mov_b32 s73, s16
	v_readlane_b32 s17, v235, 42
	v_readlane_b32 s15, v235, 2
	s_mov_b32 s98, s73
	s_cmpk_gt_i32 s98, 0x7ff
	s_cbranch_scc1 .Lcv_nopf_a
	s_lshl_b32 s98, s98, 4
	s_add_i32 s99, s59, 4
	s_lshl_b32 s99, s99, 1
	s_add_i32 s98, s98, s99
	s_and_b32 s99, s98, 0x3fff
	s_lshl_b32 s100, s99, 13
	s_mov_b32 s101, 0
	s_cmpk_gt_i32 s98, 0x3fff
	s_cbranch_scc1 .Lcv_pfv_a
	v_lshl_add_u64 v[140:141], v[72:73], 0, s[100:101]
	s_branch .Lcv_pfj_a
.Lcv_pfv_a:
	v_lshl_add_u64 v[140:141], v[68:69], 0, s[100:101]
.Lcv_pfj_a:
	s_movk_i32 s100, 0x1000
	v_lshl_add_u64 v[142:143], v[140:141], 0, s[100:101]
	s_movk_i32 s100, 0x2000
	v_lshl_add_u64 v[144:145], v[140:141], 0, s[100:101]
	s_movk_i32 s100, 0x3000
	v_lshl_add_u64 v[146:147], v[140:141], 0, s[100:101]
	global_load_dwordx4 v[150:153], v[140:141], off nt
	global_load_dwordx4 v[154:157], v[140:141], off offset:16 nt
	global_load_dwordx4 v[158:161], v[140:141], off offset:32 nt
	global_load_dwordx4 v[162:165], v[140:141], off offset:48 nt
	global_load_dwordx4 v[166:169], v[142:143], off nt
	global_load_dwordx4 v[170:173], v[142:143], off offset:16 nt
	global_load_dwordx4 v[174:177], v[142:143], off offset:32 nt
	global_load_dwordx4 v[178:181], v[142:143], off offset:48 nt
	global_load_dwordx4 v[182:185], v[144:145], off nt
	global_load_dwordx4 v[186:189], v[144:145], off offset:16 nt
	global_load_dwordx4 v[190:193], v[144:145], off offset:32 nt
	global_load_dwordx4 v[194:197], v[144:145], off offset:48 nt
	global_load_dwordx4 v[198:201], v[146:147], off nt
	global_load_dwordx4 v[202:205], v[146:147], off offset:16 nt
	global_load_dwordx4 v[206:209], v[146:147], off offset:32 nt
	global_load_dwordx4 v[210:213], v[146:147], off offset:48 nt
.Lcv_nopf_a:
	s_branch .LBB0_796

; __device__ __forceinline__ void row_to_fp8(const float* src, unsigned char* tab, int e, float* sc, int lane) {
;     f32x4 v[2][4]; float mx = 0.f;
; #pragma unroll
;     for (int c = 0; c < 2; ++c)
; #pragma unroll
;         for (int k = 0; k < 4; ++k) { v[c][k] = __builtin_nontemporal_load((const f32x4*)(src + c * 1024 + lane * 16 + k * 4));
;             mx = fmaxf(mx, fmaxf(fmaxf(fabsf(v[c][k].x), fabsf(v[c][k].y)), fmaxf(fabsf(v[c][k].z), fabsf(v[c][k].w)))); }
; #pragma unroll
;     for (int o = 1; o < 64; o <<= 1) mx = fmaxf(mx, __shfl_xor(mx, o));
;     const float scale = mx > 0.f ? 224.f / mx : 1.f;
; #pragma unroll
;     for (int c = 0; c < 2; ++c) { u32x4 w;
; #pragma unroll
;         for (int k = 0; k < 4; ++k) { const f32x4 x = v[c][k] * scale; int pk = 0; pk = __builtin_amdgcn_cvt_pk_fp8_f32(x.x, x.y, pk, false); pk = __builtin_amdgcn_cvt_pk_fp8_f32(x.z, x.w, pk, true); w[k] = (unsigned)pk; }
;         *(u32x4*)(tab + (size_t)(c * 8 + (lane >> 3)) * (16384 * 128) + (size_t)e * 128 + (lane & 7) * 16) = w; }
;     if (lane == 0) *sc = mx > 0.f ? mx * (1.f / 224.f) : 1.f;
.LBB0_796:
	s_waitcnt vmcnt(0)
	s_mov_b32 s98, s73
	s_lshl_b32 s98, s98, 4
	s_add_i32 s99, s59, 4
	s_lshl_b32 s99, s99, 1
	s_add_i32 s98, s98, s99
	s_and_b32 s99, s98, 0x3fff
	s_lshl_b32 s100, s99, 7
	s_mov_b32 s101, 0
	v_mov_b32_e32 v148, s99
	s_cmpk_gt_i32 s98, 0x3fff
	s_cbranch_scc1 .Lcv_tv
	v_lshl_add_u64 v[140:141], v[74:75], 0, s[100:101]
	s_add_u32 s100, s50, 0x8000000
	s_addc_u32 s101, s51, 0
	s_branch .Lcv_tj
.Lcv_tv:
	v_lshl_add_u64 v[140:141], v[70:71], 0, s[100:101]
	s_add_u32 s100, s50, 0x8100000
	s_addc_u32 s101, s51, 0
.Lcv_tj:
	v_lshlrev_b32_e32 v148, 2, v148
	v_add_co_u32_e32 v142, vcc, 0x1000000, v140
	s_nop 1
	v_addc_co_u32_e32 v143, vcc, 0, v141, vcc
	v_max3_f32 v144, |v150|, |v151|, |v152|
	v_max3_f32 v145, |v153|, |v154|, |v155|
	v_max3_f32 v146, |v156|, |v157|, |v158|
	v_max3_f32 v147, |v159|, |v160|, |v161|
	v_max3_f32 v144, |v162|, |v163|, v144
	v_max3_f32 v145, |v164|, |v165|, v145
	v_max3_f32 v146, |v166|, |v167|, v146
	v_max3_f32 v147, |v168|, |v169|, v147
	v_max3_f32 v144, |v170|, |v171|, v144
	v_max3_f32 v145, |v172|, |v173|, v145
	v_max3_f32 v146, |v174|, |v175|, v146
	v_max3_f32 v147, |v176|, |v177|, v147
	v_max3_f32 v144, |v178|, |v179|, v144
	v_max3_f32 v145, |v180|, |v181|, v145
	v_max3_f32 v144, v144, v145, v146
	s_nop 0
	v_max_f32_e32 v144, v144, v147
	s_nop 1
	v_max_f32_dpp v144, v144, v144 quad_perm:[1,0,3,2] row_mask:0xf bank_mask:0xf bound_ctrl:1
	s_nop 1
	v_max_f32_dpp v144, v144, v144 quad_perm:[2,3,0,1] row_mask:0xf bank_mask:0xf bound_ctrl:1
	s_nop 1
	v_max_f32_dpp v144, v144, v144 row_half_mirror row_mask:0xf bank_mask:0xf bound_ctrl:1
	s_nop 1
	v_max_f32_dpp v144, v144, v144 row_mirror row_mask:0xf bank_mask:0xf bound_ctrl:1
	s_nop 1
	v_readlane_b32 s98, v144, 0
	v_readlane_b32 s99, v144, 16
	v_readlane_b32 vcc_lo, v144, 32
	v_readlane_b32 vcc_hi, v144, 48
	s_max_u32 s98, s98, s99
	s_max_u32 vcc_lo, vcc_lo, vcc_hi
	s_max_u32 s98, s98, vcc_lo
	v_mov_b32_e32 v149, s98
	v_div_scale_f32 v224, vcc, v149, v149, s70
	v_rcp_f32_e32 v225, v224
	v_div_scale_f32 v226, vcc, s70, v149, s70
	v_cmp_lt_f32_e64 s[98:99], 0, v149
	v_fma_f32 v227, -v224, v225, 1.0
	v_fmac_f32_e32 v225, v227, v225
	v_mul_f32_e32 v227, v226, v225
	v_fma_f32 v228, -v224, v227, v226
	v_fmac_f32_e32 v227, v228, v225
	v_fma_f32 v224, -v224, v227, v226
	v_div_fmas_f32 v224, v224, v225, v227
	v_div_fixup_f32 v224, v224, v149, s70
	v_mul_f32_e32 v229, 0x3b924925, v149
	v_cndmask_b32_e64 v230, 1.0, v224, s[98:99]
	v_cndmask_b32_e64 v229, 1.0, v229, s[98:99]
	v_pk_mul_f32 v[150:151], v[150:151], v[230:231] op_sel_hi:[1,0]
	v_pk_mul_f32 v[152:153], v[152:153], v[230:231] op_sel_hi:[1,0]
	v_pk_mul_f32 v[154:155], v[154:155], v[230:231] op_sel_hi:[1,0]
	v_pk_mul_f32 v[156:157], v[156:157], v[230:231] op_sel_hi:[1,0]
	v_pk_mul_f32 v[158:159], v[158:159], v[230:231] op_sel_hi:[1,0]
	v_pk_mul_f32 v[160:161], v[160:161], v[230:231] op_sel_hi:[1,0]
	v_pk_mul_f32 v[162:163], v[162:163], v[230:231] op_sel_hi:[1,0]
	v_pk_mul_f32 v[164:165], v[164:165], v[230:231] op_sel_hi:[1,0]
	v_pk_mul_f32 v[166:167], v[166:167], v[230:231] op_sel_hi:[1,0]
	v_pk_mul_f32 v[168:169], v[168:169], v[230:231] op_sel_hi:[1,0]
	v_pk_mul_f32 v[170:171], v[170:171], v[230:231] op_sel_hi:[1,0]
	v_pk_mul_f32 v[172:173], v[172:173], v[230:231] op_sel_hi:[1,0]
	v_pk_mul_f32 v[174:175], v[174:175], v[230:231] op_sel_hi:[1,0]
	v_pk_mul_f32 v[176:177], v[176:177], v[230:231] op_sel_hi:[1,0]
	v_pk_mul_f32 v[178:179], v[178:179], v[230:231] op_sel_hi:[1,0]
	v_pk_mul_f32 v[180:181], v[180:181], v[230:231] op_sel_hi:[1,0]
	v_cvt_pk_fp8_f32 v216, v150, v151
	v_cvt_pk_fp8_f32 v217, v154, v155
	v_cvt_pk_fp8_f32 v218, v158, v159
	v_cvt_pk_fp8_f32 v219, v162, v163
	v_cvt_pk_fp8_f32 v220, v166, v167
	v_cvt_pk_fp8_f32 v221, v170, v171
	v_cvt_pk_fp8_f32 v222, v174, v175
	v_cvt_pk_fp8_f32 v223, v178, v179
	v_cvt_pk_fp8_f32 v216, v152, v153 op_sel:[0,0,1]
	v_cvt_pk_fp8_f32 v217, v156, v157 op_sel:[0,0,1]
	v_cvt_pk_fp8_f32 v218, v160, v161 op_sel:[0,0,1]
	v_cvt_pk_fp8_f32 v219, v164, v165 op_sel:[0,0,1]
	v_cvt_pk_fp8_f32 v220, v168, v169 op_sel:[0,0,1]
	v_cvt_pk_fp8_f32 v221, v172, v173 op_sel:[0,0,1]
	v_cvt_pk_fp8_f32 v222, v176, v177 op_sel:[0,0,1]
	v_cvt_pk_fp8_f32 v223, v180, v181 op_sel:[0,0,1]
	s_nop 0
	global_store_dwordx4 v[140:141], v[216:219], off
	global_store_dwordx4 v[142:143], v[220:223], off
	global_store_dword v148, v229, s[100:101]
	v_max3_f32 v144, |v182|, |v183|, |v184|
	v_max3_f32 v145, |v185|, |v186|, |v187|
	v_max3_f32 v146, |v188|, |v189|, |v190|
	v_max3_f32 v147, |v191|, |v192|, |v193|
	v_max3_f32 v144, |v194|, |v195|, v144
	v_max3_f32 v145, |v196|, |v197|, v145
	v_max3_f32 v146, |v198|, |v199|, v146
	v_max3_f32 v147, |v200|, |v201|, v147
	v_max3_f32 v144, |v202|, |v203|, v144
	v_max3_f32 v145, |v204|, |v205|, v145
	v_max3_f32 v146, |v206|, |v207|, v146
	v_max3_f32 v147, |v208|, |v209|, v147
	v_max3_f32 v144, |v210|, |v211|, v144
	v_max3_f32 v145, |v212|, |v213|, v145
	v_max3_f32 v144, v144, v145, v146
	s_nop 0
	v_max_f32_e32 v144, v144, v147
	s_nop 1
	v_max_f32_dpp v144, v144, v144 quad_perm:[1,0,3,2] row_mask:0xf bank_mask:0xf bound_ctrl:1
	s_nop 1
	v_max_f32_dpp v144, v144, v144 quad_perm:[2,3,0,1] row_mask:0xf bank_mask:0xf bound_ctrl:1
	s_nop 1
	v_max_f32_dpp v144, v144, v144 row_half_mirror row_mask:0xf bank_mask:0xf bound_ctrl:1
	s_nop 1
	v_max_f32_dpp v144, v144, v144 row_mirror row_mask:0xf bank_mask:0xf bound_ctrl:1
	s_nop 1
	v_readlane_b32 s98, v144, 0
	v_readlane_b32 s99, v144, 16
	v_readlane_b32 vcc_lo, v144, 32
	v_readlane_b32 vcc_hi, v144, 48
	s_max_u32 s98, s98, s99
	s_max_u32 vcc_lo, vcc_lo, vcc_hi
	s_max_u32 s98, s98, vcc_lo
	v_mov_b32_e32 v149, s98
; __device__ __forceinline__ void row_to_fp8(const float* src, unsigned char* tab, int e, float* sc, int lane) {
;     f32x4 v[2][4]; float mx = 0.f;
; #pragma unroll
;     for (int c = 0; c < 2; ++c)
; #pragma unroll
;         for (int k = 0; k < 4; ++k) { v[c][k] = __builtin_nontemporal_load((const f32x4*)(src + c * 1024 + lane * 16 + k * 4));
;             mx = fmaxf(mx, fmaxf(fmaxf(fabsf(v[c][k].x), fabsf(v[c][k].y)), fmaxf(fabsf(v[c][k].z), fabsf(v[c][k].w)))); }
; #pragma unroll
;     for (int o = 1; o < 64; o <<= 1) mx = fmaxf(mx, __shfl_xor(mx, o));
;     const float scale = mx > 0.f ? 224.f / mx : 1.f;
; #pragma unroll
;     for (int c = 0; c < 2; ++c) { u32x4 w;
; #pragma unroll
;         for (int k = 0; k < 4; ++k) { const f32x4 x = v[c][k] * scale; int pk = 0; pk = __builtin_amdgcn_cvt_pk_fp8_f32(x.x, x.y, pk, false); pk = __builtin_amdgcn_cvt_pk_fp8_f32(x.z, x.w, pk, true); w[k] = (unsigned)pk; }
;         *(u32x4*)(tab + (size_t)(c * 8 + (lane >> 3)) * (16384 * 128) + (size_t)e * 128 + (lane & 7) * 16) = w; }
;     if (lane == 0) *sc = mx > 0.f ? mx * (1.f / 224.f) : 1.f;
; __global__ void __launch_bounds__(NTHR, 2) fwd_megakernel(Args a) {
;     ...
;                 const bf16_t* qa = QP + (size_t)(t0 + r0 + l31) * 2048 + h * 256 + p * 128 + hi * 8;
;                 const bf16_t* kb = KEYS + (size_t)((h * 2 + p) * 128 + l31) * 128 + hi * 8;
; #pragma unroll
;                 for (int ks = 0; ks < 8; ++ks) {
;                     const bf16x8 af = *(const bf16x8*)(qa + ks * 16);
; #pragma unroll
;                     for (int nb = 0; nb < 4; ++nb) { const bf16x8 bf = *(const bf16x8*)(kb + nb * 32 * 128 + ks * 16); acc[nb] = __builtin_amdgcn_mfma_f32_32x32x16_bf16(af, bf, acc[nb], 0, 0, 0); }
;                 }
	v_div_scale_f32 v224, vcc, v149, v149, s70
	v_rcp_f32_e32 v225, v224
	v_div_scale_f32 v226, vcc, s70, v149, s70
	v_cmp_lt_f32_e64 s[98:99], 0, v149
	v_fma_f32 v227, -v224, v225, 1.0
	v_fmac_f32_e32 v225, v227, v225
	v_mul_f32_e32 v227, v226, v225
	v_fma_f32 v228, -v224, v227, v226
	v_fmac_f32_e32 v227, v228, v225
	v_fma_f32 v224, -v224, v227, v226
	v_div_fmas_f32 v224, v224, v225, v227
	v_div_fixup_f32 v224, v224, v149, s70
	v_mul_f32_e32 v229, 0x3b924925, v149
	v_cndmask_b32_e64 v230, 1.0, v224, s[98:99]
	v_cndmask_b32_e64 v229, 1.0, v229, s[98:99]
	v_pk_mul_f32 v[182:183], v[182:183], v[230:231] op_sel_hi:[1,0]
	v_pk_mul_f32 v[184:185], v[184:185], v[230:231] op_sel_hi:[1,0]
	v_pk_mul_f32 v[186:187], v[186:187], v[230:231] op_sel_hi:[1,0]
	v_pk_mul_f32 v[188:189], v[188:189], v[230:231] op_sel_hi:[1,0]
	v_pk_mul_f32 v[190:191], v[190:191], v[230:231] op_sel_hi:[1,0]
	v_pk_mul_f32 v[192:193], v[192:193], v[230:231] op_sel_hi:[1,0]
	v_pk_mul_f32 v[194:195], v[194:195], v[230:231] op_sel_hi:[1,0]
	v_pk_mul_f32 v[196:197], v[196:197], v[230:231] op_sel_hi:[1,0]
	v_pk_mul_f32 v[198:199], v[198:199], v[230:231] op_sel_hi:[1,0]
	v_pk_mul_f32 v[200:201], v[200:201], v[230:231] op_sel_hi:[1,0]
	v_pk_mul_f32 v[202:203], v[202:203], v[230:231] op_sel_hi:[1,0]
	v_pk_mul_f32 v[204:205], v[204:205], v[230:231] op_sel_hi:[1,0]
	v_pk_mul_f32 v[206:207], v[206:207], v[230:231] op_sel_hi:[1,0]
	v_pk_mul_f32 v[208:209], v[208:209], v[230:231] op_sel_hi:[1,0]
	v_pk_mul_f32 v[210:211], v[210:211], v[230:231] op_sel_hi:[1,0]
	v_pk_mul_f32 v[212:213], v[212:213], v[230:231] op_sel_hi:[1,0]
	v_cvt_pk_fp8_f32 v216, v182, v183
	v_cvt_pk_fp8_f32 v217, v186, v187
	v_cvt_pk_fp8_f32 v218, v190, v191
	v_cvt_pk_fp8_f32 v219, v194, v195
	v_cvt_pk_fp8_f32 v220, v198, v199
	v_cvt_pk_fp8_f32 v221, v202, v203
	v_cvt_pk_fp8_f32 v222, v206, v207
	v_cvt_pk_fp8_f32 v223, v210, v211
	v_cvt_pk_fp8_f32 v216, v184, v185 op_sel:[0,0,1]
	v_cvt_pk_fp8_f32 v217, v188, v189 op_sel:[0,0,1]
	v_cvt_pk_fp8_f32 v218, v192, v193 op_sel:[0,0,1]
	v_cvt_pk_fp8_f32 v219, v196, v197 op_sel:[0,0,1]
	v_cvt_pk_fp8_f32 v220, v200, v201 op_sel:[0,0,1]
	v_cvt_pk_fp8_f32 v221, v204, v205 op_sel:[0,0,1]
	v_cvt_pk_fp8_f32 v222, v208, v209 op_sel:[0,0,1]
	v_cvt_pk_fp8_f32 v223, v212, v213 op_sel:[0,0,1]
	s_nop 0
	global_store_dwordx4 v[140:141], v[216:219], off offset:128
	global_store_dwordx4 v[142:143], v[220:223], off offset:128
	global_store_dword v148, v229, s[100:101] offset:4
	s_lshl_b32 s0, s73, 4
	s_and_b32 s75, s0, 0xffffff80
	v_or_b32_e32 v0, s75, v77
	v_ashrrev_i32_e32 v1, 31, v0
	v_readlane_b32 s0, v235, 49
	s_and_b32 s74, s73, 7
	v_lshlrev_b64 v[0:1], 12, v[0:1]
	v_readlane_b32 s1, v235, 50
	s_lshl_b32 s44, s74, 9
	s_nop 0
	v_lshl_add_u64 v[0:1], s[0:1], 0, v[0:1]
	v_lshl_add_u64 v[0:1], v[0:1], 0, s[44:45]
	v_lshl_add_u64 v[0:1], s[34:35], 1, v[0:1]
	v_lshl_add_u64 v[130:131], v[0:1], 0, v[64:65]
	v_lshl_add_u32 v0, s74, 8, v78
	v_ashrrev_i32_e32 v1, 31, v0
	v_lshlrev_b64 v[0:1], 8, v[0:1]
	v_lshl_add_u64 v[132:133], v[66:67], 0, v[0:1]
	global_load_dwordx4 v[16:19], v[130:131], off
	global_load_dwordx4 v[0:3], v[132:133], off
	v_add_co_u32_e32 v134, vcc, s66, v132
	s_mov_b32 s44, 64
	s_nop 0
	v_addc_co_u32_e32 v135, vcc, 0, v133, vcc
	v_add_co_u32_e32 v136, vcc, s67, v132
	global_load_dwordx4 v[4:7], v[134:135], off
	s_nop 0
	v_addc_co_u32_e32 v137, vcc, 0, v133, vcc
	global_load_dwordx4 v[8:11], v[136:137], off
	v_add_co_u32_e32 v138, vcc, s68, v132
	s_waitcnt vmcnt(2)
	v_mfma_f32_32x32x16_bf16 v[32:47], v[16:19], v[0:3], 0
	v_addc_co_u32_e32 v139, vcc, 0, v133, vcc
	global_load_dwordx4 v[20:23], v[138:139], off
	global_load_dwordx4 v[98:101], v[130:131], off offset:32
	global_load_dwordx4 v[102:105], v[132:133], off offset:32
	global_load_dwordx4 v[106:109], v[134:135], off offset:32
	global_load_dwordx4 v[110:113], v[136:137], off offset:32
	global_load_dwordx4 v[114:117], v[138:139], off offset:32
	global_load_dwordx4 v[118:121], v[130:131], off offset:64
	global_load_dwordx4 v[122:125], v[132:133], off offset:64
	s_waitcnt vmcnt(9)
	v_mfma_f32_32x32x16_bf16 v[48:63], v[16:19], v[4:7], 0
	s_waitcnt vmcnt(8)
	v_mfma_f32_32x32x16_bf16 v[0:15], v[16:19], v[8:11], 0
	s_waitcnt vmcnt(7)
	v_mfma_f32_32x32x16_bf16 v[16:31], v[16:19], v[20:23], 0
	s_waitcnt vmcnt(5)
	v_mfma_f32_32x32x16_bf16 v[32:47], v[98:101], v[102:105], v[32:47]
	global_load_dwordx4 v[102:105], v[134:135], off offset:64
	s_waitcnt vmcnt(5)
	v_mfma_f32_32x32x16_bf16 v[48:63], v[98:101], v[106:109], v[48:63]
	global_load_dwordx4 v[106:109], v[136:137], off offset:64
	s_waitcnt vmcnt(5)
	v_mfma_f32_32x32x16_bf16 v[0:15], v[98:101], v[110:113], v[0:15]
	global_load_dwordx4 v[110:113], v[138:139], off offset:64
	global_load_dwordx4 v[126:129], v[130:131], off offset:96
	s_waitcnt vmcnt(6)
	v_mfma_f32_32x32x16_bf16 v[16:31], v[98:101], v[114:117], v[16:31]
	global_load_dwordx4 v[98:101], v[132:133], off offset:96
	global_load_dwordx4 v[114:117], v[134:135], off offset:96
	s_waitcnt vmcnt(6)
	v_mfma_f32_32x32x16_bf16 v[32:47], v[118:121], v[122:125], v[32:47]
	s_waitcnt vmcnt(5)
	v_mfma_f32_32x32x16_bf16 v[48:63], v[118:121], v[102:105], v[48:63]
	global_load_dwordx4 v[102:105], v[136:137], off offset:96
	s_waitcnt vmcnt(5)
	v_mfma_f32_32x32x16_bf16 v[0:15], v[118:121], v[106:109], v[0:15]
	global_load_dwordx4 v[106:109], v[138:139], off offset:96
	global_load_dwordx4 v[122:125], v[130:131], off offset:128
	s_waitcnt vmcnt(6)
; __device__ __forceinline__ int crow(int r, int hi) { return (r & 3) + 8 * (r >> 2) + 4 * hi; }
; __global__ void __launch_bounds__(NTHR, 2) fwd_megakernel(Args a) {
;     ...
;                 for (int ks = 0; ks < 8; ++ks) {
;                     const bf16x8 af = *(const bf16x8*)(qa + ks * 16);
; #pragma unroll
;                     for (int nb = 0; nb < 4; ++nb) { const bf16x8 bf = *(const bf16x8*)(kb + nb * 32 * 128 + ks * 16); acc[nb] = __builtin_amdgcn_mfma_f32_32x32x16_bf16(af, bf, acc[nb], 0, 0, 0); }
;                 }
; #pragma unroll
;                 for (int nb = 0; nb < 4; ++nb)
; #pragma unroll
;                     for (int i = 0; i < 16; ++i) SC[(p * 128 + r0 + crow(i, hi)) * 129 + nb * 32 + l31] = acc[nb][i];
;             }
;             __syncthreads();
;             {
;                 const int row = tid & 255, hf = tid >> 8;
;                 unsigned v[16];
; #pragma unroll
;                 for (int j = 0; j < 16; ++j) v[j] = 0u;
	v_mfma_f32_32x32x16_bf16 v[16:31], v[118:121], v[110:113], v[16:31]
	global_load_dwordx4 v[110:113], v[132:133], off offset:128
	s_waitcnt vmcnt(5)
	v_mfma_f32_32x32x16_bf16 v[32:47], v[126:129], v[98:101], v[32:47]
	global_load_dwordx4 v[98:101], v[134:135], off offset:128
	s_waitcnt vmcnt(5)
	v_mfma_f32_32x32x16_bf16 v[48:63], v[126:129], v[114:117], v[48:63]
	global_load_dwordx4 v[114:117], v[136:137], off offset:128
	s_waitcnt vmcnt(5)
	v_mfma_f32_32x32x16_bf16 v[0:15], v[126:129], v[102:105], v[0:15]
	global_load_dwordx4 v[102:105], v[138:139], off offset:128
	global_load_dwordx4 v[118:121], v[130:131], off offset:160
	s_waitcnt vmcnt(4)
	v_mfma_f32_32x32x16_bf16 v[32:47], v[122:125], v[110:113], v[32:47]
	global_load_dwordx4 v[110:113], v[134:135], off offset:160
	s_waitcnt vmcnt(4)
	v_mfma_f32_32x32x16_bf16 v[48:63], v[122:125], v[98:101], v[48:63]
	global_load_dwordx4 v[98:101], v[136:137], off offset:160
	v_mfma_f32_32x32x16_bf16 v[16:31], v[126:129], v[106:109], v[16:31]
	global_load_dwordx4 v[106:109], v[132:133], off offset:160
	s_waitcnt vmcnt(5)
	v_mfma_f32_32x32x16_bf16 v[0:15], v[122:125], v[114:117], v[0:15]
	global_load_dwordx4 v[114:117], v[138:139], off offset:160
	s_waitcnt vmcnt(2)
	v_mfma_f32_32x32x16_bf16 v[0:15], v[118:121], v[98:101], v[0:15]
	global_load_dwordx4 v[98:101], v[130:131], off offset:192
	v_mfma_f32_32x32x16_bf16 v[16:31], v[122:125], v[102:105], v[16:31]
	s_waitcnt vmcnt(2)
	v_mfma_f32_32x32x16_bf16 v[32:47], v[118:121], v[106:109], v[32:47]
	v_mfma_f32_32x32x16_bf16 v[48:63], v[118:121], v[110:113], v[48:63]
	global_load_dwordx4 v[102:105], v[132:133], off offset:192
	global_load_dwordx4 v[106:109], v[130:131], off offset:224
	global_load_dwordx4 v[110:113], v[132:133], off offset:224
	s_waitcnt vmcnt(4)
	v_mfma_f32_32x32x16_bf16 v[16:31], v[118:121], v[114:117], v[16:31]
	s_waitcnt vmcnt(2)
	v_mfma_f32_32x32x16_bf16 v[32:47], v[98:101], v[102:105], v[32:47]
	global_load_dwordx4 v[102:105], v[134:135], off offset:192
	global_load_dwordx4 v[114:117], v[134:135], off offset:224
	s_waitcnt vmcnt(1)
	v_mfma_f32_32x32x16_bf16 v[48:63], v[98:101], v[102:105], v[48:63]
	global_load_dwordx4 v[102:105], v[136:137], off offset:192
	global_load_dwordx4 v[118:121], v[136:137], off offset:224
	s_waitcnt vmcnt(1)
	v_mfma_f32_32x32x16_bf16 v[0:15], v[98:101], v[102:105], v[0:15]
	global_load_dwordx4 v[102:105], v[138:139], off offset:192
	v_mfma_f32_32x32x16_bf16 v[32:47], v[106:109], v[110:113], v[32:47]
	global_load_dwordx4 v[110:113], v[138:139], off offset:224
	s_waitcnt vmcnt(1)
	v_mfma_f32_32x32x16_bf16 v[16:31], v[98:101], v[102:105], v[16:31]
	v_mfma_f32_32x32x16_bf16 v[48:63], v[106:109], v[114:117], v[48:63]
	s_nop 11
	ds_write2_b32 v84, v32, v48 offset1:32
	ds_write2_b32 v84, v33, v49 offset0:129 offset1:161
	v_mfma_f32_32x32x16_bf16 v[0:15], v[106:109], v[118:121], v[0:15]
	ds_write2_b32 v89, v34, v50 offset0:2 offset1:34
	ds_write2_b32 v89, v35, v51 offset0:131 offset1:163
	ds_write2_b32 v90, v36, v52 offset0:8 offset1:40
	ds_write2_b32 v90, v37, v53 offset0:137 offset1:169
	ds_write2_b32 v91, v38, v54 offset0:10 offset1:42
	ds_write2_b32 v91, v39, v55 offset0:139 offset1:171
	ds_write2_b32 v92, v40, v56 offset0:16 offset1:48
	ds_write2_b32 v92, v41, v57 offset0:145 offset1:177
	ds_write2_b32 v93, v42, v58 offset0:18 offset1:50
	ds_write2_b32 v93, v43, v59 offset0:147 offset1:179
	ds_write2_b32 v94, v44, v60 offset0:24 offset1:56
	ds_write2_b32 v94, v45, v61 offset0:153 offset1:185
	ds_write2_b32 v95, v46, v62 offset0:26 offset1:58
	ds_write2_b32 v95, v47, v63 offset0:155 offset1:187
	s_waitcnt vmcnt(0)
	v_mfma_f32_32x32x16_bf16 v[16:31], v[106:109], v[110:113], v[16:31]
	s_nop 11
	ds_write2_b32 v84, v0, v16 offset0:64 offset1:96
	ds_write2_b32 v84, v1, v17 offset0:193 offset1:225
	ds_write2_b32 v89, v2, v18 offset0:66 offset1:98
	ds_write2_b32 v89, v3, v19 offset0:195 offset1:227
	ds_write2_b32 v90, v4, v20 offset0:72 offset1:104
	ds_write2_b32 v90, v5, v21 offset0:201 offset1:233
	ds_write2_b32 v91, v6, v22 offset0:74 offset1:106
	ds_write2_b32 v91, v7, v23 offset0:203 offset1:235
	ds_write2_b32 v92, v8, v24 offset0:80 offset1:112
	ds_write2_b32 v92, v9, v25 offset0:209 offset1:241
	ds_write2_b32 v93, v10, v26 offset0:82 offset1:114
	ds_write2_b32 v93, v11, v27 offset0:211 offset1:243
	ds_write2_b32 v94, v12, v28 offset0:88 offset1:120
	ds_write2_b32 v94, v13, v29 offset0:217 offset1:249
	ds_write2_b32 v95, v14, v30 offset0:90 offset1:122
	ds_write2_b32 v95, v15, v31 offset0:219 offset1:251
	v_mov_b32_e32 v24, v79
	v_mov_b32_e32 v0, 0
	v_mov_b32_e32 v1, 0
	v_mov_b32_e32 v2, 0
	v_mov_b32_e32 v3, 0
	v_mov_b32_e32 v4, 0
	v_mov_b32_e32 v5, 0
	v_mov_b32_e32 v6, 0
	v_mov_b32_e32 v7, 0
	v_mov_b32_e32 v8, 0
	v_mov_b32_e32 v9, 0
	v_mov_b32_e32 v10, 0
	v_mov_b32_e32 v11, 0
	v_mov_b32_e32 v12, 0
	v_mov_b32_e32 v13, 0
	v_mov_b32_e32 v14, 0
	v_mov_b32_e32 v15, 0
	s_waitcnt lgkmcnt(0)
	s_barrier
	v_readlane_b32 s98, v235, 1
	s_nop 0
	s_add_i32 s98, s73, s98
	s_cmpk_gt_i32 s98, 0x7ff
	s_cbranch_scc1 .Lcv_nopf_b
	s_lshl_b32 s98, s98, 4
	s_add_i32 s99, s59, 4
	s_lshl_b32 s99, s99, 1
	s_add_i32 s98, s98, s99
	s_and_b32 s99, s98, 0x3fff
	s_lshl_b32 s100, s99, 13
	s_mov_b32 s101, 0
	s_cmpk_gt_i32 s98, 0x3fff
	s_cbranch_scc1 .Lcv_pfv_b
	v_lshl_add_u64 v[140:141], v[72:73], 0, s[100:101]
	s_branch .Lcv_pfj_b

; #define LAS __attribute__((address_space(3)))
; __device__ __forceinline__ unsigned umed3(unsigned a, unsigned b, unsigned c) { unsigned r; asm("v_med3_u32 %0, %1, %2, %3" : "=v"(r) : "v"(a), "v"(b), "v"(c)); return r; }
; __device__ __forceinline__ unsigned orderable(float s) { unsigned u = __builtin_bit_cast(unsigned, s); return (u >> 31) ? ~u : (u | 0x80000000u); }
; __global__ void __launch_bounds__(NTHR, 2) fwd_megakernel(Args a) {
;     ...
;                 const LAS float* sr = SC + row * 129 + hf * 64;
; #pragma unroll 8
;                 for (int k = 0; k < 64; ++k) {
;                     const unsigned uk = (orderable(sr[k]) & ~127u) | (unsigned)(127 - (hf * 64 + k));
; #pragma unroll
;                     for (int j = 15; j >= 1; --j) v[j] = umed3(v[j - 1], v[j], uk);
;                     v[0] = v[0] > uk ? v[0] : uk;
;                 }
;                 if (hf == 1) {
; #pragma unroll
;                     for (int q = 0; q < 4; ++q) *(LAS u32x4*)(KX + row * 16 + 4 * q) = (u32x4){v[4 * q], v[4 * q + 1], v[4 * q + 2], v[4 * q + 3]};
;                 }
.Lcv_nopf_b:
.LBB0_797:
	ds_read2_b32 v[16:17], v24 offset1:1
	ds_read2_b32 v[22:23], v24 offset0:2 offset1:3
	ds_read2_b32 v[20:21], v24 offset0:4 offset1:5
	ds_read2_b32 v[18:19], v24 offset0:6 offset1:7
	v_add_u32_e32 v25, s44, v85
	s_waitcnt lgkmcnt(3)
	v_not_b32_e32 v33, v16
	v_or_b32_e32 v34, 0x80000000, v16
	v_cmp_gt_i32_e64 s[24:25], 0, v16
	v_add_u32_e32 v26, 63, v25
	v_not_b32_e32 v35, v17
	v_or_b32_e32 v36, 0x80000000, v17
	v_cmp_gt_i32_e32 vcc, 0, v17
	v_cndmask_b32_e64 v16, v34, v33, s[24:25]
	v_add_u32_e32 v27, 62, v25
	s_waitcnt lgkmcnt(2)
	v_not_b32_e32 v17, v22
	v_or_b32_e32 v37, 0x80000000, v22
	v_cmp_gt_i32_e64 s[0:1], 0, v22
	v_not_b32_e32 v22, v23
	v_or_b32_e32 v38, 0x80000000, v23
	v_cmp_gt_i32_e64 s[14:15], 0, v23
	s_waitcnt lgkmcnt(1)
	v_not_b32_e32 v23, v20
	v_or_b32_e32 v39, 0x80000000, v20
	v_cmp_gt_i32_e64 s[16:17], 0, v20
	v_not_b32_e32 v20, v21
	v_or_b32_e32 v40, 0x80000000, v21
	v_cmp_gt_i32_e64 s[18:19], 0, v21
	s_waitcnt lgkmcnt(0)
	v_not_b32_e32 v21, v18
	v_or_b32_e32 v41, 0x80000000, v18
	v_cmp_gt_i32_e64 s[20:21], 0, v18
	v_not_b32_e32 v18, v19
	v_or_b32_e32 v42, 0x80000000, v19
	v_cmp_gt_i32_e64 s[22:23], 0, v19
	v_cndmask_b32_e32 v19, v36, v35, vcc
	v_and_or_b32 v16, v16, s33, v26
	v_add_u32_e32 v28, 61, v25
	v_cndmask_b32_e64 v17, v37, v17, s[0:1]
	v_and_or_b32 v19, v19, s33, v27
	v_med3_u32 v15, v14, v15, v16
	v_med3_u32 v14, v13, v14, v16
	v_med3_u32 v13, v12, v13, v16
	v_med3_u32 v12, v11, v12, v16
	v_med3_u32 v11, v10, v11, v16
	v_med3_u32 v10, v9, v10, v16
	v_med3_u32 v9, v8, v9, v16
	v_med3_u32 v8, v7, v8, v16
	v_med3_u32 v7, v6, v7, v16
	v_med3_u32 v6, v5, v6, v16
	v_med3_u32 v5, v4, v5, v16
	v_med3_u32 v4, v3, v4, v16
	v_med3_u32 v3, v2, v3, v16
	v_med3_u32 v2, v1, v2, v16
	v_med3_u32 v1, v0, v1, v16
	v_max_u32_e32 v0, v0, v16
	v_add_u32_e32 v29, 60, v25
	v_cndmask_b32_e64 v22, v38, v22, s[14:15]
	v_and_or_b32 v17, v17, s33, v28
	v_med3_u32 v15, v14, v15, v19
	v_med3_u32 v14, v13, v14, v19
	v_med3_u32 v13, v12, v13, v19
	v_med3_u32 v12, v11, v12, v19
	v_med3_u32 v11, v10, v11, v19
	v_med3_u32 v10, v9, v10, v19
	v_med3_u32 v9, v8, v9, v19
	v_med3_u32 v8, v7, v8, v19
	v_med3_u32 v7, v6, v7, v19
	v_med3_u32 v6, v5, v6, v19
	v_med3_u32 v5, v4, v5, v19
	v_med3_u32 v4, v3, v4, v19
	v_med3_u32 v3, v2, v3, v19
	v_med3_u32 v2, v1, v2, v19
	v_med3_u32 v1, v0, v1, v19
	v_max_u32_e32 v0, v0, v19
	v_add_u32_e32 v30, 59, v25
	v_cndmask_b32_e64 v23, v39, v23, s[16:17]
	v_and_or_b32 v22, v22, s33, v29
	v_med3_u32 v15, v14, v15, v17
	v_med3_u32 v14, v13, v14, v17
	v_med3_u32 v13, v12, v13, v17
	v_med3_u32 v12, v11, v12, v17
	v_med3_u32 v11, v10, v11, v17
	v_med3_u32 v10, v9, v10, v17
	v_med3_u32 v9, v8, v9, v17
	v_med3_u32 v8, v7, v8, v17
	v_med3_u32 v7, v6, v7, v17
	v_med3_u32 v6, v5, v6, v17
	v_med3_u32 v5, v4, v5, v17
	v_med3_u32 v4, v3, v4, v17
	v_med3_u32 v3, v2, v3, v17
	v_med3_u32 v2, v1, v2, v17
	v_med3_u32 v1, v0, v1, v17
	v_max_u32_e32 v0, v0, v17
	v_add_u32_e32 v31, 58, v25
	v_cndmask_b32_e64 v20, v40, v20, s[18:19]
	v_and_or_b32 v23, v23, s33, v30
	v_med3_u32 v15, v14, v15, v22
	v_med3_u32 v14, v13, v14, v22
	v_med3_u32 v13, v12, v13, v22
	v_med3_u32 v12, v11, v12, v22
	v_med3_u32 v11, v10, v11, v22
	v_med3_u32 v10, v9, v10, v22
	v_med3_u32 v9, v8, v9, v22
	v_med3_u32 v8, v7, v8, v22
	v_med3_u32 v7, v6, v7, v22
	v_med3_u32 v6, v5, v6, v22
	v_med3_u32 v5, v4, v5, v22
	v_med3_u32 v4, v3, v4, v22
	v_med3_u32 v3, v2, v3, v22
	v_med3_u32 v2, v1, v2, v22
	v_med3_u32 v1, v0, v1, v22
	v_max_u32_e32 v0, v0, v22
	v_add_u32_e32 v32, 57, v25
	v_cndmask_b32_e64 v21, v41, v21, s[20:21]
	v_and_or_b32 v20, v20, s33, v31
	v_med3_u32 v15, v14, v15, v23
	v_med3_u32 v14, v13, v14, v23
	v_med3_u32 v13, v12, v13, v23
	v_med3_u32 v12, v11, v12, v23
	v_med3_u32 v11, v10, v11, v23
	v_med3_u32 v10, v9, v10, v23
	v_med3_u32 v9, v8, v9, v23
	v_med3_u32 v8, v7, v8, v23
	v_med3_u32 v7, v6, v7, v23
	v_med3_u32 v6, v5, v6, v23
	v_med3_u32 v5, v4, v5, v23
	v_med3_u32 v4, v3, v4, v23
	v_med3_u32 v3, v2, v3, v23
	v_med3_u32 v2, v1, v2, v23
	v_med3_u32 v1, v0, v1, v23
	v_max_u32_e32 v0, v0, v23
	v_add_u32_e32 v25, 56, v25
	v_cndmask_b32_e64 v18, v42, v18, s[22:23]
	v_and_or_b32 v21, v21, s33, v32
	v_med3_u32 v15, v14, v15, v20
	v_med3_u32 v14, v13, v14, v20
	v_med3_u32 v13, v12, v13, v20
	v_med3_u32 v12, v11, v12, v20
	v_med3_u32 v11, v10, v11, v20
	v_med3_u32 v10, v9, v10, v20
	v_med3_u32 v9, v8, v9, v20
	v_med3_u32 v8, v7, v8, v20
	v_med3_u32 v7, v6, v7, v20
	v_med3_u32 v6, v5, v6, v20
	v_med3_u32 v5, v4, v5, v20
	v_med3_u32 v4, v3, v4, v20
	v_med3_u32 v3, v2, v3, v20
	v_med3_u32 v2, v1, v2, v20
	v_med3_u32 v1, v0, v1, v20
	v_max_u32_e32 v0, v0, v20
	s_add_i32 s44, s44, -8
	v_and_or_b32 v18, v18, s33, v25
	v_med3_u32 v15, v14, v15, v21
	v_med3_u32 v14, v13, v14, v21
	v_med3_u32 v13, v12, v13, v21
	v_med3_u32 v12, v11, v12, v21
	v_med3_u32 v11, v10, v11, v21
	v_med3_u32 v10, v9, v10, v21
	v_med3_u32 v9, v8, v9, v21
	v_med3_u32 v8, v7, v8, v21
	v_med3_u32 v7, v6, v7, v21
	v_med3_u32 v6, v5, v6, v21
	v_med3_u32 v5, v4, v5, v21
	v_med3_u32 v4, v3, v4, v21
	v_med3_u32 v3, v2, v3, v21
	v_med3_u32 v2, v1, v2, v21
	v_med3_u32 v1, v0, v1, v21
	v_max_u32_e32 v0, v0, v21
	v_add_u32_e32 v24, 32, v24
	s_cmp_eq_u32 s44, 0
	v_med3_u32 v15, v14, v15, v18
	v_med3_u32 v14, v13, v14, v18
	v_med3_u32 v13, v12, v13, v18
	v_med3_u32 v12, v11, v12, v18
	v_med3_u32 v11, v10, v11, v18
	v_med3_u32 v10, v9, v10, v18
	v_med3_u32 v9, v8, v9, v18
	v_med3_u32 v8, v7, v8, v18
	v_med3_u32 v7, v6, v7, v18
	v_med3_u32 v6, v5, v6, v18
	v_med3_u32 v5, v4, v5, v18
	v_med3_u32 v4, v3, v4, v18
	v_med3_u32 v3, v2, v3, v18
	v_med3_u32 v2, v1, v2, v18
	v_med3_u32 v1, v0, v1, v18
	v_max_u32_e32 v0, v0, v18
	s_cbranch_scc0 .LBB0_797
	s_and_saveexec_b64 s[0:1], s[6:7]
	s_cbranch_execz .LBB0_800
	ds_write_b128 v86, v[0:3]
	ds_write_b128 v86, v[4:7] offset:16
	ds_write_b128 v86, v[8:11] offset:32
	ds_write_b128 v86, v[12:15] offset:48
; #define LAS __attribute__((address_space(3)))
; __device__ __forceinline__ unsigned umed3(unsigned a, unsigned b, unsigned c) { unsigned r; asm("v_med3_u32 %0, %1, %2, %3" : "=v"(r) : "v"(a), "v"(b), "v"(c)); return r; }
; __global__ void __launch_bounds__(NTHR, 2) fwd_megakernel(Args a) {
;     ...
;                 __syncthreads();
;                 if (hf == 0) {
; #pragma unroll
;                     for (int q = 0; q < 4; ++q) { const u32x4 o = *(const LAS u32x4*)(KX + row * 16 + 4 * q);
; #pragma unroll
;                         for (int c = 0; c < 4; ++c) { const unsigned uk = o[c];
; #pragma unroll
;                             for (int j = 15; j >= 1; --j) v[j] = umed3(v[j - 1], v[j], uk);
;                             v[0] = v[0] > uk ? v[0] : uk; } }
.LBB0_800:
	s_or_b64 exec, exec, s[0:1]
	s_waitcnt lgkmcnt(0)
	s_barrier
	s_and_saveexec_b64 s[0:1], s[8:9]
	s_xor_b64 s[14:15], exec, s[0:1]
	s_cbranch_execz .LBB0_802
.LBB0_802:
	s_andn2_saveexec_b64 s[0:1], s[14:15]
	s_cbranch_execz .LBB0_804
	ds_read_b128 v[28:31], v87
	ds_read_b128 v[24:27], v87 offset:16
	ds_read_b128 v[20:23], v87 offset:32
	ds_read_b128 v[16:19], v87 offset:48
	s_waitcnt lgkmcnt(3)
	v_med3_u32 v15, v14, v15, v28
	v_med3_u32 v14, v13, v14, v28
	v_med3_u32 v13, v12, v13, v28
	v_med3_u32 v12, v11, v12, v28
	v_med3_u32 v11, v10, v11, v28
	v_med3_u32 v10, v9, v10, v28
	v_med3_u32 v9, v8, v9, v28
	v_med3_u32 v8, v7, v8, v28
	v_med3_u32 v7, v6, v7, v28
	v_med3_u32 v6, v5, v6, v28
	v_med3_u32 v5, v4, v5, v28
	v_med3_u32 v4, v3, v4, v28
	v_med3_u32 v3, v2, v3, v28
	v_med3_u32 v2, v1, v2, v28
	v_med3_u32 v1, v0, v1, v28
	v_max_u32_e32 v0, v0, v28
	v_med3_u32 v15, v14, v15, v29
	v_med3_u32 v14, v13, v14, v29
	v_med3_u32 v13, v12, v13, v29
	v_med3_u32 v12, v11, v12, v29
	v_med3_u32 v11, v10, v11, v29
	v_med3_u32 v10, v9, v10, v29
	v_med3_u32 v9, v8, v9, v29
	v_med3_u32 v8, v7, v8, v29
	v_med3_u32 v7, v6, v7, v29
	v_med3_u32 v6, v5, v6, v29
	v_med3_u32 v5, v4, v5, v29
	v_med3_u32 v4, v3, v4, v29
	v_med3_u32 v3, v2, v3, v29
	v_med3_u32 v2, v1, v2, v29
	v_med3_u32 v1, v0, v1, v29
	v_max_u32_e32 v0, v0, v29
	v_med3_u32 v15, v14, v15, v30
	v_med3_u32 v14, v13, v14, v30
	v_med3_u32 v13, v12, v13, v30
	v_med3_u32 v12, v11, v12, v30
	v_med3_u32 v11, v10, v11, v30
	v_med3_u32 v10, v9, v10, v30
	v_med3_u32 v9, v8, v9, v30
	v_med3_u32 v8, v7, v8, v30
	v_med3_u32 v7, v6, v7, v30
	v_med3_u32 v6, v5, v6, v30
	v_med3_u32 v5, v4, v5, v30
	v_med3_u32 v4, v3, v4, v30
	v_med3_u32 v3, v2, v3, v30
	v_med3_u32 v2, v1, v2, v30
	v_med3_u32 v1, v0, v1, v30
	v_max_u32_e32 v0, v0, v30
	v_med3_u32 v15, v14, v15, v31
	v_med3_u32 v14, v13, v14, v31
	v_med3_u32 v13, v12, v13, v31
	v_med3_u32 v12, v11, v12, v31
	v_med3_u32 v11, v10, v11, v31
	v_med3_u32 v10, v9, v10, v31
	v_med3_u32 v9, v8, v9, v31
	v_med3_u32 v8, v7, v8, v31
	v_med3_u32 v7, v6, v7, v31
	v_med3_u32 v6, v5, v6, v31
	v_med3_u32 v5, v4, v5, v31
	v_med3_u32 v4, v3, v4, v31
	v_med3_u32 v3, v2, v3, v31
	v_med3_u32 v2, v1, v2, v31
	v_med3_u32 v1, v0, v1, v31
	v_max_u32_e32 v0, v0, v31
	s_waitcnt lgkmcnt(2)
	v_med3_u32 v15, v14, v15, v24
	v_med3_u32 v14, v13, v14, v24
	v_med3_u32 v13, v12, v13, v24
	v_med3_u32 v12, v11, v12, v24
	v_med3_u32 v11, v10, v11, v24
	v_med3_u32 v10, v9, v10, v24
	v_med3_u32 v9, v8, v9, v24
	v_med3_u32 v8, v7, v8, v24
	v_med3_u32 v7, v6, v7, v24
	v_med3_u32 v6, v5, v6, v24
	v_med3_u32 v5, v4, v5, v24
	v_med3_u32 v4, v3, v4, v24
	v_med3_u32 v3, v2, v3, v24
	v_med3_u32 v2, v1, v2, v24
	v_med3_u32 v1, v0, v1, v24
	v_max_u32_e32 v0, v0, v24
	v_med3_u32 v15, v14, v15, v25
	v_med3_u32 v14, v13, v14, v25
	v_med3_u32 v13, v12, v13, v25
	v_med3_u32 v12, v11, v12, v25
	v_med3_u32 v11, v10, v11, v25
	v_med3_u32 v10, v9, v10, v25
	v_med3_u32 v9, v8, v9, v25
	v_med3_u32 v8, v7, v8, v25
	v_med3_u32 v7, v6, v7, v25
	v_med3_u32 v6, v5, v6, v25
	v_med3_u32 v5, v4, v5, v25
	v_med3_u32 v4, v3, v4, v25
	v_med3_u32 v3, v2, v3, v25
	v_med3_u32 v2, v1, v2, v25
	v_med3_u32 v1, v0, v1, v25
	v_max_u32_e32 v0, v0, v25
	v_med3_u32 v15, v14, v15, v26
	v_med3_u32 v14, v13, v14, v26
	v_med3_u32 v13, v12, v13, v26
	v_med3_u32 v12, v11, v12, v26
	v_med3_u32 v11, v10, v11, v26
	v_med3_u32 v10, v9, v10, v26
	v_med3_u32 v9, v8, v9, v26
	v_med3_u32 v8, v7, v8, v26
	v_med3_u32 v7, v6, v7, v26
	v_med3_u32 v6, v5, v6, v26
	v_med3_u32 v5, v4, v5, v26
	v_med3_u32 v4, v3, v4, v26
	v_med3_u32 v3, v2, v3, v26
	v_med3_u32 v2, v1, v2, v26
	v_med3_u32 v1, v0, v1, v26
	v_max_u32_e32 v0, v0, v26
	v_med3_u32 v15, v14, v15, v27
	v_med3_u32 v14, v13, v14, v27
	v_med3_u32 v13, v12, v13, v27
	v_med3_u32 v12, v11, v12, v27
	v_med3_u32 v11, v10, v11, v27
	v_med3_u32 v10, v9, v10, v27
	v_med3_u32 v9, v8, v9, v27
	v_med3_u32 v8, v7, v8, v27
	v_med3_u32 v7, v6, v7, v27
	v_med3_u32 v6, v5, v6, v27
	v_med3_u32 v5, v4, v5, v27
	v_med3_u32 v4, v3, v4, v27
	v_med3_u32 v3, v2, v3, v27
	v_med3_u32 v2, v1, v2, v27
	v_med3_u32 v1, v0, v1, v27
	v_max_u32_e32 v0, v0, v27
	s_waitcnt lgkmcnt(1)
	v_med3_u32 v15, v14, v15, v20
	v_med3_u32 v14, v13, v14, v20
	v_med3_u32 v13, v12, v13, v20
	v_med3_u32 v12, v11, v12, v20
	v_med3_u32 v11, v10, v11, v20
	v_med3_u32 v10, v9, v10, v20
	v_med3_u32 v9, v8, v9, v20
	v_med3_u32 v8, v7, v8, v20
	v_med3_u32 v7, v6, v7, v20
	v_med3_u32 v6, v5, v6, v20
	v_med3_u32 v5, v4, v5, v20
	v_med3_u32 v4, v3, v4, v20
	v_med3_u32 v3, v2, v3, v20
	v_med3_u32 v2, v1, v2, v20
	v_med3_u32 v1, v0, v1, v20
	v_max_u32_e32 v0, v0, v20
	v_med3_u32 v15, v14, v15, v21
	v_med3_u32 v14, v13, v14, v21
	v_med3_u32 v13, v12, v13, v21
	v_med3_u32 v12, v11, v12, v21
	v_med3_u32 v11, v10, v11, v21
	v_med3_u32 v10, v9, v10, v21
	v_med3_u32 v9, v8, v9, v21
	v_med3_u32 v8, v7, v8, v21
	v_med3_u32 v7, v6, v7, v21
	v_med3_u32 v6, v5, v6, v21
	v_med3_u32 v5, v4, v5, v21
	v_med3_u32 v4, v3, v4, v21
	v_med3_u32 v3, v2, v3, v21
	v_med3_u32 v2, v1, v2, v21
	v_med3_u32 v1, v0, v1, v21
	v_max_u32_e32 v0, v0, v21
	v_med3_u32 v15, v14, v15, v22
	v_med3_u32 v14, v13, v14, v22
	v_med3_u32 v13, v12, v13, v22
	v_med3_u32 v12, v11, v12, v22
	v_med3_u32 v11, v10, v11, v22
	v_med3_u32 v10, v9, v10, v22
	v_med3_u32 v9, v8, v9, v22
	v_med3_u32 v8, v7, v8, v22
	v_med3_u32 v7, v6, v7, v22
	v_med3_u32 v6, v5, v6, v22
	v_med3_u32 v5, v4, v5, v22
	v_med3_u32 v4, v3, v4, v22
	v_med3_u32 v3, v2, v3, v22
	v_med3_u32 v2, v1, v2, v22
	v_med3_u32 v1, v0, v1, v22
	v_max_u32_e32 v0, v0, v22
	v_med3_u32 v15, v14, v15, v23
	v_med3_u32 v14, v13, v14, v23
	v_med3_u32 v13, v12, v13, v23
	v_med3_u32 v12, v11, v12, v23
	v_med3_u32 v11, v10, v11, v23
	v_med3_u32 v10, v9, v10, v23
	v_med3_u32 v9, v8, v9, v23
	v_med3_u32 v8, v7, v8, v23
	v_med3_u32 v7, v6, v7, v23
	v_med3_u32 v6, v5, v6, v23
	v_med3_u32 v5, v4, v5, v23
	v_med3_u32 v4, v3, v4, v23
	v_med3_u32 v3, v2, v3, v23
	v_med3_u32 v2, v1, v2, v23
	v_med3_u32 v1, v0, v1, v23
	v_max_u32_e32 v0, v0, v23
	s_waitcnt lgkmcnt(0)
; #define LAS __attribute__((address_space(3)))
; __device__ __forceinline__ unsigned umed3(unsigned a, unsigned b, unsigned c) { unsigned r; asm("v_med3_u32 %0, %1, %2, %3" : "=v"(r) : "v"(a), "v"(b), "v"(c)); return r; }
; __global__ void __launch_bounds__(NTHR, 2) fwd_megakernel(Args a) {
;     ...
;                 if (hf == 0) {
; #pragma unroll
;                     for (int q = 0; q < 4; ++q) { const u32x4 o = *(const LAS u32x4*)(KX + row * 16 + 4 * q);
; #pragma unroll
;                         for (int c = 0; c < 4; ++c) { const unsigned uk = o[c];
; #pragma unroll
;                             for (int j = 15; j >= 1; --j) v[j] = umed3(v[j - 1], v[j], uk);
;                             v[0] = v[0] > uk ? v[0] : uk; } }
;                     u32x4 iw;
; #pragma unroll
;                     for (int q = 0; q < 4; ++q) { unsigned w = 0;
; #pragma unroll
;                         for (int j = 0; j < 4; ++j) w |= (127u - (v[4 * q + j] & 127u)) << (8 * j);
;                         iw[q] = w; }
;                     *(LAS u32x4*)(TOPI + row * 16) = iw;
;                 }
;                 else {
;                     for (int r = tile * 10 + (wave - 4); r < 32768; r += 20480) { const int e = r & 16383;
;                         if (r < 16384) row_to_fp8(a.u_tab + (size_t)e * D, U8, e, USC + e, lane); else row_to_fp8(a.v_tab + (size_t)e * D, V8, e, VSC + e, lane); }
;                 }
;             }
;             __syncthreads();
;             if (tid < 128) {
;                 const int ra = tid, rb = 128 + tid;
;                 const u32x4 ia = *(const LAS u32x4*)(TOPI + ra * 16), ib = *(const LAS u32x4*)(TOPI + rb * 16);
;                 float av[16], bv[16];
; #pragma unroll
;                 for (int i = 0; i < 16; ++i) { av[i] = SC[ra * 129 + ((ia[i >> 2] >> (8 * (i & 3))) & 255u)]; bv[i] = SC[rb * 129 + ((ib[i >> 2] >> (8 * (i & 3))) & 255u)]; }
	v_med3_u32 v15, v14, v15, v16
	v_med3_u32 v14, v13, v14, v16
	v_med3_u32 v13, v12, v13, v16
	v_med3_u32 v12, v11, v12, v16
	v_med3_u32 v11, v10, v11, v16
	v_med3_u32 v10, v9, v10, v16
	v_med3_u32 v9, v8, v9, v16
	v_med3_u32 v8, v7, v8, v16
	v_med3_u32 v7, v6, v7, v16
	v_med3_u32 v6, v5, v6, v16
	v_med3_u32 v5, v4, v5, v16
	v_med3_u32 v4, v3, v4, v16
	v_med3_u32 v3, v2, v3, v16
	v_med3_u32 v2, v1, v2, v16
	v_med3_u32 v1, v0, v1, v16
	v_max_u32_e32 v0, v0, v16
	v_med3_u32 v15, v14, v15, v17
	v_med3_u32 v14, v13, v14, v17
	v_med3_u32 v13, v12, v13, v17
	v_med3_u32 v12, v11, v12, v17
	v_med3_u32 v11, v10, v11, v17
	v_med3_u32 v10, v9, v10, v17
	v_med3_u32 v9, v8, v9, v17
	v_med3_u32 v8, v7, v8, v17
	v_med3_u32 v7, v6, v7, v17
	v_med3_u32 v6, v5, v6, v17
	v_med3_u32 v5, v4, v5, v17
	v_med3_u32 v4, v3, v4, v17
	v_med3_u32 v3, v2, v3, v17
	v_med3_u32 v2, v1, v2, v17
	v_med3_u32 v1, v0, v1, v17
	v_max_u32_e32 v0, v0, v17
	v_med3_u32 v15, v14, v15, v18
	v_med3_u32 v14, v13, v14, v18
	v_med3_u32 v13, v12, v13, v18
	v_med3_u32 v12, v11, v12, v18
	v_med3_u32 v11, v10, v11, v18
	v_med3_u32 v10, v9, v10, v18
	v_med3_u32 v9, v8, v9, v18
	v_med3_u32 v8, v7, v8, v18
	v_med3_u32 v7, v6, v7, v18
	v_med3_u32 v6, v5, v6, v18
	v_med3_u32 v5, v4, v5, v18
	v_med3_u32 v4, v3, v4, v18
	v_med3_u32 v3, v2, v3, v18
	v_med3_u32 v2, v1, v2, v18
	v_med3_u32 v1, v0, v1, v18
	v_max_u32_e32 v0, v0, v18
	v_med3_u32 v15, v14, v15, v19
	v_med3_u32 v14, v13, v14, v19
	v_med3_u32 v13, v12, v13, v19
	v_med3_u32 v12, v11, v12, v19
	v_med3_u32 v11, v10, v11, v19
	v_med3_u32 v10, v9, v10, v19
	v_med3_u32 v9, v8, v9, v19
	v_med3_u32 v8, v7, v8, v19
	v_med3_u32 v7, v6, v7, v19
	v_med3_u32 v6, v5, v6, v19
	v_med3_u32 v5, v4, v5, v19
	v_med3_u32 v4, v3, v4, v19
	v_med3_u32 v3, v2, v3, v19
	v_med3_u32 v2, v1, v2, v19
	v_med3_u32 v1, v0, v1, v19
	v_max_u32_e32 v0, v0, v19
	v_lshlrev_b32_e32 v1, 8, v1
	v_lshlrev_b32_e32 v2, 16, v2
	v_and_b32_e32 v0, 0x7f, v0
	v_and_b32_e32 v1, 0x7f00, v1
	v_and_b32_e32 v2, 0x7f0000, v2
	v_or3_b32 v0, v0, v1, v2
	v_lshlrev_b32_e32 v1, 24, v3
	v_and_b32_e32 v1, 0x7f000000, v1
	v_lshlrev_b32_e32 v2, 8, v5
	v_lshlrev_b32_e32 v3, 16, v6
	v_bitop3_b32 v0, v0, s71, v1 bitop3:0x36
	v_and_b32_e32 v1, 0x7f, v4
	v_and_b32_e32 v2, 0x7f00, v2
	v_and_b32_e32 v3, 0x7f0000, v3
	v_or3_b32 v1, v1, v2, v3
	v_lshlrev_b32_e32 v2, 24, v7
	v_and_b32_e32 v2, 0x7f000000, v2
	v_lshlrev_b32_e32 v3, 8, v9
	v_lshlrev_b32_e32 v4, 16, v10
	v_bitop3_b32 v1, v1, s71, v2 bitop3:0x36
	v_and_b32_e32 v2, 0x7f, v8
	v_and_b32_e32 v3, 0x7f00, v3
	v_and_b32_e32 v4, 0x7f0000, v4
	v_or3_b32 v2, v2, v3, v4
	v_lshlrev_b32_e32 v3, 24, v11
	v_and_b32_e32 v3, 0x7f000000, v3
	v_lshlrev_b32_e32 v4, 8, v13
	v_lshlrev_b32_e32 v5, 16, v14
	v_bitop3_b32 v2, v2, s71, v3 bitop3:0x36
	v_and_b32_e32 v3, 0x7f, v12
	v_and_b32_e32 v4, 0x7f00, v4
	v_and_b32_e32 v5, 0x7f0000, v5
	v_or3_b32 v3, v3, v4, v5
	v_lshlrev_b32_e32 v4, 24, v15
	v_and_b32_e32 v4, 0x7f000000, v4
	v_bitop3_b32 v3, v3, s71, v4 bitop3:0x36
	ds_write_b128 v80, v[0:3]
.LBB0_804:
	s_or_b64 exec, exec, s[0:1]
	s_waitcnt lgkmcnt(0)
	s_barrier
	s_and_saveexec_b64 s[0:1], s[12:13]
	s_xor_b64 s[14:15], exec, s[0:1]
	s_cbranch_execz .LBB0_807
.LBB0_807:
	s_andn2_saveexec_b64 s[0:1], s[14:15]
	s_cbranch_execz .LBB0_795
	ds_read_b128 v[12:15], v80
	ds_read_b128 v[16:19], v81
	s_cmp_lg_u32 s74, 0
	s_waitcnt lgkmcnt(1)
	v_bfe_u32 v9, v13, 8, 8
	v_lshl_add_u32 v10, v9, 2, v82
	s_waitcnt lgkmcnt(0)
	v_bfe_u32 v9, v17, 8, 8
	v_lshrrev_b32_e32 v6, 24, v12
	v_lshl_add_u32 v11, v9, 2, v83
	v_bfe_u32 v9, v13, 16, 8
	v_and_b32_e32 v0, 0xff, v12
	v_and_b32_e32 v1, 0xff, v16
	v_bfe_u32 v2, v12, 8, 8
	v_bfe_u32 v3, v16, 8, 8
	v_bfe_u32 v4, v12, 16, 8
	v_bfe_u32 v5, v16, 16, 8
	v_lshl_add_u32 v7, v6, 2, v82
	v_lshrrev_b32_e32 v6, 24, v16
	v_lshl_add_u32 v16, v9, 2, v82
	v_bfe_u32 v9, v17, 16, 8
	v_lshl_add_u32 v0, v0, 2, v82
	v_lshl_add_u32 v1, v1, 2, v83
	v_lshl_add_u32 v2, v2, 2, v82
	v_lshl_add_u32 v3, v3, 2, v83
	v_lshl_add_u32 v4, v4, 2, v82
	v_lshl_add_u32 v5, v5, 2, v83
	v_lshl_add_u32 v8, v6, 2, v83
	v_lshl_add_u32 v20, v9, 2, v83
	v_lshrrev_b32_e32 v9, 24, v13
	ds_read_b32 v12, v0
	ds_read_b32 v1, v1
	ds_read_b32 v2, v2
	ds_read_b32 v0, v3
	ds_read_b32 v6, v4
	ds_read_b32 v5, v5
	ds_read_b32 v7, v7
	ds_read_b32 v4, v8
	v_and_b32_e32 v3, 0xff, v13
	v_and_b32_e32 v8, 0xff, v17
	v_lshl_add_u32 v13, v9, 2, v82
	v_lshrrev_b32_e32 v9, 24, v17
	v_lshl_add_u32 v3, v3, 2, v82
	v_lshl_add_u32 v8, v8, 2, v83
	v_lshl_add_u32 v17, v9, 2, v83
	ds_read_b32 v3, v3
	ds_read_b32 v9, v8
	ds_read_b32 v27, v10
	ds_read_b32 v8, v11
	ds_read_b32 v26, v16
	ds_read_b32 v11, v20
	ds_read_b32 v25, v13
	ds_read_b32 v10, v17
	v_and_b32_e32 v13, 0xff, v14
	v_bfe_u32 v17, v14, 8, 8
	v_bfe_u32 v21, v14, 16, 8
	v_bfe_u32 v22, v18, 16, 8
	v_lshl_add_u32 v13, v13, 2, v82
	v_and_b32_e32 v16, 0xff, v18
	v_lshl_add_u32 v17, v17, 2, v82
	v_bfe_u32 v20, v18, 8, 8
	v_lshl_add_u32 v21, v21, 2, v82
	v_lshl_add_u32 v30, v22, 2, v83
	v_lshrrev_b32_e32 v14, 24, v14
	v_lshrrev_b32_e32 v18, 24, v18
	v_lshl_add_u32 v16, v16, 2, v83
	v_lshl_add_u32 v20, v20, 2, v83
	v_lshl_add_u32 v14, v14, 2, v82
	v_lshl_add_u32 v18, v18, 2, v83
	ds_read_b32 v24, v13
	ds_read_b32 v29, v16
	ds_read_b32 v23, v17
	ds_read_b32 v28, v20
	ds_read_b32 v22, v21
	ds_read_b32 v31, v30
	ds_read_b32 v21, v14
	ds_read_b32 v30, v18
	v_bfe_u32 v17, v19, 8, 8
	v_and_b32_e32 v13, 0xff, v15
	v_and_b32_e32 v14, 0xff, v19
	v_bfe_u32 v16, v15, 8, 8
	v_lshl_add_u32 v18, v17, 2, v83
	v_bfe_u32 v17, v15, 16, 8
	v_lshrrev_b32_e32 v15, 24, v15
	v_lshl_add_u32 v13, v13, 2, v82
	v_lshl_add_u32 v14, v14, 2, v83
	v_lshl_add_u32 v16, v16, 2, v82
	v_lshl_add_u32 v32, v17, 2, v82
	v_bfe_u32 v17, v19, 16, 8
	v_lshl_add_u32 v34, v15, 2, v82
	v_lshrrev_b32_e32 v15, 24, v19
	v_lshl_add_u32 v33, v17, 2, v83
	v_lshl_add_u32 v35, v15, 2, v83
	ds_read_b32 v20, v13
	ds_read_b32 v17, v14
	ds_read_b32 v19, v16
	ds_read_b32 v16, v18
	ds_read_b32 v18, v32
	ds_read_b32 v15, v33
	ds_read_b32 v13, v34
	ds_read_b32 v14, v35
	s_waitcnt lgkmcnt(1)
; __device__ __forceinline__ unsigned umed3(unsigned a, unsigned b, unsigned c) { unsigned r; asm("v_med3_u32 %0, %1, %2, %3" : "=v"(r) : "v"(a), "v"(b), "v"(c)); return r; }
; __device__ __forceinline__ unsigned orderable(float s) { unsigned u = __builtin_bit_cast(unsigned, s); return (u >> 31) ? ~u : (u | 0x80000000u); }
; __global__ void __launch_bounds__(NTHR, 2) fwd_megakernel(Args a) {
;     ...
;                 for (int i = 0; i < 16; ++i)
; #pragma unroll
;                     for (int jj = 0; jj < 16; ++jj)
;                         if ((i + 1) * (jj + 1) <= 16) {
;                             const unsigned uk = (orderable(av[i] + bv[jj]) & ~255u) | (unsigned)(255 - (i * 16 + jj));
; #pragma unroll
;                             for (int j = 15; j >= 1; --j) v[j] = umed3(v[j - 1], v[j], uk);
;                             v[0] = v[0] > uk ? v[0] : uk;
;                         }
	v_pk_add_f32 v[32:33], v[12:13], v[0:1] op_sel_hi:[0,1]
	v_not_b32_e32 v34, v33
	v_or_b32_e32 v35, 0x80000000, v33
	v_cmp_gt_i32_e32 vcc, 0, v33
	v_or_b32_e32 v36, 0x80000000, v32
	v_pk_add_f32 v[28:29], v[12:13], v[28:29] op_sel_hi:[0,1]
	v_cndmask_b32_e32 v33, v35, v34, vcc
	v_not_b32_e32 v35, v32
	v_cmp_gt_i32_e32 vcc, 0, v32
	v_or_b32_e32 v33, 0xff, v33
	v_med3_u32 v34, v65, v65, v33
	v_pk_add_f32 v[16:17], v[12:13], v[16:17] op_sel_hi:[0,1]
	v_cndmask_b32_e32 v32, v36, v35, vcc
	v_and_b32_e32 v32, 0xffffff00, v32
	v_or_b32_e32 v32, 0xfe, v32
	v_med3_u32 v35, v34, v34, v32
	v_med3_u32 v34, v33, v34, v32
	v_max_u32_e32 v36, v33, v32
	v_pk_add_f32 v[32:33], v[12:13], v[4:5] op_sel_hi:[0,1]
	v_not_b32_e32 v37, v33
	v_or_b32_e32 v38, 0x80000000, v33
	v_cmp_gt_i32_e32 vcc, 0, v33
	s_waitcnt lgkmcnt(0)
	v_pk_add_f32 v[14:15], v[12:13], v[14:15] op_sel_hi:[0,1]
	v_cndmask_b32_e32 v33, v38, v37, vcc
	v_and_b32_e32 v33, 0xffffff00, v33
	v_or_b32_e32 v33, 0xfd, v33
	v_med3_u32 v37, v35, v35, v33
	v_med3_u32 v35, v34, v35, v33
	v_med3_u32 v34, v36, v34, v33
	v_max_u32_e32 v33, v36, v33
	v_not_b32_e32 v36, v32
	v_or_b32_e32 v38, 0x80000000, v32
	v_cmp_gt_i32_e32 vcc, 0, v32
	s_nop 1
	v_cndmask_b32_e32 v32, v38, v36, vcc
	v_and_b32_e32 v32, 0xffffff00, v32
	v_or_b32_e32 v32, 0xfc, v32
	v_med3_u32 v36, v37, v37, v32
	v_med3_u32 v37, v35, v37, v32
	v_med3_u32 v35, v34, v35, v32
	v_med3_u32 v34, v33, v34, v32
	v_max_u32_e32 v38, v33, v32
	v_pk_add_f32 v[32:33], v[12:13], v[8:9] op_sel_hi:[0,1]
	v_not_b32_e32 v39, v33
	v_or_b32_e32 v40, 0x80000000, v33
	v_cmp_gt_i32_e32 vcc, 0, v33
	s_nop 1
	v_cndmask_b32_e32 v33, v40, v39, vcc
	v_and_b32_e32 v33, 0xffffff00, v33
	v_or_b32_e32 v33, 0xfb, v33
	v_med3_u32 v39, v36, v36, v33
	v_med3_u32 v36, v37, v36, v33
	v_med3_u32 v37, v35, v37, v33
	v_med3_u32 v35, v34, v35, v33
	v_med3_u32 v34, v38, v34, v33
	v_max_u32_e32 v33, v38, v33
	v_not_b32_e32 v38, v32
	v_or_b32_e32 v40, 0x80000000, v32
	v_cmp_gt_i32_e32 vcc, 0, v32
	s_nop 1
	v_cndmask_b32_e32 v32, v40, v38, vcc
	v_and_b32_e32 v32, 0xffffff00, v32
	v_or_b32_e32 v32, 0xfa, v32
	v_med3_u32 v38, v39, v39, v32
	v_med3_u32 v39, v36, v39, v32
	v_med3_u32 v36, v37, v36, v32
	v_med3_u32 v37, v35, v37, v32
	v_med3_u32 v35, v34, v35, v32
	v_med3_u32 v34, v33, v34, v32
	v_max_u32_e32 v40, v33, v32
	v_pk_add_f32 v[32:33], v[12:13], v[10:11] op_sel_hi:[0,1]
	v_not_b32_e32 v41, v33
	v_or_b32_e32 v42, 0x80000000, v33
	v_cmp_gt_i32_e32 vcc, 0, v33
	v_pk_add_f32 v[10:11], v[2:3], v[10:11] op_sel_hi:[0,1]
	s_nop 0
	v_cndmask_b32_e32 v33, v42, v41, vcc
	v_and_b32_e32 v33, 0xffffff00, v33
	v_or_b32_e32 v33, 0xf9, v33
	v_med3_u32 v41, v38, v38, v33
	v_med3_u32 v38, v39, v38, v33
	v_med3_u32 v39, v36, v39, v33
	v_med3_u32 v36, v37, v36, v33
	v_med3_u32 v37, v35, v37, v33
	v_med3_u32 v35, v34, v35, v33
	v_med3_u32 v34, v40, v34, v33
	v_max_u32_e32 v33, v40, v33
	v_not_b32_e32 v40, v32
	v_or_b32_e32 v42, 0x80000000, v32
	v_cmp_gt_i32_e32 vcc, 0, v32
	s_nop 1
	v_cndmask_b32_e32 v32, v42, v40, vcc
	v_and_b32_e32 v32, 0xffffff00, v32
	v_or_b32_e32 v32, 0xf8, v32
	v_med3_u32 v40, v41, v41, v32
	v_med3_u32 v41, v38, v41, v32
	v_med3_u32 v38, v39, v38, v32
	v_med3_u32 v39, v36, v39, v32
	v_med3_u32 v36, v37, v36, v32
	v_med3_u32 v37, v35, v37, v32
	v_med3_u32 v35, v34, v35, v32
	v_med3_u32 v34, v33, v34, v32
	v_max_u32_e32 v32, v33, v32
	v_not_b32_e32 v33, v29
	v_or_b32_e32 v42, 0x80000000, v29
	v_cmp_gt_i32_e32 vcc, 0, v29
	s_nop 1
	v_cndmask_b32_e32 v29, v42, v33, vcc
	v_and_b32_e32 v29, 0xffffff00, v29
	v_or_b32_e32 v29, 0xf7, v29
	v_med3_u32 v33, v40, v40, v29
	v_med3_u32 v40, v41, v40, v29
	v_med3_u32 v41, v38, v41, v29
	v_med3_u32 v38, v39, v38, v29
	v_med3_u32 v39, v36, v39, v29
	v_med3_u32 v36, v37, v36, v29
	v_med3_u32 v37, v35, v37, v29
	v_med3_u32 v35, v34, v35, v29
	v_med3_u32 v34, v32, v34, v29
	v_max_u32_e32 v29, v32, v29
	v_not_b32_e32 v32, v28
	v_or_b32_e32 v42, 0x80000000, v28
	v_cmp_gt_i32_e32 vcc, 0, v28
	s_nop 1
	v_cndmask_b32_e32 v28, v42, v32, vcc
	v_and_b32_e32 v28, 0xffffff00, v28
	v_or_b32_e32 v28, 0xf6, v28
	v_med3_u32 v32, v33, v33, v28
	v_med3_u32 v33, v40, v33, v28
	v_med3_u32 v40, v41, v40, v28
	v_med3_u32 v41, v38, v41, v28
	v_med3_u32 v38, v39, v38, v28
	v_med3_u32 v39, v36, v39, v28
	v_med3_u32 v36, v37, v36, v28
	v_med3_u32 v37, v35, v37, v28
	v_med3_u32 v35, v34, v35, v28
	v_med3_u32 v34, v29, v34, v28
	v_max_u32_e32 v42, v29, v28
	v_pk_add_f32 v[28:29], v[12:13], v[30:31] op_sel_hi:[0,1]
	v_not_b32_e32 v30, v29
	v_or_b32_e32 v31, 0x80000000, v29
	v_cmp_gt_i32_e32 vcc, 0, v29
	v_not_b32_e32 v12, v15
	s_nop 0
	v_cndmask_b32_e32 v29, v31, v30, vcc
	v_and_b32_e32 v29, 0xffffff00, v29
	v_or_b32_e32 v29, 0xf5, v29
	v_med3_u32 v30, v32, v32, v29
	v_med3_u32 v31, v33, v32, v29
	v_med3_u32 v32, v40, v33, v29
	v_med3_u32 v33, v41, v40, v29
	v_med3_u32 v40, v38, v41, v29
	v_med3_u32 v38, v39, v38, v29
	v_med3_u32 v39, v36, v39, v29
	v_med3_u32 v36, v37, v36, v29
	v_med3_u32 v37, v35, v37, v29
	v_med3_u32 v35, v34, v35, v29
	v_med3_u32 v34, v42, v34, v29
	v_max_u32_e32 v29, v42, v29
	v_not_b32_e32 v41, v28
	v_or_b32_e32 v42, 0x80000000, v28
	v_cmp_gt_i32_e32 vcc, 0, v28
	s_nop 1
	v_cndmask_b32_e32 v28, v42, v41, vcc
	v_and_b32_e32 v28, 0xffffff00, v28
	v_or_b32_e32 v28, 0xf4, v28
	v_med3_u32 v41, v30, v30, v28
	v_med3_u32 v30, v31, v30, v28
	v_med3_u32 v31, v32, v31, v28
	v_med3_u32 v32, v33, v32, v28
	v_med3_u32 v33, v40, v33, v28
	v_med3_u32 v40, v38, v40, v28
	v_med3_u32 v38, v39, v38, v28
	v_med3_u32 v39, v36, v39, v28
	v_med3_u32 v36, v37, v36, v28
	v_med3_u32 v37, v35, v37, v28
	v_med3_u32 v35, v34, v35, v28
	v_med3_u32 v34, v29, v34, v28
; __device__ __forceinline__ unsigned umed3(unsigned a, unsigned b, unsigned c) { unsigned r; asm("v_med3_u32 %0, %1, %2, %3" : "=v"(r) : "v"(a), "v"(b), "v"(c)); return r; }
; __device__ __forceinline__ unsigned orderable(float s) { unsigned u = __builtin_bit_cast(unsigned, s); return (u >> 31) ? ~u : (u | 0x80000000u); }
; __global__ void __launch_bounds__(NTHR, 2) fwd_megakernel(Args a) {
;     ...
;                 for (int i = 0; i < 16; ++i)
; #pragma unroll
;                     for (int jj = 0; jj < 16; ++jj)
;                         if ((i + 1) * (jj + 1) <= 16) {
;                             const unsigned uk = (orderable(av[i] + bv[jj]) & ~255u) | (unsigned)(255 - (i * 16 + jj));
; #pragma unroll
;                             for (int j = 15; j >= 1; --j) v[j] = umed3(v[j - 1], v[j], uk);
;                             v[0] = v[0] > uk ? v[0] : uk;
;                         }
	v_max_u32_e32 v28, v29, v28
	v_not_b32_e32 v29, v17
	v_or_b32_e32 v42, 0x80000000, v17
	v_cmp_gt_i32_e32 vcc, 0, v17
	s_nop 1
	v_cndmask_b32_e32 v17, v42, v29, vcc
	v_and_b32_e32 v17, 0xffffff00, v17
	v_or_b32_e32 v17, 0xf3, v17
	v_med3_u32 v29, v41, v41, v17
	v_med3_u32 v41, v30, v41, v17
	v_med3_u32 v30, v31, v30, v17
	v_med3_u32 v31, v32, v31, v17
	v_med3_u32 v32, v33, v32, v17
	v_med3_u32 v33, v40, v33, v17
	v_med3_u32 v40, v38, v40, v17
	v_med3_u32 v38, v39, v38, v17
	v_med3_u32 v39, v36, v39, v17
	v_med3_u32 v36, v37, v36, v17
	v_med3_u32 v37, v35, v37, v17
	v_med3_u32 v35, v34, v35, v17
	v_med3_u32 v34, v28, v34, v17
	v_max_u32_e32 v17, v28, v17
	v_not_b32_e32 v28, v16
	v_or_b32_e32 v42, 0x80000000, v16
	v_cmp_gt_i32_e32 vcc, 0, v16
	s_nop 1
	v_cndmask_b32_e32 v16, v42, v28, vcc
	v_and_b32_e32 v16, 0xffffff00, v16
	v_or_b32_e32 v16, 0xf2, v16
	v_med3_u32 v28, v29, v29, v16
	v_med3_u32 v29, v41, v29, v16
	v_med3_u32 v41, v30, v41, v16
	v_med3_u32 v30, v31, v30, v16
	v_med3_u32 v31, v32, v31, v16
	v_med3_u32 v32, v33, v32, v16
	v_med3_u32 v33, v40, v33, v16
	v_med3_u32 v40, v38, v40, v16
	v_med3_u32 v38, v39, v38, v16
	v_med3_u32 v39, v36, v39, v16
	v_med3_u32 v36, v37, v36, v16
	v_med3_u32 v37, v35, v37, v16
	v_med3_u32 v35, v34, v35, v16
	v_med3_u32 v34, v17, v34, v16
	v_max_u32_e32 v16, v17, v16
	v_or_b32_e32 v17, 0x80000000, v15
	v_cmp_gt_i32_e32 vcc, 0, v15
	s_nop 1
	v_cndmask_b32_e32 v12, v17, v12, vcc
	v_and_b32_e32 v12, 0xffffff00, v12
	v_or_b32_e32 v12, 0xf1, v12
	v_med3_u32 v15, v28, v28, v12
	v_med3_u32 v17, v29, v28, v12
	v_med3_u32 v28, v41, v29, v12
	v_med3_u32 v29, v30, v41, v12
	v_med3_u32 v30, v31, v30, v12
	v_med3_u32 v31, v32, v31, v12
	v_med3_u32 v32, v33, v32, v12
	v_med3_u32 v33, v40, v33, v12
	v_med3_u32 v40, v38, v40, v12
	v_med3_u32 v38, v39, v38, v12
	v_med3_u32 v39, v36, v39, v12
	v_med3_u32 v36, v37, v36, v12
	v_med3_u32 v37, v35, v37, v12
	v_med3_u32 v35, v34, v35, v12
	v_med3_u32 v34, v16, v34, v12
	v_max_u32_e32 v12, v16, v12
	v_not_b32_e32 v16, v14
	v_or_b32_e32 v41, 0x80000000, v14
	v_cmp_gt_i32_e32 vcc, 0, v14
	s_nop 1
	v_cndmask_b32_e32 v14, v41, v16, vcc
	v_and_b32_e32 v14, 0xffffff00, v14
	v_or_b32_e32 v14, 0xf0, v14
	v_med3_u32 v16, v17, v15, v14
	v_med3_u32 v17, v28, v17, v14
	v_med3_u32 v28, v29, v28, v14
	v_med3_u32 v29, v30, v29, v14
	v_med3_u32 v30, v31, v30, v14
	v_med3_u32 v31, v32, v31, v14
	v_med3_u32 v32, v33, v32, v14
	v_med3_u32 v33, v40, v33, v14
	v_med3_u32 v40, v38, v40, v14
	v_med3_u32 v38, v39, v38, v14
	v_med3_u32 v39, v36, v39, v14
	v_med3_u32 v36, v37, v36, v14
	v_med3_u32 v37, v35, v37, v14
	v_med3_u32 v35, v34, v35, v14
	v_med3_u32 v34, v12, v34, v14
	v_max_u32_e32 v12, v12, v14
	v_pk_add_f32 v[14:15], v[2:3], v[0:1] op_sel_hi:[0,1]
	v_not_b32_e32 v41, v15
	v_or_b32_e32 v42, 0x80000000, v15
	v_cmp_gt_i32_e32 vcc, 0, v15
	s_nop 1
	v_cndmask_b32_e32 v15, v42, v41, vcc
	v_and_b32_e32 v15, 0xffffff00, v15
	v_or_b32_e32 v15, 0xef, v15
	v_med3_u32 v16, v17, v16, v15
	v_med3_u32 v17, v28, v17, v15
	v_med3_u32 v28, v29, v28, v15
	v_med3_u32 v29, v30, v29, v15
	v_med3_u32 v30, v31, v30, v15
	v_med3_u32 v31, v32, v31, v15
	v_med3_u32 v32, v33, v32, v15
	v_med3_u32 v33, v40, v33, v15
	v_med3_u32 v40, v38, v40, v15
	v_med3_u32 v38, v39, v38, v15
	v_med3_u32 v39, v36, v39, v15
	v_med3_u32 v36, v37, v36, v15
	v_med3_u32 v37, v35, v37, v15
	v_med3_u32 v35, v34, v35, v15
	v_med3_u32 v34, v12, v34, v15
	v_max_u32_e32 v12, v12, v15
	v_not_b32_e32 v15, v14
	v_or_b32_e32 v41, 0x80000000, v14
	v_cmp_gt_i32_e32 vcc, 0, v14
	s_nop 1
	v_cndmask_b32_e32 v14, v41, v15, vcc
	v_and_b32_e32 v14, 0xffffff00, v14
	v_or_b32_e32 v14, 0xee, v14
	v_med3_u32 v16, v17, v16, v14
	v_med3_u32 v17, v28, v17, v14
	v_med3_u32 v28, v29, v28, v14
	v_med3_u32 v29, v30, v29, v14
	v_med3_u32 v30, v31, v30, v14
	v_med3_u32 v31, v32, v31, v14
	v_med3_u32 v32, v33, v32, v14
	v_med3_u32 v33, v40, v33, v14
	v_med3_u32 v40, v38, v40, v14
	v_med3_u32 v38, v39, v38, v14
	v_med3_u32 v39, v36, v39, v14
	v_med3_u32 v36, v37, v36, v14
	v_med3_u32 v37, v35, v37, v14
	v_med3_u32 v35, v34, v35, v14
	v_med3_u32 v34, v12, v34, v14
	v_max_u32_e32 v12, v12, v14
	v_pk_add_f32 v[14:15], v[2:3], v[4:5] op_sel_hi:[0,1]
	v_not_b32_e32 v41, v15
	v_or_b32_e32 v42, 0x80000000, v15
	v_cmp_gt_i32_e32 vcc, 0, v15
	s_nop 1
	v_cndmask_b32_e32 v15, v42, v41, vcc
	v_and_b32_e32 v15, 0xffffff00, v15
	v_or_b32_e32 v15, 0xed, v15
	v_med3_u32 v16, v17, v16, v15
	v_med3_u32 v17, v28, v17, v15
	v_med3_u32 v28, v29, v28, v15
	v_med3_u32 v29, v30, v29, v15
	v_med3_u32 v30, v31, v30, v15
	v_med3_u32 v31, v32, v31, v15
	v_med3_u32 v32, v33, v32, v15
	v_med3_u32 v33, v40, v33, v15
	v_med3_u32 v40, v38, v40, v15
	v_med3_u32 v38, v39, v38, v15
	v_med3_u32 v39, v36, v39, v15
	v_med3_u32 v36, v37, v36, v15
	v_med3_u32 v37, v35, v37, v15
	v_med3_u32 v35, v34, v35, v15
	v_med3_u32 v34, v12, v34, v15
	v_max_u32_e32 v12, v12, v15
	v_not_b32_e32 v15, v14
	v_or_b32_e32 v41, 0x80000000, v14
	v_cmp_gt_i32_e32 vcc, 0, v14
	s_nop 1
	v_cndmask_b32_e32 v14, v41, v15, vcc
	v_and_b32_e32 v14, 0xffffff00, v14
	v_or_b32_e32 v14, 0xec, v14
	v_med3_u32 v16, v17, v16, v14
	v_med3_u32 v17, v28, v17, v14
	v_med3_u32 v28, v29, v28, v14
	v_med3_u32 v29, v30, v29, v14
	v_med3_u32 v30, v31, v30, v14
	v_med3_u32 v31, v32, v31, v14
	v_med3_u32 v32, v33, v32, v14
	v_med3_u32 v33, v40, v33, v14
	v_med3_u32 v40, v38, v40, v14
	v_med3_u32 v38, v39, v38, v14
	v_med3_u32 v39, v36, v39, v14
	v_med3_u32 v36, v37, v36, v14
	v_med3_u32 v37, v35, v37, v14
	v_med3_u32 v35, v34, v35, v14
	v_med3_u32 v34, v12, v34, v14
	v_max_u32_e32 v12, v12, v14
	v_pk_add_f32 v[14:15], v[2:3], v[8:9] op_sel_hi:[0,1]
; __device__ __forceinline__ unsigned umed3(unsigned a, unsigned b, unsigned c) { unsigned r; asm("v_med3_u32 %0, %1, %2, %3" : "=v"(r) : "v"(a), "v"(b), "v"(c)); return r; }
; __device__ __forceinline__ unsigned orderable(float s) { unsigned u = __builtin_bit_cast(unsigned, s); return (u >> 31) ? ~u : (u | 0x80000000u); }
; __global__ void __launch_bounds__(NTHR, 2) fwd_megakernel(Args a) {
;     ...
;                 for (int i = 0; i < 16; ++i)
; #pragma unroll
;                     for (int jj = 0; jj < 16; ++jj)
;                         if ((i + 1) * (jj + 1) <= 16) {
;                             const unsigned uk = (orderable(av[i] + bv[jj]) & ~255u) | (unsigned)(255 - (i * 16 + jj));
; #pragma unroll
;                             for (int j = 15; j >= 1; --j) v[j] = umed3(v[j - 1], v[j], uk);
;                             v[0] = v[0] > uk ? v[0] : uk;
;                         }
	v_not_b32_e32 v8, v15
	v_or_b32_e32 v41, 0x80000000, v15
	v_cmp_gt_i32_e32 vcc, 0, v15
	v_not_b32_e32 v2, v11
	s_nop 0
	v_cndmask_b32_e32 v8, v41, v8, vcc
	v_and_b32_e32 v8, 0xffffff00, v8
	v_or_b32_e32 v8, 0xeb, v8
	v_med3_u32 v15, v17, v16, v8
	v_med3_u32 v16, v28, v17, v8
	v_med3_u32 v17, v29, v28, v8
	v_med3_u32 v28, v30, v29, v8
	v_med3_u32 v29, v31, v30, v8
	v_med3_u32 v30, v32, v31, v8
	v_med3_u32 v31, v33, v32, v8
	v_med3_u32 v32, v40, v33, v8
	v_med3_u32 v33, v38, v40, v8
	v_med3_u32 v38, v39, v38, v8
	v_med3_u32 v39, v36, v39, v8
	v_med3_u32 v36, v37, v36, v8
	v_med3_u32 v37, v35, v37, v8
	v_med3_u32 v35, v34, v35, v8
	v_med3_u32 v34, v12, v34, v8
	v_max_u32_e32 v8, v12, v8
	v_not_b32_e32 v12, v14
	v_or_b32_e32 v40, 0x80000000, v14
	v_cmp_gt_i32_e32 vcc, 0, v14
	s_nop 1
	v_cndmask_b32_e32 v12, v40, v12, vcc
	v_and_b32_e32 v12, 0xffffff00, v12
	v_or_b32_e32 v12, 0xea, v12
	v_med3_u32 v14, v16, v15, v12
	v_med3_u32 v15, v17, v16, v12
	v_med3_u32 v16, v28, v17, v12
	v_med3_u32 v17, v29, v28, v12
	v_med3_u32 v28, v30, v29, v12
	v_med3_u32 v29, v31, v30, v12
	v_med3_u32 v30, v32, v31, v12
	v_med3_u32 v31, v33, v32, v12
	v_med3_u32 v32, v38, v33, v12
	v_med3_u32 v33, v39, v38, v12
	v_med3_u32 v38, v36, v39, v12
	v_med3_u32 v36, v37, v36, v12
	v_med3_u32 v37, v35, v37, v12
	v_med3_u32 v35, v34, v35, v12
	v_med3_u32 v34, v8, v34, v12
	v_max_u32_e32 v8, v8, v12
	v_or_b32_e32 v12, 0x80000000, v11
	v_cmp_gt_i32_e32 vcc, 0, v11
	s_nop 1
	v_cndmask_b32_e32 v2, v12, v2, vcc
	v_and_b32_e32 v2, 0xffffff00, v2
	v_or_b32_e32 v2, 0xe9, v2
	v_med3_u32 v11, v15, v14, v2
	v_med3_u32 v12, v16, v15, v2
	v_med3_u32 v14, v17, v16, v2
	v_med3_u32 v15, v28, v17, v2
	v_med3_u32 v16, v29, v28, v2
	v_med3_u32 v17, v30, v29, v2
	v_med3_u32 v28, v31, v30, v2
	v_med3_u32 v29, v32, v31, v2
	v_med3_u32 v30, v33, v32, v2
	v_med3_u32 v31, v38, v33, v2
	v_med3_u32 v32, v36, v38, v2
	v_med3_u32 v33, v37, v36, v2
	v_med3_u32 v36, v35, v37, v2
	v_med3_u32 v35, v34, v35, v2
	v_med3_u32 v34, v8, v34, v2
	v_max_u32_e32 v2, v8, v2
	v_not_b32_e32 v8, v10
	v_or_b32_e32 v37, 0x80000000, v10
	v_cmp_gt_i32_e32 vcc, 0, v10
	v_mov_b32_e32 v10, v6
	s_nop 0
	v_cndmask_b32_e32 v8, v37, v8, vcc
	v_and_b32_e32 v8, 0xffffff00, v8
	v_or_b32_e32 v8, 0xe8, v8
	v_med3_u32 v37, v12, v11, v8
	v_mov_b32_e32 v11, v6
	v_med3_u32 v12, v14, v12, v8
	v_med3_u32 v38, v15, v14, v8
	v_med3_u32 v39, v16, v15, v8
	v_pk_add_f32 v[14:15], v[10:11], v[0:1]
	v_med3_u32 v16, v17, v16, v8
	v_med3_u32 v17, v28, v17, v8
	v_med3_u32 v28, v29, v28, v8
	v_med3_u32 v29, v30, v29, v8
	v_med3_u32 v30, v31, v30, v8
	v_med3_u32 v31, v32, v31, v8
	v_med3_u32 v32, v33, v32, v8
	v_med3_u32 v33, v36, v33, v8
	v_med3_u32 v36, v35, v36, v8
	v_med3_u32 v35, v34, v35, v8
	v_med3_u32 v34, v2, v34, v8
	v_max_u32_e32 v2, v2, v8
	v_not_b32_e32 v8, v15
	v_or_b32_e32 v40, 0x80000000, v15
	v_cmp_gt_i32_e32 vcc, 0, v15
	v_pk_add_f32 v[10:11], v[10:11], v[4:5]
	s_nop 0
	v_cndmask_b32_e32 v8, v40, v8, vcc
	v_and_b32_e32 v8, 0xffffff00, v8
	v_or_b32_e32 v8, 0xdf, v8
	v_med3_u32 v15, v12, v37, v8
	v_med3_u32 v12, v38, v12, v8
	v_med3_u32 v37, v39, v38, v8
	v_med3_u32 v38, v16, v39, v8
	v_med3_u32 v16, v17, v16, v8
	v_med3_u32 v17, v28, v17, v8
	v_med3_u32 v28, v29, v28, v8
	v_med3_u32 v29, v30, v29, v8
	v_med3_u32 v30, v31, v30, v8
	v_med3_u32 v31, v32, v31, v8
	v_med3_u32 v32, v33, v32, v8
	v_med3_u32 v33, v36, v33, v8
	v_med3_u32 v36, v35, v36, v8
	v_med3_u32 v35, v34, v35, v8
	v_med3_u32 v34, v2, v34, v8
	v_max_u32_e32 v2, v2, v8
	v_not_b32_e32 v8, v14
	v_or_b32_e32 v39, 0x80000000, v14
	v_cmp_gt_i32_e32 vcc, 0, v14
	s_nop 1
	v_cndmask_b32_e32 v8, v39, v8, vcc
	v_and_b32_e32 v8, 0xffffff00, v8
	v_or_b32_e32 v8, 0xde, v8
	v_med3_u32 v14, v12, v15, v8
	v_med3_u32 v12, v37, v12, v8
	v_med3_u32 v15, v38, v37, v8
	v_med3_u32 v37, v16, v38, v8
	v_med3_u32 v16, v17, v16, v8
	v_med3_u32 v17, v28, v17, v8
	v_med3_u32 v28, v29, v28, v8
	v_med3_u32 v29, v30, v29, v8
	v_med3_u32 v30, v31, v30, v8
	v_med3_u32 v31, v32, v31, v8
	v_med3_u32 v32, v33, v32, v8
	v_med3_u32 v33, v36, v33, v8
	v_med3_u32 v36, v35, v36, v8
	v_med3_u32 v35, v34, v35, v8
	v_med3_u32 v34, v2, v34, v8
	v_max_u32_e32 v2, v2, v8
	v_not_b32_e32 v8, v11
	v_or_b32_e32 v38, 0x80000000, v11
	v_cmp_gt_i32_e32 vcc, 0, v11
	s_nop 1
	v_cndmask_b32_e32 v8, v38, v8, vcc
	v_and_b32_e32 v8, 0xffffff00, v8
	v_or_b32_e32 v8, 0xdd, v8
	v_med3_u32 v11, v12, v14, v8
	v_med3_u32 v12, v15, v12, v8
	v_med3_u32 v14, v37, v15, v8
	v_med3_u32 v15, v16, v37, v8
	v_med3_u32 v16, v17, v16, v8
	v_med3_u32 v17, v28, v17, v8
	v_med3_u32 v28, v29, v28, v8
	v_med3_u32 v29, v30, v29, v8
	v_med3_u32 v30, v31, v30, v8
	v_med3_u32 v31, v32, v31, v8
	v_med3_u32 v32, v33, v32, v8
	v_med3_u32 v33, v36, v33, v8
	v_med3_u32 v36, v35, v36, v8
	v_med3_u32 v35, v34, v35, v8
	v_med3_u32 v34, v2, v34, v8
	v_max_u32_e32 v2, v2, v8
	v_not_b32_e32 v8, v10
	v_or_b32_e32 v37, 0x80000000, v10
	v_cmp_gt_i32_e32 vcc, 0, v10
	s_nop 1
	v_cndmask_b32_e32 v8, v37, v8, vcc
	v_and_b32_e32 v8, 0xffffff00, v8
	v_or_b32_e32 v8, 0xdc, v8
	v_med3_u32 v10, v12, v11, v8
	v_med3_u32 v11, v14, v12, v8
	v_med3_u32 v12, v15, v14, v8
	v_med3_u32 v14, v16, v15, v8
	v_med3_u32 v15, v17, v16, v8
	v_med3_u32 v16, v28, v17, v8
	v_med3_u32 v17, v29, v28, v8
	v_med3_u32 v28, v30, v29, v8
	v_med3_u32 v29, v31, v30, v8
	v_med3_u32 v30, v32, v31, v8
	v_med3_u32 v31, v33, v32, v8
	v_med3_u32 v32, v36, v33, v8
	v_med3_u32 v33, v35, v36, v8
	v_med3_u32 v35, v34, v35, v8
	v_med3_u32 v34, v2, v34, v8
	v_max_u32_e32 v2, v2, v8
	v_mov_b32_e32 v8, v9
	v_mov_b32_e32 v9, v1
	v_pk_add_f32 v[8:9], v[6:7], v[8:9]
	s_nop 0
	v_not_b32_e32 v6, v8
	v_or_b32_e32 v36, 0x80000000, v8
; __device__ __forceinline__ unsigned umed3(unsigned a, unsigned b, unsigned c) { unsigned r; asm("v_med3_u32 %0, %1, %2, %3" : "=v"(r) : "v"(a), "v"(b), "v"(c)); return r; }
; __device__ __forceinline__ unsigned orderable(float s) { unsigned u = __builtin_bit_cast(unsigned, s); return (u >> 31) ? ~u : (u | 0x80000000u); }
; __global__ void __launch_bounds__(NTHR, 2) fwd_megakernel(Args a) {
;     ...
;                 for (int i = 0; i < 16; ++i)
; #pragma unroll
;                     for (int jj = 0; jj < 16; ++jj)
;                         if ((i + 1) * (jj + 1) <= 16) {
;                             const unsigned uk = (orderable(av[i] + bv[jj]) & ~255u) | (unsigned)(255 - (i * 16 + jj));
; #pragma unroll
;                             for (int j = 15; j >= 1; --j) v[j] = umed3(v[j - 1], v[j], uk);
;                             v[0] = v[0] > uk ? v[0] : uk;
;                         }
	v_cmp_gt_i32_e32 vcc, 0, v8
	s_nop 1
	v_cndmask_b32_e32 v6, v36, v6, vcc
	v_and_b32_e32 v6, 0xffffff00, v6
	v_or_b32_e32 v6, 0xdb, v6
	v_med3_u32 v8, v11, v10, v6
	v_med3_u32 v10, v12, v11, v6
	v_med3_u32 v11, v14, v12, v6
	v_med3_u32 v12, v15, v14, v6
	v_med3_u32 v14, v16, v15, v6
	v_med3_u32 v15, v17, v16, v6
	v_med3_u32 v16, v28, v17, v6
	v_med3_u32 v17, v29, v28, v6
	v_med3_u32 v28, v30, v29, v6
	v_med3_u32 v29, v31, v30, v6
	v_med3_u32 v30, v32, v31, v6
	v_med3_u32 v31, v33, v32, v6
	v_med3_u32 v32, v35, v33, v6
	v_med3_u32 v33, v34, v35, v6
	v_med3_u32 v34, v2, v34, v6
	v_max_u32_e32 v2, v2, v6
	v_not_b32_e32 v6, v9
	v_or_b32_e32 v35, 0x80000000, v9
	v_cmp_gt_i32_e32 vcc, 0, v9
	v_mov_b32_e32 v9, v0
	s_nop 0
	v_cndmask_b32_e32 v6, v35, v6, vcc
	v_and_b32_e32 v6, 0xffffff00, v6
	v_or_b32_e32 v6, 0xcf, v6
	v_med3_u32 v35, v10, v8, v6
	v_med3_u32 v10, v11, v10, v6
	v_med3_u32 v11, v12, v11, v6
	v_med3_u32 v12, v14, v12, v6
	v_med3_u32 v14, v15, v14, v6
	v_med3_u32 v15, v16, v15, v6
	v_med3_u32 v16, v17, v16, v6
	v_med3_u32 v17, v28, v17, v6
	v_med3_u32 v28, v29, v28, v6
	v_med3_u32 v29, v30, v29, v6
	v_med3_u32 v30, v31, v30, v6
	v_med3_u32 v31, v32, v31, v6
	v_med3_u32 v32, v33, v32, v6
	v_med3_u32 v33, v34, v33, v6
	v_med3_u32 v34, v2, v34, v6
	v_max_u32_e32 v36, v2, v6
	v_mov_b32_e32 v6, v7
	v_mov_b32_e32 v8, v5
	v_mov_b32_e32 v2, v7
	v_pk_add_f32 v[6:7], v[6:7], v[8:9]
	s_nop 0
	v_not_b32_e32 v5, v7
	v_or_b32_e32 v37, 0x80000000, v7
	v_cmp_gt_i32_e32 vcc, 0, v7
	s_nop 1
	v_cndmask_b32_e32 v5, v37, v5, vcc
	v_and_b32_e32 v5, 0xffffff00, v5
	v_or_b32_e32 v5, 0xce, v5
	v_med3_u32 v7, v10, v35, v5
	v_med3_u32 v10, v11, v10, v5
	v_med3_u32 v11, v12, v11, v5
	v_med3_u32 v12, v14, v12, v5
	v_med3_u32 v14, v15, v14, v5
	v_med3_u32 v15, v16, v15, v5
	v_med3_u32 v16, v17, v16, v5
	v_med3_u32 v17, v28, v17, v5
	v_med3_u32 v28, v29, v28, v5
	v_med3_u32 v29, v30, v29, v5
	v_med3_u32 v30, v31, v30, v5
	v_med3_u32 v31, v32, v31, v5
	v_med3_u32 v32, v33, v32, v5
	v_med3_u32 v33, v34, v33, v5
	v_med3_u32 v34, v36, v34, v5
	v_max_u32_e32 v5, v36, v5
	v_not_b32_e32 v35, v6
	v_or_b32_e32 v36, 0x80000000, v6
	v_cmp_gt_i32_e32 vcc, 0, v6
	s_nop 1
	v_cndmask_b32_e32 v6, v36, v35, vcc
	v_and_b32_e32 v6, 0xffffff00, v6
	v_or_b32_e32 v6, 0xcd, v6
	v_med3_u32 v7, v10, v7, v6
	v_med3_u32 v10, v11, v10, v6
	v_med3_u32 v11, v12, v11, v6
	v_med3_u32 v12, v14, v12, v6
	v_med3_u32 v14, v15, v14, v6
	v_med3_u32 v15, v16, v15, v6
	v_med3_u32 v16, v17, v16, v6
	v_med3_u32 v17, v28, v17, v6
	v_med3_u32 v28, v29, v28, v6
	v_med3_u32 v29, v30, v29, v6
	v_med3_u32 v30, v31, v30, v6
	v_med3_u32 v31, v32, v31, v6
	v_med3_u32 v32, v33, v32, v6
	v_med3_u32 v33, v34, v33, v6
	v_med3_u32 v34, v5, v34, v6
	v_max_u32_e32 v6, v5, v6
	v_mov_b32_e32 v5, v1
	v_pk_add_f32 v[4:5], v[2:3], v[4:5]
	s_nop 0
	v_not_b32_e32 v2, v4
	v_or_b32_e32 v35, 0x80000000, v4
	v_cmp_gt_i32_e32 vcc, 0, v4
	s_nop 1
	v_cndmask_b32_e32 v2, v35, v2, vcc
	v_and_b32_e32 v2, 0xffffff00, v2
	v_or_b32_e32 v2, 0xcc, v2
	v_med3_u32 v4, v10, v7, v2
	v_med3_u32 v7, v11, v10, v2
	v_med3_u32 v10, v12, v11, v2
	v_med3_u32 v11, v14, v12, v2
	v_med3_u32 v12, v15, v14, v2
	v_med3_u32 v14, v16, v15, v2
	v_med3_u32 v15, v17, v16, v2
	v_med3_u32 v16, v28, v17, v2
	v_med3_u32 v17, v29, v28, v2
	v_med3_u32 v28, v30, v29, v2
	v_med3_u32 v29, v31, v30, v2
	v_med3_u32 v30, v32, v31, v2
	v_med3_u32 v31, v33, v32, v2
	v_med3_u32 v32, v34, v33, v2
	v_med3_u32 v33, v6, v34, v2
	v_max_u32_e32 v2, v6, v2
	v_not_b32_e32 v6, v5
	v_or_b32_e32 v34, 0x80000000, v5
	v_cmp_gt_i32_e32 vcc, 0, v5
	s_nop 1
	v_cndmask_b32_e32 v5, v34, v6, vcc
	v_and_b32_e32 v5, 0xffffff00, v5
	v_or_b32_e32 v5, 0xbf, v5
	v_med3_u32 v4, v7, v4, v5
	v_med3_u32 v6, v10, v7, v5
	v_med3_u32 v7, v11, v10, v5
	v_med3_u32 v10, v12, v11, v5
	v_med3_u32 v11, v14, v12, v5
	v_med3_u32 v12, v15, v14, v5
	v_med3_u32 v14, v16, v15, v5
	v_med3_u32 v15, v17, v16, v5
	v_med3_u32 v16, v28, v17, v5
	v_med3_u32 v17, v29, v28, v5
	v_med3_u32 v28, v30, v29, v5
	v_med3_u32 v29, v31, v30, v5
	v_med3_u32 v30, v32, v31, v5
	v_med3_u32 v31, v33, v32, v5
	v_med3_u32 v32, v2, v33, v5
	v_max_u32_e32 v5, v2, v5
	v_mov_b32_e32 v2, v3
	v_pk_add_f32 v[2:3], v[2:3], v[8:9] op_sel_hi:[0,1]
	v_not_b32_e32 v8, v3
	v_or_b32_e32 v9, 0x80000000, v3
	v_cmp_gt_i32_e32 vcc, 0, v3
	s_nop 1
	v_cndmask_b32_e32 v3, v9, v8, vcc
	v_and_b32_e32 v3, 0xffffff00, v3
	v_or_b32_e32 v3, 0xbe, v3
	v_med3_u32 v4, v6, v4, v3
	v_med3_u32 v6, v7, v6, v3
	v_med3_u32 v7, v10, v7, v3
	v_med3_u32 v8, v11, v10, v3
	v_med3_u32 v9, v12, v11, v3
	v_med3_u32 v10, v14, v12, v3
	v_med3_u32 v11, v15, v14, v3
	v_med3_u32 v12, v16, v15, v3
	v_med3_u32 v14, v17, v16, v3
	v_med3_u32 v15, v28, v17, v3
	v_med3_u32 v16, v29, v28, v3
	v_med3_u32 v17, v30, v29, v3
	v_med3_u32 v28, v31, v30, v3
	v_med3_u32 v29, v32, v31, v3
	v_med3_u32 v30, v5, v32, v3
	v_max_u32_e32 v3, v5, v3
	v_not_b32_e32 v5, v2
	v_or_b32_e32 v31, 0x80000000, v2
	v_cmp_gt_i32_e32 vcc, 0, v2
	s_nop 1
	v_cndmask_b32_e32 v2, v31, v5, vcc
	v_and_b32_e32 v2, 0xffffff00, v2
	v_or_b32_e32 v2, 0xbd, v2
	v_med3_u32 v4, v6, v4, v2
	v_med3_u32 v5, v7, v6, v2
	v_med3_u32 v6, v8, v7, v2
	v_med3_u32 v7, v9, v8, v2
	v_med3_u32 v8, v10, v9, v2
	v_med3_u32 v9, v11, v10, v2
	v_med3_u32 v10, v12, v11, v2
	v_med3_u32 v11, v14, v12, v2
	v_med3_u32 v12, v15, v14, v2
	v_med3_u32 v14, v16, v15, v2
	v_med3_u32 v15, v17, v16, v2
	v_med3_u32 v16, v28, v17, v2
	v_med3_u32 v17, v29, v28, v2
	v_med3_u32 v28, v30, v29, v2
	v_med3_u32 v29, v3, v30, v2
	v_max_u32_e32 v2, v3, v2
	v_add_f32_e32 v3, v27, v1
	v_not_b32_e32 v30, v3
	v_or_b32_e32 v31, 0x80000000, v3
	v_cmp_gt_i32_e32 vcc, 0, v3
	s_nop 1
; __device__ __forceinline__ unsigned umed3(unsigned a, unsigned b, unsigned c) { unsigned r; asm("v_med3_u32 %0, %1, %2, %3" : "=v"(r) : "v"(a), "v"(b), "v"(c)); return r; }
; __device__ __forceinline__ unsigned orderable(float s) { unsigned u = __builtin_bit_cast(unsigned, s); return (u >> 31) ? ~u : (u | 0x80000000u); }
; __global__ void __launch_bounds__(NTHR, 2) fwd_megakernel(Args a) {
;     ...
;                 for (int i = 0; i < 16; ++i)
; #pragma unroll
;                     for (int jj = 0; jj < 16; ++jj)
;                         if ((i + 1) * (jj + 1) <= 16) {
;                             const unsigned uk = (orderable(av[i] + bv[jj]) & ~255u) | (unsigned)(255 - (i * 16 + jj));
; #pragma unroll
;                             for (int j = 15; j >= 1; --j) v[j] = umed3(v[j - 1], v[j], uk);
;                             v[0] = v[0] > uk ? v[0] : uk;
;                         }
	v_cndmask_b32_e32 v3, v31, v30, vcc
	v_and_b32_e32 v3, 0xffffff00, v3
	v_or_b32_e32 v3, 0xaf, v3
	v_med3_u32 v4, v5, v4, v3
	v_med3_u32 v5, v6, v5, v3
	v_med3_u32 v6, v7, v6, v3
	v_med3_u32 v7, v8, v7, v3
	v_med3_u32 v8, v9, v8, v3
	v_med3_u32 v9, v10, v9, v3
	v_med3_u32 v10, v11, v10, v3
	v_med3_u32 v11, v12, v11, v3
	v_med3_u32 v12, v14, v12, v3
	v_med3_u32 v14, v15, v14, v3
	v_med3_u32 v15, v16, v15, v3
	v_med3_u32 v16, v17, v16, v3
	v_med3_u32 v17, v28, v17, v3
	v_med3_u32 v28, v29, v28, v3
	v_med3_u32 v29, v2, v29, v3
	v_max_u32_e32 v2, v2, v3
	v_add_f32_e32 v3, v27, v0
	v_not_b32_e32 v27, v3
	v_or_b32_e32 v30, 0x80000000, v3
	v_cmp_gt_i32_e32 vcc, 0, v3
	s_nop 1
	v_cndmask_b32_e32 v3, v30, v27, vcc
	v_and_b32_e32 v3, 0xffffff00, v3
	v_or_b32_e32 v3, 0xae, v3
	v_med3_u32 v4, v5, v4, v3
	v_med3_u32 v5, v6, v5, v3
	v_med3_u32 v6, v7, v6, v3
	v_med3_u32 v7, v8, v7, v3
	v_med3_u32 v8, v9, v8, v3
	v_med3_u32 v9, v10, v9, v3
	v_med3_u32 v10, v11, v10, v3
	v_med3_u32 v11, v12, v11, v3
	v_med3_u32 v12, v14, v12, v3
	v_med3_u32 v14, v15, v14, v3
	v_med3_u32 v15, v16, v15, v3
	v_med3_u32 v16, v17, v16, v3
	v_med3_u32 v17, v28, v17, v3
	v_med3_u32 v27, v29, v28, v3
	v_med3_u32 v28, v2, v29, v3
	v_max_u32_e32 v2, v2, v3
	v_add_f32_e32 v3, v26, v1
	v_not_b32_e32 v29, v3
	v_or_b32_e32 v30, 0x80000000, v3
	v_cmp_gt_i32_e32 vcc, 0, v3
	s_nop 1
	v_cndmask_b32_e32 v3, v30, v29, vcc
	v_and_b32_e32 v3, 0xffffff00, v3
	v_or_b32_e32 v3, 0x9f, v3
	v_med3_u32 v4, v5, v4, v3
	v_med3_u32 v5, v6, v5, v3
	v_med3_u32 v6, v7, v6, v3
	v_med3_u32 v7, v8, v7, v3
	v_med3_u32 v8, v9, v8, v3
	v_med3_u32 v9, v10, v9, v3
	v_med3_u32 v10, v11, v10, v3
	v_med3_u32 v11, v12, v11, v3
	v_med3_u32 v12, v14, v12, v3
	v_med3_u32 v14, v15, v14, v3
	v_med3_u32 v15, v16, v15, v3
	v_med3_u32 v16, v17, v16, v3
	v_med3_u32 v17, v27, v17, v3
	v_med3_u32 v27, v28, v27, v3
	v_med3_u32 v28, v2, v28, v3
	v_max_u32_e32 v2, v2, v3
	v_add_f32_e32 v3, v26, v0
	v_not_b32_e32 v26, v3
	v_or_b32_e32 v29, 0x80000000, v3
	v_cmp_gt_i32_e32 vcc, 0, v3
	v_add_f32_e32 v0, v25, v0
	s_nop 0
	v_cndmask_b32_e32 v3, v29, v26, vcc
	v_and_b32_e32 v3, 0xffffff00, v3
	v_or_b32_e32 v3, 0x9e, v3
	v_med3_u32 v4, v5, v4, v3
	v_med3_u32 v5, v6, v5, v3
	v_med3_u32 v6, v7, v6, v3
	v_med3_u32 v7, v8, v7, v3
	v_med3_u32 v8, v9, v8, v3
	v_med3_u32 v9, v10, v9, v3
	v_med3_u32 v10, v11, v10, v3
	v_med3_u32 v11, v12, v11, v3
	v_med3_u32 v12, v14, v12, v3
	v_med3_u32 v14, v15, v14, v3
	v_med3_u32 v15, v16, v15, v3
	v_med3_u32 v16, v17, v16, v3
	v_med3_u32 v17, v27, v17, v3
	v_med3_u32 v26, v28, v27, v3
	v_med3_u32 v27, v2, v28, v3
	v_max_u32_e32 v2, v2, v3
	v_add_f32_e32 v3, v25, v1
	v_not_b32_e32 v28, v3
	v_or_b32_e32 v29, 0x80000000, v3
	v_cmp_gt_i32_e32 vcc, 0, v3
	v_or_b32_e32 v25, 0x80000000, v0
	s_nop 0
	v_cndmask_b32_e32 v3, v29, v28, vcc
	v_and_b32_e32 v3, 0xffffff00, v3
	v_or_b32_e32 v3, 0x8f, v3
	v_med3_u32 v4, v5, v4, v3
	v_med3_u32 v5, v6, v5, v3
	v_med3_u32 v6, v7, v6, v3
	v_med3_u32 v7, v8, v7, v3
	v_med3_u32 v8, v9, v8, v3
	v_med3_u32 v9, v10, v9, v3
	v_med3_u32 v10, v11, v10, v3
	v_med3_u32 v11, v12, v11, v3
	v_med3_u32 v12, v14, v12, v3
	v_med3_u32 v14, v15, v14, v3
	v_med3_u32 v15, v16, v15, v3
	v_med3_u32 v16, v17, v16, v3
	v_med3_u32 v17, v26, v17, v3
	v_med3_u32 v26, v27, v26, v3
	v_med3_u32 v27, v2, v27, v3
	v_max_u32_e32 v2, v2, v3
	v_not_b32_e32 v3, v0
	v_cmp_gt_i32_e32 vcc, 0, v0
	s_nop 1
	v_cndmask_b32_e32 v0, v25, v3, vcc
	v_and_b32_e32 v0, 0xffffff00, v0
	v_or_b32_e32 v0, 0x8e, v0
	v_med3_u32 v3, v5, v4, v0
	v_med3_u32 v4, v6, v5, v0
	v_med3_u32 v5, v7, v6, v0
	v_med3_u32 v6, v8, v7, v0
	v_med3_u32 v7, v9, v8, v0
	v_med3_u32 v8, v10, v9, v0
	v_med3_u32 v9, v11, v10, v0
	v_med3_u32 v10, v12, v11, v0
	v_med3_u32 v11, v14, v12, v0
	v_med3_u32 v12, v15, v14, v0
	v_med3_u32 v14, v16, v15, v0
	v_med3_u32 v15, v17, v16, v0
	v_med3_u32 v16, v26, v17, v0
	v_med3_u32 v17, v27, v26, v0
	v_med3_u32 v25, v2, v27, v0
	v_max_u32_e32 v0, v2, v0
	v_add_f32_e32 v2, v24, v1
	v_not_b32_e32 v24, v2
	v_or_b32_e32 v26, 0x80000000, v2
	v_cmp_gt_i32_e32 vcc, 0, v2
	s_nop 1
	v_cndmask_b32_e32 v2, v26, v24, vcc
	v_and_b32_e32 v2, 0xffffff00, v2
	v_or_b32_e32 v2, 0x7f, v2
	v_med3_u32 v3, v4, v3, v2
	v_med3_u32 v4, v5, v4, v2
	v_med3_u32 v5, v6, v5, v2
	v_med3_u32 v6, v7, v6, v2
	v_med3_u32 v7, v8, v7, v2
	v_med3_u32 v8, v9, v8, v2
	v_med3_u32 v9, v10, v9, v2
	v_med3_u32 v10, v11, v10, v2
	v_med3_u32 v11, v12, v11, v2
	v_med3_u32 v12, v14, v12, v2
	v_med3_u32 v14, v15, v14, v2
	v_med3_u32 v15, v16, v15, v2
	v_med3_u32 v16, v17, v16, v2
	v_med3_u32 v17, v25, v17, v2
	v_med3_u32 v24, v0, v25, v2
	v_max_u32_e32 v0, v0, v2
	v_add_f32_e32 v2, v23, v1
	v_not_b32_e32 v23, v2
	v_or_b32_e32 v25, 0x80000000, v2
	v_cmp_gt_i32_e32 vcc, 0, v2
	s_nop 1
	v_cndmask_b32_e32 v2, v25, v23, vcc
	v_and_b32_e32 v2, 0xffffff00, v2
	v_or_b32_e32 v2, 0x6f, v2
	v_med3_u32 v3, v4, v3, v2
	v_med3_u32 v4, v5, v4, v2
	v_med3_u32 v5, v6, v5, v2
	v_med3_u32 v6, v7, v6, v2
	v_med3_u32 v7, v8, v7, v2
	v_med3_u32 v8, v9, v8, v2
	v_med3_u32 v9, v10, v9, v2
	v_med3_u32 v10, v11, v10, v2
	v_med3_u32 v11, v12, v11, v2
	v_med3_u32 v12, v14, v12, v2
	v_med3_u32 v14, v15, v14, v2
	v_med3_u32 v15, v16, v15, v2
	v_med3_u32 v16, v17, v16, v2
	v_med3_u32 v17, v24, v17, v2
	v_med3_u32 v23, v0, v24, v2
	v_max_u32_e32 v0, v0, v2
	v_add_f32_e32 v2, v22, v1
	v_not_b32_e32 v22, v2
	v_or_b32_e32 v24, 0x80000000, v2
	v_cmp_gt_i32_e32 vcc, 0, v2
	s_nop 1
	v_cndmask_b32_e32 v2, v24, v22, vcc
	v_and_b32_e32 v2, 0xffffff00, v2
	v_or_b32_e32 v2, 0x5f, v2
	v_med3_u32 v3, v4, v3, v2
	v_med3_u32 v4, v5, v4, v2
	v_med3_u32 v5, v6, v5, v2
	v_med3_u32 v6, v7, v6, v2
	v_med3_u32 v7, v8, v7, v2
; __device__ __forceinline__ unsigned umed3(unsigned a, unsigned b, unsigned c) { unsigned r; asm("v_med3_u32 %0, %1, %2, %3" : "=v"(r) : "v"(a), "v"(b), "v"(c)); return r; }
; __device__ __forceinline__ unsigned orderable(float s) { unsigned u = __builtin_bit_cast(unsigned, s); return (u >> 31) ? ~u : (u | 0x80000000u); }
; __global__ void __launch_bounds__(NTHR, 2) fwd_megakernel(Args a) {
;     ...
;                 for (int i = 0; i < 16; ++i)
; #pragma unroll
;                     for (int jj = 0; jj < 16; ++jj)
;                         if ((i + 1) * (jj + 1) <= 16) {
;                             const unsigned uk = (orderable(av[i] + bv[jj]) & ~255u) | (unsigned)(255 - (i * 16 + jj));
; #pragma unroll
;                             for (int j = 15; j >= 1; --j) v[j] = umed3(v[j - 1], v[j], uk);
;                             v[0] = v[0] > uk ? v[0] : uk;
;                         }
;                 float best[16]; int ex[16];
; #pragma unroll
;                 for (int r = 0; r < 16; ++r) {
;                     const unsigned code = 255u - (v[r] & 255u); const unsigned i = code >> 4, jj = code & 15u;
;                     const unsigned ka = TOPI[ra * 16 + i], kb2 = TOPI[rb * 16 + jj];
;                     best[r] = SC[ra * 129 + ka] + SC[rb * 129 + kb2];
;                     ex[r] = (int)(ka * 128u + kb2);
	v_med3_u32 v8, v9, v8, v2
	v_med3_u32 v9, v10, v9, v2
	v_med3_u32 v10, v11, v10, v2
	v_med3_u32 v11, v12, v11, v2
	v_med3_u32 v12, v14, v12, v2
	v_med3_u32 v14, v15, v14, v2
	v_med3_u32 v15, v16, v15, v2
	v_med3_u32 v16, v17, v16, v2
	v_med3_u32 v17, v23, v17, v2
	v_med3_u32 v22, v0, v23, v2
	v_max_u32_e32 v0, v0, v2
	v_add_f32_e32 v2, v21, v1
	v_not_b32_e32 v21, v2
	v_or_b32_e32 v23, 0x80000000, v2
	v_cmp_gt_i32_e32 vcc, 0, v2
	s_nop 1
	v_cndmask_b32_e32 v2, v23, v21, vcc
	v_and_b32_e32 v2, 0xffffff00, v2
	v_or_b32_e32 v2, 0x4f, v2
	v_med3_u32 v3, v4, v3, v2
	v_med3_u32 v4, v5, v4, v2
	v_med3_u32 v5, v6, v5, v2
	v_med3_u32 v6, v7, v6, v2
	v_med3_u32 v7, v8, v7, v2
	v_med3_u32 v8, v9, v8, v2
	v_med3_u32 v9, v10, v9, v2
	v_med3_u32 v10, v11, v10, v2
	v_med3_u32 v11, v12, v11, v2
	v_med3_u32 v12, v14, v12, v2
	v_med3_u32 v14, v15, v14, v2
	v_med3_u32 v15, v16, v15, v2
	v_med3_u32 v16, v17, v16, v2
	v_med3_u32 v17, v22, v17, v2
	v_med3_u32 v21, v0, v22, v2
	v_max_u32_e32 v0, v0, v2
	v_add_f32_e32 v2, v20, v1
	v_not_b32_e32 v20, v2
	v_or_b32_e32 v22, 0x80000000, v2
	v_cmp_gt_i32_e32 vcc, 0, v2
	s_nop 1
	v_cndmask_b32_e32 v2, v22, v20, vcc
	v_and_or_b32 v2, v2, s58, 63
	v_med3_u32 v3, v4, v3, v2
	v_med3_u32 v4, v5, v4, v2
	v_med3_u32 v5, v6, v5, v2
	v_med3_u32 v6, v7, v6, v2
	v_med3_u32 v7, v8, v7, v2
	v_med3_u32 v8, v9, v8, v2
	v_med3_u32 v9, v10, v9, v2
	v_med3_u32 v10, v11, v10, v2
	v_med3_u32 v11, v12, v11, v2
	v_med3_u32 v12, v14, v12, v2
	v_med3_u32 v14, v15, v14, v2
	v_med3_u32 v15, v16, v15, v2
	v_med3_u32 v16, v17, v16, v2
	v_med3_u32 v17, v21, v17, v2
	v_med3_u32 v20, v0, v21, v2
	v_max_u32_e32 v0, v0, v2
	v_add_f32_e32 v2, v19, v1
	v_not_b32_e32 v19, v2
	v_or_b32_e32 v21, 0x80000000, v2
	v_cmp_gt_i32_e32 vcc, 0, v2
	s_nop 1
	v_cndmask_b32_e32 v2, v21, v19, vcc
	v_and_or_b32 v2, v2, s58, 47
	v_med3_u32 v3, v4, v3, v2
	v_med3_u32 v4, v5, v4, v2
	v_med3_u32 v5, v6, v5, v2
	v_med3_u32 v6, v7, v6, v2
	v_med3_u32 v7, v8, v7, v2
	v_med3_u32 v8, v9, v8, v2
	v_med3_u32 v9, v10, v9, v2
	v_med3_u32 v10, v11, v10, v2
	v_med3_u32 v11, v12, v11, v2
	v_med3_u32 v12, v14, v12, v2
	v_med3_u32 v14, v15, v14, v2
	v_med3_u32 v15, v16, v15, v2
	v_med3_u32 v16, v17, v16, v2
	v_med3_u32 v17, v20, v17, v2
	v_med3_u32 v19, v0, v20, v2
	v_max_u32_e32 v0, v0, v2
	v_add_f32_e32 v2, v18, v1
	v_not_b32_e32 v18, v2
	v_or_b32_e32 v20, 0x80000000, v2
	v_cmp_gt_i32_e32 vcc, 0, v2
	v_add_f32_e32 v1, v13, v1
	v_or_b32_e32 v13, 0x80000000, v1
	v_cndmask_b32_e32 v2, v20, v18, vcc
	v_and_or_b32 v2, v2, s58, 31
	v_med3_u32 v3, v4, v3, v2
	v_med3_u32 v4, v5, v4, v2
	v_med3_u32 v5, v6, v5, v2
	v_med3_u32 v6, v7, v6, v2
	v_med3_u32 v7, v8, v7, v2
	v_med3_u32 v8, v9, v8, v2
	v_med3_u32 v9, v10, v9, v2
	v_med3_u32 v10, v11, v10, v2
	v_med3_u32 v11, v12, v11, v2
	v_med3_u32 v12, v14, v12, v2
	v_med3_u32 v14, v15, v14, v2
	v_med3_u32 v15, v16, v15, v2
	v_med3_u32 v16, v17, v16, v2
	v_med3_u32 v17, v19, v17, v2
	v_med3_u32 v18, v0, v19, v2
	v_max_u32_e32 v0, v0, v2
	v_not_b32_e32 v2, v1
	v_cmp_gt_i32_e32 vcc, 0, v1
	s_nop 1
	v_cndmask_b32_e32 v1, v13, v2, vcc
	v_and_or_b32 v1, v1, s58, 15
	v_med3_u32 v48, v12, v11, v1
	v_med3_u32 v35, v14, v12, v1
	v_med3_u32 v12, v15, v14, v1
	v_med3_u32 v13, v16, v15, v1
	v_med3_u32 v14, v17, v16, v1
	v_med3_u32 v16, v0, v18, v1
	v_max_u32_e32 v0, v0, v1
	v_med3_u32 v31, v4, v3, v1
	v_med3_u32 v32, v5, v4, v1
	v_med3_u32 v42, v6, v5, v1
	v_med3_u32 v60, v7, v6, v1
	v_med3_u32 v44, v8, v7, v1
	v_med3_u32 v45, v9, v8, v1
	v_med3_u32 v46, v10, v9, v1
	v_med3_u32 v47, v11, v10, v1
	v_not_b32_e32 v4, v35
	v_not_b32_e32 v5, v12
	v_not_b32_e32 v6, v13
	v_not_b32_e32 v7, v14
	v_med3_u32 v15, v18, v17, v1
	v_not_b32_e32 v9, v16
	v_not_b32_e32 v8, v15
	v_not_b32_e32 v1, v0
	v_bfe_u32 v1, v1, 4, 4
	v_bitop3_b32 v0, v0, 15, v0 bitop3:0xc
	v_bfe_u32 v9, v9, 4, 4
	v_bfe_u32 v8, v8, 4, 4
	v_bfe_u32 v7, v7, 4, 4
	v_bfe_u32 v6, v6, 4, 4
	v_bfe_u32 v5, v5, 4, 4
	v_bfe_u32 v4, v4, 4, 4
	v_add_u32_e32 v1, v80, v1
	v_add_u32_e32 v0, v81, v0
	v_add_u32_e32 v10, v80, v9
	v_add_u32_e32 v8, v80, v8
	v_add_u32_e32 v7, v80, v7
	v_add_u32_e32 v6, v80, v6
	v_add_u32_e32 v5, v80, v5
	v_add_u32_e32 v4, v80, v4
	v_bitop3_b32 v16, v16, 15, v16 bitop3:0xc
	v_bitop3_b32 v14, v14, 15, v14 bitop3:0xc
	v_bitop3_b32 v13, v13, 15, v13 bitop3:0xc
	v_bitop3_b32 v12, v12, 15, v12 bitop3:0xc
	ds_read_u8 v9, v1
	ds_read_u8 v11, v0
	ds_read_u8 v10, v10
	ds_read_u8 v8, v8
	ds_read_u8 v7, v7
	ds_read_u8 v6, v6
	ds_read_u8 v5, v5
	ds_read_u8 v4, v4
	s_waitcnt lgkmcnt(7)
	v_lshl_add_u32 v0, v9, 2, v82
	v_add_u32_e32 v16, v81, v16
	s_waitcnt lgkmcnt(5)
	v_lshl_add_u32 v19, v10, 2, v82
	v_bitop3_b32 v15, v15, 15, v15 bitop3:0xc
	v_add_u32_e32 v14, v81, v14
	v_add_u32_e32 v13, v81, v13
	v_add_u32_e32 v12, v81, v12
	v_lshl_add_u32 v1, v11, 2, v83
	v_add_u32_e32 v20, v81, v15
	ds_read_b32 v17, v0
	ds_read_b32 v18, v1
	ds_read_u8 v15, v16
	ds_read_b32 v19, v19
	ds_read_u8 v16, v20
	ds_read_u8 v14, v14
	ds_read_u8 v13, v13
	ds_read_u8 v12, v12
	s_waitcnt lgkmcnt(5)
	v_lshl_add_u32 v0, v15, 2, v83
	s_waitcnt lgkmcnt(3)
	v_lshl_add_u32 v21, v16, 2, v83
	v_lshl_add_u32 v22, v7, 2, v82
	s_waitcnt lgkmcnt(2)
	v_lshl_add_u32 v23, v14, 2, v83
	v_lshl_add_u32 v27, v6, 2, v82
	v_not_b32_e32 v34, v48
	v_lshl_add_u32 v1, v8, 2, v82
	s_waitcnt lgkmcnt(1)
; __device__ __forceinline__ void xcd_barrier(const XcdBarrier& b) {
;     asm volatile("s_waitcnt vmcnt(0)" ::: "memory");
;     __syncthreads();
;     if (threadIdx.x == 0) {
;         unsigned* bar = b.bar;
;         __builtin_amdgcn_s_waitcnt(0);
;         unsigned nloc = b.st[0], nx = b.st[1];
;         if (nloc == 0u) { xcd_barrier_complete(bar, b.x, nloc, nx); b.st[0] = nloc; b.st[1] = nx; }
; __global__ void __launch_bounds__(NTHR, 2) fwd_megakernel(Args a) {
;     ...
;                 for (int r = 0; r < 16; ++r) {
;                     const unsigned code = 255u - (v[r] & 255u); const unsigned i = code >> 4, jj = code & 15u;
;                     const unsigned ka = TOPI[ra * 16 + i], kb2 = TOPI[rb * 16 + jj];
;                     best[r] = SC[ra * 129 + ka] + SC[rb * 129 + kb2];
;                     ex[r] = (int)(ka * 128u + kb2);
;                 }
;                 float rf;
;                 { const f32x4* sp4 = (const f32x4*)(SSP + (size_t)(t0 + tid) * 32); f32x4 a4 = sp4[0];
; #pragma unroll
;                     for (int q = 1; q < 8; ++q) a4 += sp4[q];
;                     rf = rsqrtf(((a4.x + a4.y) + (a4.z + a4.w)) * (1.f / D) + EPS); if (h == 0) RSTDF[t0 + tid] = rf; }
	v_lshl_add_u32 v36, v13, 2, v83
	v_lshl_add_u32 v37, v5, 2, v82
	ds_read_b32 v24, v0
	ds_read_b32 v20, v1
	ds_read_b32 v25, v21
	ds_read_b32 v21, v22
	ds_read_b32 v26, v23
	ds_read_b32 v22, v27
	ds_read_b32 v27, v36
	ds_read_b32 v23, v37
	v_bitop3_b32 v0, v35, 15, v35 bitop3:0xc
	v_not_b32_e32 v29, v47
	v_add_u32_e32 v35, v81, v0
	v_bfe_u32 v0, v34, 4, 4
	v_not_b32_e32 v28, v46
	v_add_u32_e32 v34, v80, v0
	v_bfe_u32 v0, v29, 4, 4
	v_not_b32_e32 v3, v45
	v_add_u32_e32 v49, v80, v0
	v_bfe_u32 v0, v28, 4, 4
	v_not_b32_e32 v2, v44
	v_add_u32_e32 v50, v80, v0
	v_bfe_u32 v0, v3, 4, 4
	v_add_u32_e32 v51, v80, v0
	v_bfe_u32 v0, v2, 4, 4
	v_add_u32_e32 v2, s75, v76
	v_ashrrev_i32_e32 v3, 31, v2
	v_add_u32_e32 v52, v80, v0
	v_lshlrev_b64 v[0:1], 7, v[2:3]
	v_lshl_add_u64 v[28:29], s[62:63], 0, v[0:1]
	global_load_dwordx4 v[98:101], v[28:29], off offset:48
	global_load_dwordx4 v[102:105], v[28:29], off offset:32
	global_load_dwordx4 v[106:109], v[28:29], off
	global_load_dwordx4 v[110:113], v[28:29], off offset:16
	s_waitcnt lgkmcnt(8)
	v_lshl_add_u32 v36, v12, 2, v83
	v_lshl_add_u32 v37, v4, 2, v82
	ds_read_b32 v40, v36
	ds_read_u8 v38, v35
	ds_read_b32 v41, v37
	ds_read_u8 v39, v34
	ds_read_u8 v37, v49
	ds_read_u8 v36, v50
	ds_read_u8 v35, v51
	ds_read_u8 v34, v52
	global_load_dwordx4 v[114:117], v[28:29], off offset:80
	global_load_dwordx4 v[118:121], v[28:29], off offset:64
	global_load_dwordx4 v[122:125], v[28:29], off offset:112
	global_load_dwordx4 v[126:129], v[28:29], off offset:96
	v_not_b32_e32 v43, v60
	v_bitop3_b32 v48, v48, 15, v48 bitop3:0xc
	v_bitop3_b32 v46, v46, 15, v46 bitop3:0xc
	v_bitop3_b32 v45, v45, 15, v45 bitop3:0xc
	v_bitop3_b32 v44, v44, 15, v44 bitop3:0xc
	v_bfe_u32 v43, v43, 4, 4
	s_waitcnt lgkmcnt(6)
	v_lshl_add_u32 v49, v38, 2, v83
	v_add_u32_e32 v48, v81, v48
	v_bitop3_b32 v29, v47, 15, v47 bitop3:0xc
	v_add_u32_e32 v46, v81, v46
	v_add_u32_e32 v45, v81, v45
	v_add_u32_e32 v44, v81, v44
	v_add_u32_e32 v43, v80, v43
	s_waitcnt lgkmcnt(4)
	v_lshl_add_u32 v28, v39, 2, v82
	v_add_u32_e32 v29, v81, v29
	ds_read_b32 v49, v49
	ds_read_u8 v47, v48
	ds_read_b32 v50, v28
	ds_read_u8 v48, v29
	ds_read_u8 v46, v46
	ds_read_u8 v45, v45
	ds_read_u8 v44, v44
	ds_read_u8 v43, v43
	v_not_b32_e32 v30, v31
	s_waitcnt lgkmcnt(6)
	v_lshl_add_u32 v28, v47, 2, v83
	v_lshl_add_u32 v29, v37, 2, v82
	s_waitcnt lgkmcnt(4)
	v_lshl_add_u32 v52, v48, 2, v83
	v_lshl_add_u32 v53, v36, 2, v82
	s_waitcnt lgkmcnt(3)
	v_lshl_add_u32 v54, v46, 2, v83
	v_lshl_add_u32 v58, v35, 2, v82
	v_not_b32_e32 v33, v32
	v_not_b32_e32 v59, v42
	s_waitcnt lgkmcnt(2)
	v_lshl_add_u32 v61, v45, 2, v83
	v_lshl_add_u32 v62, v34, 2, v82
	ds_read_b32 v55, v28
	ds_read_b32 v51, v29
	ds_read_b32 v56, v52
	ds_read_b32 v52, v53
	ds_read_b32 v57, v54
	ds_read_b32 v53, v58
	ds_read_b32 v58, v61
	ds_read_b32 v54, v62
	v_bitop3_b32 v29, v60, 15, v60 bitop3:0xc
	v_bfe_u32 v30, v30, 4, 4
	s_waitcnt lgkmcnt(9)
	v_lshl_add_u32 v28, v44, 2, v83
	v_add_u32_e32 v29, v81, v29
	s_waitcnt lgkmcnt(8)
	v_lshl_add_u32 v61, v43, 2, v82
	v_bfe_u32 v59, v59, 4, 4
	v_bfe_u32 v33, v33, 4, 4
	v_add_u32_e32 v30, v80, v30
	v_add_u32_e32 v62, v80, v59
	v_add_u32_e32 v33, v80, v33
	ds_read_b32 v60, v28
	ds_read_u8 v59, v29
	ds_read_b32 v61, v61
	ds_read_u8 v28, v62
	ds_read_u8 v29, v33
	ds_read_u8 v30, v30
	v_bitop3_b32 v42, v42, 15, v42 bitop3:0xc
	v_bitop3_b32 v32, v32, 15, v32 bitop3:0xc
	s_waitcnt lgkmcnt(4)
	v_lshl_add_u32 v33, v59, 2, v83
	v_add_u32_e32 v42, v81, v42
	s_waitcnt lgkmcnt(2)
	v_lshl_add_u32 v63, v28, 2, v82
	v_add_u32_e32 v32, v81, v32
	v_bitop3_b32 v31, v31, 15, v31 bitop3:0xc
	v_add_u32_e32 v97, v81, v31
	ds_read_u8 v31, v42
	ds_read_b32 v62, v33
	ds_read_u8 v32, v32
	ds_read_b32 v63, v63
	ds_read_u8 v33, v97
	s_waitcnt lgkmcnt(4)
	v_lshl_add_u32 v42, v31, 2, v83
	v_lshl_add_u32 v97, v29, 2, v82
	s_waitcnt lgkmcnt(2)
	v_lshl_add_u32 v130, v32, 2, v83
	v_lshl_add_u32 v131, v30, 2, v82
	s_waitcnt lgkmcnt(0)
	v_lshl_add_u32 v132, v33, 2, v83
	s_waitcnt vmcnt(4)
	v_pk_add_f32 v[108:109], v[108:109], v[112:113]
	v_pk_add_f32 v[106:107], v[106:107], v[110:111]
	v_pk_add_f32 v[104:105], v[108:109], v[104:105]
	v_pk_add_f32 v[102:103], v[106:107], v[102:103]
	v_pk_add_f32 v[100:101], v[104:105], v[100:101]
	v_pk_add_f32 v[98:99], v[102:103], v[98:99]
	s_waitcnt vmcnt(2)
	v_pk_add_f32 v[100:101], v[100:101], v[120:121]
	v_pk_add_f32 v[98:99], v[98:99], v[118:119]
	v_pk_add_f32 v[100:101], v[100:101], v[116:117]
	v_pk_add_f32 v[98:99], v[98:99], v[114:115]
	s_waitcnt vmcnt(0)
	v_pk_add_f32 v[100:101], v[100:101], v[128:129]
	v_pk_add_f32 v[98:99], v[98:99], v[126:127]
	v_pk_add_f32 v[100:101], v[100:101], v[124:125]
	v_pk_add_f32 v[98:99], v[98:99], v[122:123]
	s_nop 0
	v_pk_mov_b32 v[102:103], v[98:99], v[100:101] op_sel:[1,0]
	v_mov_b32_e32 v99, v101
	v_pk_add_f32 v[98:99], v[102:103], v[98:99]
	s_nop 0
	v_add_f32_e32 v98, v98, v99
	v_fmamk_f32 v98, v98, 0x3a000000, v88
	v_mul_f32_e32 v99, 0x4b800000, v98
	v_cmp_gt_f32_e32 vcc, s72, v98
	s_nop 1
	v_cndmask_b32_e32 v98, v98, v99, vcc
	v_rsq_f32_e32 v102, v98
	ds_read_b32 v99, v42
	ds_read_b32 v97, v97
	ds_read_b32 v100, v130
	ds_read_b32 v98, v131
	ds_read_b32 v101, v132
	v_mul_f32_e32 v42, 0x45800000, v102
	v_cndmask_b32_e32 v42, v102, v42, vcc
	s_cbranch_scc1 .LBB0_794
	v_lshl_add_u64 v[2:3], v[2:3], 2, s[52:53]
	global_store_dword v[2:3], v42, off
	s_branch .LBB0_794
.LBB0_824:
	s_waitcnt vmcnt(0)
	s_barrier
	s_mov_b64 s[0:1], exec
	v_readlane_b32 s6, v235, 3
	v_readlane_b32 s7, v235, 4
	s_and_b64 s[6:7], s[0:1], s[6:7]
	s_mov_b64 exec, s[6:7]
	s_cbranch_execz .LBB0_876
	s_add_i32 s6, 0, 0x25ff0
	v_mov_b32_e32 v0, s6
	s_waitcnt vmcnt(0) expcnt(0) lgkmcnt(0)
	ds_read_b32 v2, v0
	s_add_i32 s6, 0, 0x25ff4
	v_mov_b32_e32 v0, s6
	ds_read_b32 v0, v0
	s_waitcnt lgkmcnt(1)
	v_cmp_ne_u32_e32 vcc, 0, v2
	s_cbranch_vccnz .LBB0_840
	v_readlane_b32 s6, v235, 1
	v_readlane_b32 s7, v235, 2
	v_readlane_b32 s8, v235, 0
	s_mul_i32 s33, s7, s8
	s_mul_i32 s33, s33, s6
	s_add_u32 s6, s50, 0x8208200
	s_addc_u32 s7, s51, 0
	s_add_u32 s8, s50, 0x8208400
	s_addc_u32 s9, s51, 0
	s_add_u32 s10, s50, 0x8208500
	s_addc_u32 s11, s51, 0
	s_add_u32 s12, s50, 0x8208600
	s_addc_u32 s13, s51, 0
	s_add_u32 s14, s50, 0x8208700
	s_addc_u32 s15, s51, 0
	s_add_u32 s16, s50, 0x8208800
	s_addc_u32 s17, s51, 0
	s_add_u32 s18, s50, 0x8208900
	s_addc_u32 s19, s51, 0
	s_add_u32 s20, s50, 0x8208a00
	s_addc_u32 s21, s51, 0
	s_add_u32 s22, s50, 0x8208b00
	s_addc_u32 s23, s51, 0
	s_add_u32 s24, s50, 0x8208c00
	s_addc_u32 s25, s51, 0
	s_add_u32 s34, s50, 0x8208d00
	s_addc_u32 s35, s51, 0
	s_add_u32 s36, s50, 0x8208e00
	s_addc_u32 s37, s51, 0
	s_add_u32 s38, s50, 0x8208f00
	s_addc_u32 s39, s51, 0
	s_add_u32 s44, s50, 0x8209000
	s_addc_u32 s45, s51, 0
	s_add_u32 s58, s50, 0x8209100
	s_addc_u32 s59, s51, 0
	s_add_u32 s60, s50, 0x8209200
	s_addc_u32 s61, s51, 0
	s_add_u32 s62, s50, 0x8209300
	s_addc_u32 s63, s51, 0
	s_mov_b32 s70, 1
	v_mov_b32_e32 v16, 0
	s_branch .LBB0_828
